# v2: GEMM loops issue LDS fragment reads before global prefetch loads; MLA QK ring-buffered; QK prologue reads hoisted above prefetch in both attention loops
# speedup vs baseline: 1.0073x; 1.0073x over previous
; #define G_LOAD(T) { const int k_ = (T) << 6; _Pragma("unroll") for (int i = 0; i < 4; ++i) { \
;     ra[i] = *(const u32x4*)(Ag + (size_t)(i * 64) * lda + k_); rb[i] = *(const u32x4*)(Bg + (size_t)(i * 64) * ldb + k_); } }
; #define L_STORE(ST) { u16* dA_ = sbase + (ST) * GSTAGE + lr * LSTR + lkw; u16* dB_ = dA_ + 256 * LSTR; _Pragma("unroll") for (int i = 0; i < 4; ++i) { \
;     *(u32x4*)(dA_ + i * 64 * LSTR) = ra[i]; *(u32x4*)(dB_ + i * 64 * LSTR) = rb[i]; } }
; template <int EPI>
; DI void gemm_tile(const Params& p, const u16* __restrict__ A, int lda, const u16* __restrict__ Bt, int ldb, int K, int m0, int n0,
;                   char* smem, u16* Cb, int ldc) {
;     ...
;   for (int kt = 0; kt < nk; ++kt) {
;     __syncthreads();
;     if (kt + 1 < nk) L_STORE((kt + 1) & 1)
;     G_LOAD(min(kt + 2, nk - 1))
;     const u16* cA = sbase + (kt & 1) * GSTAGE + (wr * 128 + fr) * LSTR;
;     const u16* cB = sbase + (kt & 1) * GSTAGE + 256 * LSTR + (wc * 64 + fr) * LSTR;
; #pragma unroll
;     for (int ks = 0; ks < 2; ++ks) {
;       bf16x8 bfr[4];
; #pragma unroll
;       for (int n = 0; n < 4; ++n) bfr[n] = *(const bf16x8*)(cB + n * 16 * LSTR + (ks ? fo1 : fo0));
; #pragma unroll
;       for (int mh = 0; mh < 2; ++mh) {
;         bf16x8 af[4];
; #pragma unroll
;         for (int m = 0; m < 4; ++m) af[m] = *(const bf16x8*)(cA + (mh * 4 + m) * 16 * LSTR + (ks ? fo1 : fo0));
;         __builtin_amdgcn_s_setprio(1);
; #pragma unroll
;         for (int m = 0; m < 4; ++m)
; #pragma unroll
;           for (int n = 0; n < 4; ++n)
;             acc[mh * 4 + m][n] = EpiSwap<EPI>::v ? __builtin_amdgcn_mfma_f32_16x16x32_bf16(bfr[n], af[m], acc[mh * 4 + m][n], 0, 0, 0)
;                                                  : __builtin_amdgcn_mfma_f32_16x16x32_bf16(af[m], bfr[n], acc[mh * 4 + m][n], 0, 0, 0);
;         __builtin_amdgcn_s_setprio(0);
;       }
;     }
;   }
.LBB0_605:
	s_and_b32 s0, s3, 0x8000
	s_lshl_b32 s0, s0, 1
	s_add_i32 s0, s0, 0
	v_add3_u32 v212, s0, v172, v174
	v_add3_u32 v213, s0, v173, v174
	v_add_u32_e32 v190, v213, v175
	v_add_u32_e32 v214, v212, v175
	ds_read_b128 v[178:181], v190 offset:32768
	ds_read_b128 v[182:185], v190 offset:34816
	ds_read_b128 v[186:189], v190 offset:36864
	ds_read_b128 v[190:193], v190 offset:38912
	ds_read_b128 v[196:199], v214
	ds_read_b128 v[200:203], v214 offset:2048
	ds_read_b128 v[204:207], v214 offset:4096
	ds_read_b128 v[208:211], v214 offset:6144
	s_min_i32 s0, s5, 29
	s_lshl_b32 s10, s0, 7
	s_waitcnt vmcnt(0)
	v_lshl_add_u64 v[152:153], v[164:165], 0, s[10:11]
	v_add_co_u32_e32 v136, vcc, s31, v152
	v_lshl_add_u64 v[156:157], v[166:167], 0, s[10:11]
	s_nop 0
	v_addc_co_u32_e32 v137, vcc, 0, v153, vcc
	v_add_co_u32_e32 v140, vcc, s31, v156
	global_load_dwordx4 v[132:135], v[152:153], off offset:256
	global_load_dwordx4 v[128:131], v[156:157], off offset:256
	v_addc_co_u32_e32 v141, vcc, 0, v157, vcc
	v_add_co_u32_e32 v144, vcc, s97, v152
	global_load_dwordx4 v[136:139], v[136:137], off offset:256
	s_nop 0
	v_addc_co_u32_e32 v145, vcc, 0, v153, vcc
	v_add_co_u32_e32 v148, vcc, s97, v156
	global_load_dwordx4 v[140:143], v[140:141], off offset:256
	s_nop 0
	v_addc_co_u32_e32 v149, vcc, 0, v157, vcc
	v_add_co_u32_e32 v152, vcc, s33, v152
	global_load_dwordx4 v[144:147], v[144:145], off offset:256
	s_nop 0
	v_addc_co_u32_e32 v153, vcc, 0, v153, vcc
	v_add_co_u32_e32 v156, vcc, s33, v156
	global_load_dwordx4 v[148:151], v[148:149], off offset:256
	s_nop 0
	v_addc_co_u32_e32 v157, vcc, 0, v157, vcc
	global_load_dwordx4 v[152:155], v[152:153], off offset:256
	s_nop 0
	global_load_dwordx4 v[156:159], v[156:157], off offset:256
	s_add_i32 s5, s5, 1
	s_setprio 1
	s_waitcnt lgkmcnt(3)
	v_mfma_f32_16x16x32_bf16 v[124:127], v[178:181], v[196:199], v[124:127]
	v_mfma_f32_16x16x32_bf16 v[92:95], v[182:185], v[196:199], v[92:95]
	v_mfma_f32_16x16x32_bf16 v[60:63], v[186:189], v[196:199], v[60:63]
	v_mfma_f32_16x16x32_bf16 v[28:31], v[190:193], v[196:199], v[28:31]
	s_waitcnt lgkmcnt(2)
	v_mfma_f32_16x16x32_bf16 v[120:123], v[178:181], v[200:203], v[120:123]
	v_mfma_f32_16x16x32_bf16 v[88:91], v[182:185], v[200:203], v[88:91]
	v_mfma_f32_16x16x32_bf16 v[56:59], v[186:189], v[200:203], v[56:59]
	v_mfma_f32_16x16x32_bf16 v[24:27], v[190:193], v[200:203], v[24:27]
	s_waitcnt lgkmcnt(1)
	v_mfma_f32_16x16x32_bf16 v[116:119], v[178:181], v[204:207], v[116:119]
	v_mfma_f32_16x16x32_bf16 v[84:87], v[182:185], v[204:207], v[84:87]
	v_mfma_f32_16x16x32_bf16 v[52:55], v[186:189], v[204:207], v[52:55]
	v_mfma_f32_16x16x32_bf16 v[20:23], v[190:193], v[204:207], v[20:23]
	s_waitcnt lgkmcnt(0)
	v_mfma_f32_16x16x32_bf16 v[112:115], v[178:181], v[208:211], v[112:115]
	v_mfma_f32_16x16x32_bf16 v[80:83], v[182:185], v[208:211], v[80:83]
	v_mfma_f32_16x16x32_bf16 v[48:51], v[186:189], v[208:211], v[48:51]
	v_mfma_f32_16x16x32_bf16 v[16:19], v[190:193], v[208:211], v[16:19]
	s_setprio 0
	ds_read_b128 v[196:199], v214 offset:8192
	ds_read_b128 v[200:203], v214 offset:10240
	ds_read_b128 v[204:207], v214 offset:12288
	ds_read_b128 v[208:211], v214 offset:14336
	s_setprio 1
	s_waitcnt lgkmcnt(3)
	v_mfma_f32_16x16x32_bf16 v[108:111], v[178:181], v[196:199], v[108:111]
	v_mfma_f32_16x16x32_bf16 v[76:79], v[182:185], v[196:199], v[76:79]
	v_mfma_f32_16x16x32_bf16 v[44:47], v[186:189], v[196:199], v[44:47]
	v_mfma_f32_16x16x32_bf16 v[12:15], v[190:193], v[196:199], v[12:15]
	s_waitcnt lgkmcnt(2)
	v_mfma_f32_16x16x32_bf16 v[104:107], v[178:181], v[200:203], v[104:107]
	v_mfma_f32_16x16x32_bf16 v[72:75], v[182:185], v[200:203], v[72:75]
	v_mfma_f32_16x16x32_bf16 v[40:43], v[186:189], v[200:203], v[40:43]
	v_mfma_f32_16x16x32_bf16 v[8:11], v[190:193], v[200:203], v[8:11]
	s_waitcnt lgkmcnt(1)
; template <int EPI>
; DI void gemm_tile(const Params& p, const u16* __restrict__ A, int lda, const u16* __restrict__ Bt, int ldb, int K, int m0, int n0,
;                   char* smem, u16* Cb, int ldc) {
;     ...
; #pragma unroll
;     for (int ks = 0; ks < 2; ++ks) {
;       bf16x8 bfr[4];
; #pragma unroll
;       for (int n = 0; n < 4; ++n) bfr[n] = *(const bf16x8*)(cB + n * 16 * LSTR + (ks ? fo1 : fo0));
; #pragma unroll
;       for (int mh = 0; mh < 2; ++mh) {
;         bf16x8 af[4];
; #pragma unroll
;         for (int m = 0; m < 4; ++m) af[m] = *(const bf16x8*)(cA + (mh * 4 + m) * 16 * LSTR + (ks ? fo1 : fo0));
;         __builtin_amdgcn_s_setprio(1);
; #pragma unroll
;         for (int m = 0; m < 4; ++m)
; #pragma unroll
;           for (int n = 0; n < 4; ++n)
;             acc[mh * 4 + m][n] = EpiSwap<EPI>::v ? __builtin_amdgcn_mfma_f32_16x16x32_bf16(bfr[n], af[m], acc[mh * 4 + m][n], 0, 0, 0)
;                                                  : __builtin_amdgcn_mfma_f32_16x16x32_bf16(af[m], bfr[n], acc[mh * 4 + m][n], 0, 0, 0);
;         __builtin_amdgcn_s_setprio(0);
;       }
;     }
	v_mfma_f32_16x16x32_bf16 v[100:103], v[178:181], v[204:207], v[100:103]
	v_mfma_f32_16x16x32_bf16 v[68:71], v[182:185], v[204:207], v[68:71]
	v_mfma_f32_16x16x32_bf16 v[36:39], v[186:189], v[204:207], v[36:39]
	v_mfma_f32_16x16x32_bf16 v[4:7], v[190:193], v[204:207], v[4:7]
	s_waitcnt lgkmcnt(0)
	v_mfma_f32_16x16x32_bf16 v[96:99], v[178:181], v[208:211], v[96:99]
	v_mfma_f32_16x16x32_bf16 v[64:67], v[182:185], v[208:211], v[64:67]
	v_mfma_f32_16x16x32_bf16 v[32:35], v[186:189], v[208:211], v[32:35]
	v_mfma_f32_16x16x32_bf16 v[0:3], v[190:193], v[208:211], v[0:3]
	s_setprio 0
	v_add_u32_e32 v190, v213, v176
	v_add_u32_e32 v212, v212, v176
	ds_read_b128 v[178:181], v190 offset:32768
	ds_read_b128 v[182:185], v190 offset:34816
	ds_read_b128 v[186:189], v190 offset:36864
	ds_read_b128 v[190:193], v190 offset:38912
	ds_read_b128 v[196:199], v212
	ds_read_b128 v[200:203], v212 offset:2048
	ds_read_b128 v[204:207], v212 offset:4096
	ds_read_b128 v[208:211], v212 offset:6144
	s_setprio 1
	s_waitcnt lgkmcnt(3)
	v_mfma_f32_16x16x32_bf16 v[124:127], v[178:181], v[196:199], v[124:127]
	v_mfma_f32_16x16x32_bf16 v[92:95], v[182:185], v[196:199], v[92:95]
	v_mfma_f32_16x16x32_bf16 v[60:63], v[186:189], v[196:199], v[60:63]
	v_mfma_f32_16x16x32_bf16 v[28:31], v[190:193], v[196:199], v[28:31]
	s_waitcnt lgkmcnt(2)
	v_mfma_f32_16x16x32_bf16 v[120:123], v[178:181], v[200:203], v[120:123]
	v_mfma_f32_16x16x32_bf16 v[88:91], v[182:185], v[200:203], v[88:91]
	v_mfma_f32_16x16x32_bf16 v[56:59], v[186:189], v[200:203], v[56:59]
	v_mfma_f32_16x16x32_bf16 v[24:27], v[190:193], v[200:203], v[24:27]
	s_waitcnt lgkmcnt(1)
	v_mfma_f32_16x16x32_bf16 v[116:119], v[178:181], v[204:207], v[116:119]
	v_mfma_f32_16x16x32_bf16 v[84:87], v[182:185], v[204:207], v[84:87]
	v_mfma_f32_16x16x32_bf16 v[52:55], v[186:189], v[204:207], v[52:55]
	v_mfma_f32_16x16x32_bf16 v[20:23], v[190:193], v[204:207], v[20:23]
	s_waitcnt lgkmcnt(0)
	v_mfma_f32_16x16x32_bf16 v[112:115], v[178:181], v[208:211], v[112:115]
	v_mfma_f32_16x16x32_bf16 v[80:83], v[182:185], v[208:211], v[80:83]
	v_mfma_f32_16x16x32_bf16 v[48:51], v[186:189], v[208:211], v[48:51]
	v_mfma_f32_16x16x32_bf16 v[16:19], v[190:193], v[208:211], v[16:19]
	s_setprio 0
	ds_read_b128 v[196:199], v212 offset:8192
	ds_read_b128 v[200:203], v212 offset:10240
	ds_read_b128 v[204:207], v212 offset:12288
	ds_read_b128 v[208:211], v212 offset:14336
	s_setprio 1
	s_waitcnt lgkmcnt(3)
	v_mfma_f32_16x16x32_bf16 v[108:111], v[178:181], v[196:199], v[108:111]
	v_mfma_f32_16x16x32_bf16 v[76:79], v[182:185], v[196:199], v[76:79]
	v_mfma_f32_16x16x32_bf16 v[44:47], v[186:189], v[196:199], v[44:47]
	v_mfma_f32_16x16x32_bf16 v[12:15], v[190:193], v[196:199], v[12:15]
	s_waitcnt lgkmcnt(2)
	v_mfma_f32_16x16x32_bf16 v[104:107], v[178:181], v[200:203], v[104:107]
	v_mfma_f32_16x16x32_bf16 v[72:75], v[182:185], v[200:203], v[72:75]
	v_mfma_f32_16x16x32_bf16 v[40:43], v[186:189], v[200:203], v[40:43]
	v_mfma_f32_16x16x32_bf16 v[8:11], v[190:193], v[200:203], v[8:11]
	s_waitcnt lgkmcnt(1)
	v_mfma_f32_16x16x32_bf16 v[100:103], v[178:181], v[204:207], v[100:103]
	v_mfma_f32_16x16x32_bf16 v[68:71], v[182:185], v[204:207], v[68:71]
	v_mfma_f32_16x16x32_bf16 v[36:39], v[186:189], v[204:207], v[36:39]
	v_mfma_f32_16x16x32_bf16 v[4:7], v[190:193], v[204:207], v[4:7]
	s_waitcnt lgkmcnt(0)
	v_mfma_f32_16x16x32_bf16 v[96:99], v[178:181], v[208:211], v[96:99]
	v_mfma_f32_16x16x32_bf16 v[64:67], v[182:185], v[208:211], v[64:67]
	v_mfma_f32_16x16x32_bf16 v[32:35], v[186:189], v[208:211], v[32:35]
	v_mfma_f32_16x16x32_bf16 v[0:3], v[190:193], v[208:211], v[0:3]
	s_setprio 0
	s_cmp_eq_u32 s5, 32
	s_mov_b32 s3, s24
	s_cbranch_scc1 .LBB0_610

; #define G_LOAD(T) { const int k_ = (T) << 6; _Pragma("unroll") for (int i = 0; i < 4; ++i) { \
;     ra[i] = *(const u32x4*)(Ag + (size_t)(i * 64) * lda + k_); rb[i] = *(const u32x4*)(Bg + (size_t)(i * 64) * ldb + k_); } }
; #define L_STORE(ST) { u16* dA_ = sbase + (ST) * GSTAGE + lr * LSTR + lkw; u16* dB_ = dA_ + 256 * LSTR; _Pragma("unroll") for (int i = 0; i < 4; ++i) { \
;     *(u32x4*)(dA_ + i * 64 * LSTR) = ra[i]; *(u32x4*)(dB_ + i * 64 * LSTR) = rb[i]; } }
; template <int EPI>
; DI void gemm_tile(const Params& p, const u16* __restrict__ A, int lda, const u16* __restrict__ Bt, int ldb, int K, int m0, int n0,
;                   char* smem, u16* Cb, int ldc) {
;     ...
;   for (int kt = 0; kt < nk; ++kt) {
;     __syncthreads();
;     if (kt + 1 < nk) L_STORE((kt + 1) & 1)
;     G_LOAD(min(kt + 2, nk - 1))
;     const u16* cA = sbase + (kt & 1) * GSTAGE + (wr * 128 + fr) * LSTR;
;     const u16* cB = sbase + (kt & 1) * GSTAGE + 256 * LSTR + (wc * 64 + fr) * LSTR;
; #pragma unroll
;     for (int ks = 0; ks < 2; ++ks) {
;       bf16x8 bfr[4];
; #pragma unroll
;       for (int n = 0; n < 4; ++n) bfr[n] = *(const bf16x8*)(cB + n * 16 * LSTR + (ks ? fo1 : fo0));
; #pragma unroll
;       for (int mh = 0; mh < 2; ++mh) {
;         bf16x8 af[4];
; #pragma unroll
;         for (int m = 0; m < 4; ++m) af[m] = *(const bf16x8*)(cA + (mh * 4 + m) * 16 * LSTR + (ks ? fo1 : fo0));
;         __builtin_amdgcn_s_setprio(1);
; #pragma unroll
;         for (int m = 0; m < 4; ++m)
; #pragma unroll
;           for (int n = 0; n < 4; ++n)
;             acc[mh * 4 + m][n] = EpiSwap<EPI>::v ? __builtin_amdgcn_mfma_f32_16x16x32_bf16(bfr[n], af[m], acc[mh * 4 + m][n], 0, 0, 0)
;                                                  : __builtin_amdgcn_mfma_f32_16x16x32_bf16(af[m], bfr[n], acc[mh * 4 + m][n], 0, 0, 0);
;         __builtin_amdgcn_s_setprio(0);
;       }
;     }
;   }
.LBB0_969:
	s_and_b32 s0, s3, 0x8000
	s_lshl_b32 s0, s0, 1
	s_add_i32 s0, s0, 0
	v_add3_u32 v212, s0, v176, v172
	v_add3_u32 v213, s0, v177, v172
	v_add_u32_e32 v190, v213, v173
	v_add_u32_e32 v214, v212, v173
	ds_read_b128 v[178:181], v190 offset:32768
	ds_read_b128 v[182:185], v190 offset:34816
	ds_read_b128 v[186:189], v190 offset:36864
	ds_read_b128 v[190:193], v190 offset:38912
	ds_read_b128 v[196:199], v214
	ds_read_b128 v[200:203], v214 offset:2048
	ds_read_b128 v[204:207], v214 offset:4096
	ds_read_b128 v[208:211], v214 offset:6144
	s_min_i32 s0, s5, 29
	s_lshl_b32 s10, s0, 7
	s_waitcnt vmcnt(1)
	v_lshl_add_u64 v[152:153], v[164:165], 0, s[10:11]
	v_add_co_u32_e32 v136, vcc, s31, v152
	s_waitcnt vmcnt(0)
	v_lshl_add_u64 v[156:157], v[166:167], 0, s[10:11]
	v_addc_co_u32_e32 v137, vcc, 0, v153, vcc
	v_add_co_u32_e32 v140, vcc, s31, v156
	global_load_dwordx4 v[128:131], v[152:153], off offset:256
	global_load_dwordx4 v[132:135], v[156:157], off offset:256
	v_addc_co_u32_e32 v141, vcc, 0, v157, vcc
	v_add_co_u32_e32 v144, vcc, s92, v152
	global_load_dwordx4 v[136:139], v[136:137], off offset:256
	s_nop 0
	v_addc_co_u32_e32 v145, vcc, 0, v153, vcc
	v_add_co_u32_e32 v148, vcc, s92, v156
	global_load_dwordx4 v[140:143], v[140:141], off offset:256
	s_nop 0
	v_addc_co_u32_e32 v149, vcc, 0, v157, vcc
	v_add_co_u32_e32 v152, vcc, s85, v152
	global_load_dwordx4 v[144:147], v[144:145], off offset:256
	s_nop 0
	v_addc_co_u32_e32 v153, vcc, 0, v153, vcc
	v_add_co_u32_e32 v156, vcc, s85, v156
	global_load_dwordx4 v[148:151], v[148:149], off offset:256
	s_nop 0
	v_addc_co_u32_e32 v157, vcc, 0, v157, vcc
	global_load_dwordx4 v[152:155], v[152:153], off offset:256
	s_nop 0
	global_load_dwordx4 v[156:159], v[156:157], off offset:256
	s_add_i32 s5, s5, 1
	s_setprio 1
	s_waitcnt lgkmcnt(3)
	v_mfma_f32_16x16x32_bf16 v[124:127], v[178:181], v[196:199], v[124:127]
	v_mfma_f32_16x16x32_bf16 v[92:95], v[182:185], v[196:199], v[92:95]
	v_mfma_f32_16x16x32_bf16 v[60:63], v[186:189], v[196:199], v[60:63]
	v_mfma_f32_16x16x32_bf16 v[28:31], v[190:193], v[196:199], v[28:31]
	s_waitcnt lgkmcnt(2)
	v_mfma_f32_16x16x32_bf16 v[120:123], v[178:181], v[200:203], v[120:123]
	v_mfma_f32_16x16x32_bf16 v[88:91], v[182:185], v[200:203], v[88:91]
	v_mfma_f32_16x16x32_bf16 v[56:59], v[186:189], v[200:203], v[56:59]
	v_mfma_f32_16x16x32_bf16 v[24:27], v[190:193], v[200:203], v[24:27]
	s_waitcnt lgkmcnt(1)
	v_mfma_f32_16x16x32_bf16 v[116:119], v[178:181], v[204:207], v[116:119]
	v_mfma_f32_16x16x32_bf16 v[84:87], v[182:185], v[204:207], v[84:87]
	v_mfma_f32_16x16x32_bf16 v[52:55], v[186:189], v[204:207], v[52:55]
	v_mfma_f32_16x16x32_bf16 v[20:23], v[190:193], v[204:207], v[20:23]
	s_waitcnt lgkmcnt(0)
	v_mfma_f32_16x16x32_bf16 v[112:115], v[178:181], v[208:211], v[112:115]
	v_mfma_f32_16x16x32_bf16 v[80:83], v[182:185], v[208:211], v[80:83]
	v_mfma_f32_16x16x32_bf16 v[48:51], v[186:189], v[208:211], v[48:51]
	v_mfma_f32_16x16x32_bf16 v[16:19], v[190:193], v[208:211], v[16:19]
	s_setprio 0
	ds_read_b128 v[196:199], v214 offset:8192
	ds_read_b128 v[200:203], v214 offset:10240
	ds_read_b128 v[204:207], v214 offset:12288
	ds_read_b128 v[208:211], v214 offset:14336
	s_setprio 1
	s_waitcnt lgkmcnt(3)
	v_mfma_f32_16x16x32_bf16 v[108:111], v[178:181], v[196:199], v[108:111]
	v_mfma_f32_16x16x32_bf16 v[76:79], v[182:185], v[196:199], v[76:79]
	v_mfma_f32_16x16x32_bf16 v[44:47], v[186:189], v[196:199], v[44:47]
	v_mfma_f32_16x16x32_bf16 v[12:15], v[190:193], v[196:199], v[12:15]
	s_waitcnt lgkmcnt(2)
	v_mfma_f32_16x16x32_bf16 v[104:107], v[178:181], v[200:203], v[104:107]
	v_mfma_f32_16x16x32_bf16 v[72:75], v[182:185], v[200:203], v[72:75]
	v_mfma_f32_16x16x32_bf16 v[40:43], v[186:189], v[200:203], v[40:43]
	v_mfma_f32_16x16x32_bf16 v[8:11], v[190:193], v[200:203], v[8:11]
	s_waitcnt lgkmcnt(1)
; template <int EPI>
; DI void gemm_tile(const Params& p, const u16* __restrict__ A, int lda, const u16* __restrict__ Bt, int ldb, int K, int m0, int n0,
;                   char* smem, u16* Cb, int ldc) {
;     ...
; #pragma unroll
;     for (int ks = 0; ks < 2; ++ks) {
;       bf16x8 bfr[4];
; #pragma unroll
;       for (int n = 0; n < 4; ++n) bfr[n] = *(const bf16x8*)(cB + n * 16 * LSTR + (ks ? fo1 : fo0));
; #pragma unroll
;       for (int mh = 0; mh < 2; ++mh) {
;         bf16x8 af[4];
; #pragma unroll
;         for (int m = 0; m < 4; ++m) af[m] = *(const bf16x8*)(cA + (mh * 4 + m) * 16 * LSTR + (ks ? fo1 : fo0));
;         __builtin_amdgcn_s_setprio(1);
; #pragma unroll
;         for (int m = 0; m < 4; ++m)
; #pragma unroll
;           for (int n = 0; n < 4; ++n)
;             acc[mh * 4 + m][n] = EpiSwap<EPI>::v ? __builtin_amdgcn_mfma_f32_16x16x32_bf16(bfr[n], af[m], acc[mh * 4 + m][n], 0, 0, 0)
;                                                  : __builtin_amdgcn_mfma_f32_16x16x32_bf16(af[m], bfr[n], acc[mh * 4 + m][n], 0, 0, 0);
;         __builtin_amdgcn_s_setprio(0);
;       }
;     }
	v_mfma_f32_16x16x32_bf16 v[100:103], v[178:181], v[204:207], v[100:103]
	v_mfma_f32_16x16x32_bf16 v[68:71], v[182:185], v[204:207], v[68:71]
	v_mfma_f32_16x16x32_bf16 v[36:39], v[186:189], v[204:207], v[36:39]
	v_mfma_f32_16x16x32_bf16 v[4:7], v[190:193], v[204:207], v[4:7]
	s_waitcnt lgkmcnt(0)
	v_mfma_f32_16x16x32_bf16 v[96:99], v[178:181], v[208:211], v[96:99]
	v_mfma_f32_16x16x32_bf16 v[64:67], v[182:185], v[208:211], v[64:67]
	v_mfma_f32_16x16x32_bf16 v[32:35], v[186:189], v[208:211], v[32:35]
	v_mfma_f32_16x16x32_bf16 v[0:3], v[190:193], v[208:211], v[0:3]
	s_setprio 0
	v_add_u32_e32 v190, v213, v174
	v_add_u32_e32 v212, v212, v174
	ds_read_b128 v[178:181], v190 offset:32768
	ds_read_b128 v[182:185], v190 offset:34816
	ds_read_b128 v[186:189], v190 offset:36864
	ds_read_b128 v[190:193], v190 offset:38912
	ds_read_b128 v[196:199], v212
	ds_read_b128 v[200:203], v212 offset:2048
	ds_read_b128 v[204:207], v212 offset:4096
	ds_read_b128 v[208:211], v212 offset:6144
	s_setprio 1
	s_waitcnt lgkmcnt(3)
	v_mfma_f32_16x16x32_bf16 v[124:127], v[178:181], v[196:199], v[124:127]
	v_mfma_f32_16x16x32_bf16 v[92:95], v[182:185], v[196:199], v[92:95]
	v_mfma_f32_16x16x32_bf16 v[60:63], v[186:189], v[196:199], v[60:63]
	v_mfma_f32_16x16x32_bf16 v[28:31], v[190:193], v[196:199], v[28:31]
	s_waitcnt lgkmcnt(2)
	v_mfma_f32_16x16x32_bf16 v[120:123], v[178:181], v[200:203], v[120:123]
	v_mfma_f32_16x16x32_bf16 v[88:91], v[182:185], v[200:203], v[88:91]
	v_mfma_f32_16x16x32_bf16 v[56:59], v[186:189], v[200:203], v[56:59]
	v_mfma_f32_16x16x32_bf16 v[24:27], v[190:193], v[200:203], v[24:27]
	s_waitcnt lgkmcnt(1)
	v_mfma_f32_16x16x32_bf16 v[116:119], v[178:181], v[204:207], v[116:119]
	v_mfma_f32_16x16x32_bf16 v[84:87], v[182:185], v[204:207], v[84:87]
	v_mfma_f32_16x16x32_bf16 v[52:55], v[186:189], v[204:207], v[52:55]
	v_mfma_f32_16x16x32_bf16 v[20:23], v[190:193], v[204:207], v[20:23]
	s_waitcnt lgkmcnt(0)
	v_mfma_f32_16x16x32_bf16 v[112:115], v[178:181], v[208:211], v[112:115]
	v_mfma_f32_16x16x32_bf16 v[80:83], v[182:185], v[208:211], v[80:83]
	v_mfma_f32_16x16x32_bf16 v[48:51], v[186:189], v[208:211], v[48:51]
	v_mfma_f32_16x16x32_bf16 v[16:19], v[190:193], v[208:211], v[16:19]
	s_setprio 0
	ds_read_b128 v[196:199], v212 offset:8192
	ds_read_b128 v[200:203], v212 offset:10240
	ds_read_b128 v[204:207], v212 offset:12288
	ds_read_b128 v[208:211], v212 offset:14336
	s_setprio 1
	s_waitcnt lgkmcnt(3)
	v_mfma_f32_16x16x32_bf16 v[108:111], v[178:181], v[196:199], v[108:111]
	v_mfma_f32_16x16x32_bf16 v[76:79], v[182:185], v[196:199], v[76:79]
	v_mfma_f32_16x16x32_bf16 v[44:47], v[186:189], v[196:199], v[44:47]
	v_mfma_f32_16x16x32_bf16 v[12:15], v[190:193], v[196:199], v[12:15]
	s_waitcnt lgkmcnt(2)
	v_mfma_f32_16x16x32_bf16 v[104:107], v[178:181], v[200:203], v[104:107]
	v_mfma_f32_16x16x32_bf16 v[72:75], v[182:185], v[200:203], v[72:75]
	v_mfma_f32_16x16x32_bf16 v[40:43], v[186:189], v[200:203], v[40:43]
	v_mfma_f32_16x16x32_bf16 v[8:11], v[190:193], v[200:203], v[8:11]
	s_waitcnt lgkmcnt(1)
	v_mfma_f32_16x16x32_bf16 v[100:103], v[178:181], v[204:207], v[100:103]
	v_mfma_f32_16x16x32_bf16 v[68:71], v[182:185], v[204:207], v[68:71]
	v_mfma_f32_16x16x32_bf16 v[36:39], v[186:189], v[204:207], v[36:39]
	v_mfma_f32_16x16x32_bf16 v[4:7], v[190:193], v[204:207], v[4:7]
	s_waitcnt lgkmcnt(0)
	v_mfma_f32_16x16x32_bf16 v[96:99], v[178:181], v[208:211], v[96:99]
	v_mfma_f32_16x16x32_bf16 v[64:67], v[182:185], v[208:211], v[64:67]
	v_mfma_f32_16x16x32_bf16 v[32:35], v[186:189], v[208:211], v[32:35]
	v_mfma_f32_16x16x32_bf16 v[0:3], v[190:193], v[208:211], v[0:3]
	s_setprio 0
	s_cmp_eq_u32 s5, 32
	s_mov_b32 s3, s24
	s_cbranch_scc1 .LBB0_974

; template <int MODE>
; DI void attn_item(const Params& p, int item, char* smem, u16* gdst) {
;     ...
;     if (active && jt < myt) {
;       f32x4 s[2][4];
; #pragma unroll
;       for (int qt = 0; qt < 2; ++qt) {
;         const float nb_ = (jt == 0) ? 0.f : -mrow[qt];
; #pragma unroll
;         for (int kt = 0; kt < 4; ++kt) s[qt][kt] = (f32x4){nb_, nb_, nb_, nb_};
;       }
; #pragma unroll
;       for (int kt = 0; kt < 4; ++kt) {
; #pragma unroll
;         for (int ks = 0; ks < NKS; ++ks) {
;           bf16x8 kf = *(const bf16x8*)(sK + (kt * 16 + fr) * KSTR + (ks >> 1) * 64 + ((ks & 1) ? ko1 : ko0));
.LBB0_1567:
	s_waitcnt vmcnt(2)
	s_add_i32 s60, s5, 0
	v_add_u32_e32 v120, s60, v197
	v_add_u32_e32 v128, v120, v196
	v_add_u32_e32 v129, v120, v198
	ds_read_b128 v[232:235], v128
	ds_read_b128 v[236:239], v129
	ds_read_b128 v[240:243], v128 offset:128
	ds_read_b128 v[244:247], v129 offset:128
	v_add_u32_e32 v132, s60, v199
	v_add_u32_e32 v136, v132, v196
	v_add_u32_e32 v137, v132, v198
	ds_read_b128 v[248:251], v136
	s_add_i32 s0, s4, 2
	s_min_i32 s0, s0, s11
	s_lshl_b32 s0, s0, 6
	s_add_i32 s16, s0, s10
	s_ashr_i32 s17, s16, 31
	v_lshl_add_u64 v[96:97], v[152:153], 0, s[16:17]
	v_lshlrev_b64 v[96:97], 12, v[96:97]
	v_lshl_add_u64 v[96:97], v[158:159], 0, v[96:97]
	v_add_co_u32_e32 v100, vcc, 0x20000, v96
	s_ashr_i32 s1, s0, 31
	s_nop 0
	v_addc_co_u32_e32 v101, vcc, 0, v97, vcc
	global_load_dwordx4 v[96:99], v[96:97], off
	s_nop 0
	global_load_dwordx4 v[104:107], v[100:101], off
	v_lshl_add_u64 v[100:101], s[0:1], 1, v[154:155]
	v_lshl_add_u64 v[108:109], v[100:101], 0, s[14:15]
	global_load_dwordx4 v[100:103], v[100:101], off
	s_nop 0
	global_load_dwordx4 v[108:111], v[108:109], off
	s_lshl_b32 s61, s4, 6
	v_cmp_lt_i32_e32 vcc, s4, v182
	s_and_b64 s[0:1], s[2:3], vcc
	s_and_saveexec_b64 s[16:17], s[0:1]
	s_cbranch_execz .LBB0_1577
	s_branch .Ldsa_qk_main

; template <int MODE>
; DI void attn_item(const Params& p, int item, char* smem, u16* gdst) {
;     ...
;     if (active && jt < myt) {
;       f32x4 s[2][4];
; #pragma unroll
;       for (int qt = 0; qt < 2; ++qt) {
;         const float nb_ = (jt == 0) ? 0.f : -mrow[qt];
; #pragma unroll
;         for (int kt = 0; kt < 4; ++kt) s[qt][kt] = (f32x4){nb_, nb_, nb_, nb_};
;       }
; #pragma unroll
;       for (int kt = 0; kt < 4; ++kt) {
; #pragma unroll
;         for (int ks = 0; ks < NKS; ++ks) {
;           bf16x8 kf = *(const bf16x8*)(sK + (kt * 16 + fr) * KSTR + (ks >> 1) * 64 + ((ks & 1) ? ko1 : ko0));
;           s[0][kt] = __builtin_amdgcn_mfma_f32_16x16x32_bf16(kf, qf[0][ks], s[0][kt], 0, 0, 0);
;           s[1][kt] = __builtin_amdgcn_mfma_f32_16x16x32_bf16(kf, qf[1][ks], s[1][kt], 0, 0, 0);
;         }
;       }
;       unsigned mlo[2] = {0u, 0u}, mhi[2] = {0u, 0u};
;       if (MODE == 0) {
;         if (key0 + 64 > nkeys) {
; #pragma unroll
;           for (int kt = 0; kt < 4; ++kt)
; #pragma unroll
;             for (int j = 0; j < 4; ++j)
;               if (key0 + kt * 16 + fq * 4 + j >= nkeys) { s[0][kt][j] = -1e30f; s[1][kt][j] = -1e30f; }
;         }
;       } else {
;         const bool far = (key0 + 63) - (qpos0 + wq0) <= -128;
.Ldsa_qk_main:
	s_cmp_eq_u32 s4, 0
	s_cselect_b64 s[4:5], -1, 0
	v_cndmask_b32_e64 v124, -v207, 0, s[4:5]
	v_cndmask_b32_e64 v140, -v205, 0, s[4:5]
	v_mov_b32_e32 v125, v124
	v_mov_b32_e32 v126, v124
	v_mov_b32_e32 v127, v124
	v_mov_b32_e32 v141, v140
	v_mov_b32_e32 v142, v140
	v_mov_b32_e32 v143, v140
	s_movk_i32 s0, 0xff80
	s_waitcnt lgkmcnt(4)
	v_mfma_f32_16x16x32_bf16 v[128:131], v[232:235], v[44:47], v[124:127]
	v_mfma_f32_16x16x32_bf16 v[112:115], v[232:235], v[64:67], v[140:143]
	ds_read_b128 v[232:235], v137
	s_waitcnt lgkmcnt(4)
	v_mfma_f32_16x16x32_bf16 v[128:131], v[236:239], v[52:55], v[128:131]
	v_mfma_f32_16x16x32_bf16 v[112:115], v[236:239], v[68:71], v[112:115]
	ds_read_b128 v[236:239], v136 offset:128
	s_waitcnt lgkmcnt(4)
	v_mfma_f32_16x16x32_bf16 v[128:131], v[240:243], v[56:59], v[128:131]
	v_mfma_f32_16x16x32_bf16 v[112:115], v[240:243], v[72:75], v[112:115]
	ds_read_b128 v[240:243], v137 offset:128
	s_waitcnt lgkmcnt(4)
	v_mfma_f32_16x16x32_bf16 v[128:131], v[244:247], v[60:63], v[128:131]
	v_mfma_f32_16x16x32_bf16 v[112:115], v[244:247], v[76:79], v[112:115]
	v_add_u32_e32 v147, s60, v200
	v_add_u32_e32 v157, v147, v196
	v_add_u32_e32 v147, v147, v198
	ds_read_b128 v[244:247], v157
	s_waitcnt lgkmcnt(4)
	v_mfma_f32_16x16x32_bf16 v[132:135], v[248:251], v[44:47], v[124:127]
	v_mfma_f32_16x16x32_bf16 v[116:119], v[248:251], v[64:67], v[140:143]
	ds_read_b128 v[248:251], v147
	s_waitcnt lgkmcnt(4)
	v_mfma_f32_16x16x32_bf16 v[132:135], v[232:235], v[52:55], v[132:135]
	v_mfma_f32_16x16x32_bf16 v[116:119], v[232:235], v[68:71], v[116:119]
	ds_read_b128 v[232:235], v157 offset:128
	s_waitcnt lgkmcnt(4)
	v_mfma_f32_16x16x32_bf16 v[132:135], v[236:239], v[56:59], v[132:135]
	v_mfma_f32_16x16x32_bf16 v[116:119], v[236:239], v[72:75], v[116:119]
	ds_read_b128 v[236:239], v147 offset:128
	s_waitcnt lgkmcnt(4)
	v_mfma_f32_16x16x32_bf16 v[132:135], v[240:243], v[60:63], v[132:135]
	v_mfma_f32_16x16x32_bf16 v[116:119], v[240:243], v[76:79], v[116:119]
	v_add_u32_e32 v147, s60, v201
	v_add_u32_e32 v157, v147, v196
	v_add_u32_e32 v147, v147, v198
	ds_read_b128 v[240:243], v157
	s_waitcnt lgkmcnt(4)
	v_mfma_f32_16x16x32_bf16 v[136:139], v[244:247], v[44:47], v[124:127]
	v_mfma_f32_16x16x32_bf16 v[120:123], v[244:247], v[64:67], v[140:143]
	ds_read_b128 v[244:247], v147
	s_waitcnt lgkmcnt(4)
	v_mfma_f32_16x16x32_bf16 v[136:139], v[248:251], v[52:55], v[136:139]
	v_mfma_f32_16x16x32_bf16 v[120:123], v[248:251], v[68:71], v[120:123]
	ds_read_b128 v[248:251], v157 offset:128
	s_waitcnt lgkmcnt(4)
	v_mfma_f32_16x16x32_bf16 v[136:139], v[232:235], v[56:59], v[136:139]
	v_mfma_f32_16x16x32_bf16 v[120:123], v[232:235], v[72:75], v[120:123]
	ds_read_b128 v[232:235], v147 offset:128
	s_waitcnt lgkmcnt(4)
	v_mfma_f32_16x16x32_bf16 v[136:139], v[236:239], v[60:63], v[136:139]
	v_mfma_f32_16x16x32_bf16 v[120:123], v[236:239], v[76:79], v[120:123]
	v_sub_u32_e32 v147, s61, v203
	v_add_u32_e32 v147, 63, v147
	s_waitcnt lgkmcnt(3)
	v_mfma_f32_16x16x32_bf16 v[252:255], v[240:243], v[64:67], v[140:143]
	v_mfma_f32_16x16x32_bf16 v[140:143], v[240:243], v[44:47], v[124:127]
	v_cmp_lt_i32_e32 vcc, s0, v147
	s_waitcnt lgkmcnt(2)
	v_mfma_f32_16x16x32_bf16 v[140:143], v[244:247], v[52:55], v[140:143]
	v_mfma_f32_16x16x32_bf16 v[252:255], v[244:247], v[68:71], v[252:255]
	s_waitcnt lgkmcnt(1)
	v_mfma_f32_16x16x32_bf16 v[140:143], v[248:251], v[56:59], v[140:143]
	v_mfma_f32_16x16x32_bf16 v[252:255], v[248:251], v[72:75], v[252:255]
	s_waitcnt lgkmcnt(0)
	v_mfma_f32_16x16x32_bf16 v[140:143], v[232:235], v[60:63], v[140:143]
	v_mfma_f32_16x16x32_bf16 v[124:127], v[232:235], v[76:79], v[252:255]
	s_and_saveexec_b64 s[18:19], vcc
	s_cbranch_execz .LBB0_1571
; template <int MODE>
; DI void attn_item(const Params& p, int item, char* smem, u16* gdst) {
;     ...
;         const bool far = (key0 + 63) - (qpos0 + wq0) <= -128;
;         if (!far) {
; #pragma unroll
;           for (int qt = 0; qt < 2; ++qt) {
;             const int rb = key0 + fq * 4 - (qpos0 + qrow[qt]) + 128;
; #pragma unroll
;             for (int kt = 0; kt < 4; ++kt)
; #pragma unroll
;               for (int j = 0; j < 4; ++j) {
;                 int r = min(max(rb + kt * 16 + j, 0), 256);
;                 s[qt][kt][j] += sBias[r];
;               }
;           }
;         }
	v_add_u32_e32 v147, s61, v192
	v_sub_u32_e32 v157, v147, v185
	s_nop 1
	v_max_i32_e32 v169, -1, v157
	v_add_u32_e32 v169, 1, v169
	v_med3_i32 v168, v157, 0, v180
	v_min_u32_e32 v169, 0x100, v169
	v_lshl_add_u32 v168, v168, 2, s34
	v_lshl_add_u32 v169, v169, 2, s34
	ds_read_b32 v168, v168
	ds_read_b32 v169, v169
	v_max_i32_e32 v170, -2, v157
	v_max_i32_e32 v171, -3, v157
	v_add_u32_e32 v170, 2, v170
	v_add_u32_e32 v171, 3, v171
	v_min_u32_e32 v170, 0x100, v170
	v_min_u32_e32 v171, 0x100, v171
	v_lshl_add_u32 v170, v170, 2, s34
	v_lshl_add_u32 v171, v171, 2, s34
	ds_read_b32 v170, v170
	ds_read_b32 v171, v171
	s_waitcnt lgkmcnt(2)
	v_pk_add_f32 v[128:129], v[128:129], v[168:169]
	v_max_i32_e32 v168, -16, v157
	v_max_i32_e32 v169, 0xffffffef, v157
	v_add_u32_e32 v168, 16, v168
	v_add_u32_e32 v169, 17, v169
	v_min_u32_e32 v168, 0x100, v168
	v_min_u32_e32 v169, 0x100, v169
	v_lshl_add_u32 v168, v168, 2, s34
	v_lshl_add_u32 v169, v169, 2, s34
	s_waitcnt lgkmcnt(0)
	v_pk_add_f32 v[130:131], v[130:131], v[170:171]
	ds_read_b32 v168, v168
	ds_read_b32 v169, v169
	v_max_i32_e32 v170, 0xffffffee, v157
	v_max_i32_e32 v171, 0xffffffed, v157
	v_add_u32_e32 v170, 18, v170
	v_add_u32_e32 v171, 19, v171
	v_min_u32_e32 v170, 0x100, v170
	v_min_u32_e32 v171, 0x100, v171
	v_lshl_add_u32 v170, v170, 2, s34
	v_lshl_add_u32 v171, v171, 2, s34
	ds_read_b32 v170, v170
	ds_read_b32 v171, v171
	s_waitcnt lgkmcnt(2)
	v_pk_add_f32 v[132:133], v[132:133], v[168:169]
	v_max_i32_e32 v168, 0xffffffe0, v157
	v_max_i32_e32 v169, 0xffffffdf, v157
	v_add_u32_e32 v168, 32, v168
	v_add_u32_e32 v169, 33, v169
	v_min_u32_e32 v168, 0x100, v168
	v_min_u32_e32 v169, 0x100, v169
	v_lshl_add_u32 v168, v168, 2, s34
	v_lshl_add_u32 v169, v169, 2, s34
	s_waitcnt lgkmcnt(0)
	v_pk_add_f32 v[134:135], v[134:135], v[170:171]
	ds_read_b32 v168, v168
	ds_read_b32 v169, v169
	v_max_i32_e32 v170, 0xffffffde, v157
	v_max_i32_e32 v171, 0xffffffdd, v157
	v_add_u32_e32 v170, 34, v170
	v_add_u32_e32 v171, 35, v171
	v_min_u32_e32 v170, 0x100, v170
	v_min_u32_e32 v171, 0x100, v171
	v_lshl_add_u32 v170, v170, 2, s34
	v_lshl_add_u32 v171, v171, 2, s34
	ds_read_b32 v170, v170
	ds_read_b32 v171, v171
	s_waitcnt lgkmcnt(2)
	v_pk_add_f32 v[136:137], v[136:137], v[168:169]
	v_max_i32_e32 v168, 0xffffffd0, v157
	v_max_i32_e32 v169, 0xffffffcf, v157
	v_add_u32_e32 v168, 48, v168
	v_add_u32_e32 v169, 49, v169
	v_min_u32_e32 v168, 0x100, v168
	v_min_u32_e32 v169, 0x100, v169
	v_lshl_add_u32 v168, v168, 2, s34
	v_lshl_add_u32 v169, v169, 2, s34
	ds_read_b32 v168, v168
	ds_read_b32 v169, v169
	s_waitcnt lgkmcnt(2)
	v_pk_add_f32 v[138:139], v[138:139], v[170:171]
	v_max_i32_e32 v170, 0xffffffce, v157
	v_max_i32_e32 v157, 0xffffffcd, v157
	v_add_u32_e32 v157, 51, v157
	v_min_u32_e32 v157, 0x100, v157
	v_add_u32_e32 v170, 50, v170
	v_lshl_add_u32 v157, v157, 2, s34
	v_sub_u32_e32 v147, v147, v186
	v_min_u32_e32 v170, 0x100, v170
	ds_read_b32 v171, v157
	v_med3_i32 v157, v147, 0, v180
	v_lshl_add_u32 v170, v170, 2, s34
	v_lshl_add_u32 v157, v157, 2, s34
	ds_read_b32 v170, v170
	s_waitcnt lgkmcnt(2)
	v_pk_add_f32 v[140:141], v[140:141], v[168:169]
	ds_read_b32 v168, v157
	v_max_i32_e32 v157, -1, v147
	v_add_u32_e32 v157, 1, v157
	v_min_u32_e32 v157, 0x100, v157
	v_lshl_add_u32 v157, v157, 2, s34
	ds_read_b32 v169, v157
	v_max_i32_e32 v157, -2, v147
	v_add_u32_e32 v157, 2, v157
	v_min_u32_e32 v157, 0x100, v157
	v_lshl_add_u32 v157, v157, 2, s34
	s_waitcnt lgkmcnt(2)
	v_pk_add_f32 v[142:143], v[142:143], v[170:171]
	ds_read_b32 v170, v157
	v_max_i32_e32 v157, -3, v147
	v_add_u32_e32 v157, 3, v157
	v_min_u32_e32 v157, 0x100, v157
	v_lshl_add_u32 v157, v157, 2, s34
	ds_read_b32 v171, v157
	v_max_i32_e32 v157, -16, v147
	v_add_u32_e32 v157, 16, v157
	v_min_u32_e32 v157, 0x100, v157
	v_lshl_add_u32 v157, v157, 2, s34
	s_waitcnt lgkmcnt(2)
	v_pk_add_f32 v[112:113], v[112:113], v[168:169]
	ds_read_b32 v168, v157
	v_max_i32_e32 v157, 0xffffffef, v147
	v_add_u32_e32 v157, 17, v157
	v_min_u32_e32 v157, 0x100, v157
	v_lshl_add_u32 v157, v157, 2, s34
	ds_read_b32 v169, v157
	v_max_i32_e32 v157, 0xffffffee, v147
	v_add_u32_e32 v157, 18, v157
	v_min_u32_e32 v157, 0x100, v157
	v_lshl_add_u32 v157, v157, 2, s34
	s_waitcnt lgkmcnt(2)
	v_pk_add_f32 v[114:115], v[114:115], v[170:171]
	ds_read_b32 v170, v157
	v_max_i32_e32 v157, 0xffffffed, v147
	v_add_u32_e32 v157, 19, v157
	v_min_u32_e32 v157, 0x100, v157
	v_lshl_add_u32 v157, v157, 2, s34
	ds_read_b32 v171, v157
	v_max_i32_e32 v157, 0xffffffe0, v147
	v_add_u32_e32 v157, 32, v157
	v_min_u32_e32 v157, 0x100, v157
	v_lshl_add_u32 v157, v157, 2, s34
	s_waitcnt lgkmcnt(2)
	v_pk_add_f32 v[116:117], v[116:117], v[168:169]
	ds_read_b32 v168, v157
	v_max_i32_e32 v157, 0xffffffdf, v147
	v_add_u32_e32 v157, 33, v157
	v_min_u32_e32 v157, 0x100, v157
	v_lshl_add_u32 v157, v157, 2, s34
	ds_read_b32 v169, v157
	v_max_i32_e32 v157, 0xffffffde, v147
	v_add_u32_e32 v157, 34, v157
	v_min_u32_e32 v157, 0x100, v157
	v_lshl_add_u32 v157, v157, 2, s34
	s_waitcnt lgkmcnt(2)
	v_pk_add_f32 v[118:119], v[118:119], v[170:171]
	ds_read_b32 v170, v157
	v_max_i32_e32 v157, 0xffffffdd, v147
	v_add_u32_e32 v157, 35, v157
	v_min_u32_e32 v157, 0x100, v157
	v_lshl_add_u32 v157, v157, 2, s34
	ds_read_b32 v171, v157
	v_max_i32_e32 v157, 0xffffffd0, v147
	v_add_u32_e32 v157, 48, v157
	v_min_u32_e32 v157, 0x100, v157
	v_lshl_add_u32 v157, v157, 2, s34
	s_waitcnt lgkmcnt(2)
	v_pk_add_f32 v[120:121], v[120:121], v[168:169]
	ds_read_b32 v168, v157
	v_max_i32_e32 v157, 0xffffffcf, v147
	v_add_u32_e32 v157, 49, v157
	v_min_u32_e32 v157, 0x100, v157
	v_lshl_add_u32 v157, v157, 2, s34
	ds_read_b32 v169, v157
	v_max_i32_e32 v157, 0xffffffce, v147
	v_max_i32_e32 v147, 0xffffffcd, v147
	v_add_u32_e32 v157, 50, v157
	v_add_u32_e32 v147, 51, v147
	v_min_u32_e32 v157, 0x100, v157
	v_min_u32_e32 v147, 0x100, v147
	v_lshl_add_u32 v157, v157, 2, s34
	v_lshl_add_u32 v147, v147, 2, s34
	s_waitcnt lgkmcnt(2)
	v_pk_add_f32 v[122:123], v[122:123], v[170:171]
	ds_read_b32 v170, v157
	ds_read_b32 v171, v147
	s_waitcnt lgkmcnt(2)
	v_pk_add_f32 v[124:125], v[124:125], v[168:169]
	s_waitcnt lgkmcnt(0)
	v_pk_add_f32 v[126:127], v[126:127], v[170:171]

; #define G_LOAD(T) { const int k_ = (T) << 6; _Pragma("unroll") for (int i = 0; i < 4; ++i) { \
;     ra[i] = *(const u32x4*)(Ag + (size_t)(i * 64) * lda + k_); rb[i] = *(const u32x4*)(Bg + (size_t)(i * 64) * ldb + k_); } }
; #define L_STORE(ST) { u16* dA_ = sbase + (ST) * GSTAGE + lr * LSTR + lkw; u16* dB_ = dA_ + 256 * LSTR; _Pragma("unroll") for (int i = 0; i < 4; ++i) { \
;     *(u32x4*)(dA_ + i * 64 * LSTR) = ra[i]; *(u32x4*)(dB_ + i * 64 * LSTR) = rb[i]; } }
; template <int EPI>
; DI void gemm_tile(const Params& p, const u16* __restrict__ A, int lda, const u16* __restrict__ Bt, int ldb, int K, int m0, int n0,
;                   char* smem, u16* Cb, int ldc) {
;     ...
;   for (int kt = 0; kt < nk; ++kt) {
;     __syncthreads();
;     if (kt + 1 < nk) L_STORE((kt + 1) & 1)
;     G_LOAD(min(kt + 2, nk - 1))
;     const u16* cA = sbase + (kt & 1) * GSTAGE + (wr * 128 + fr) * LSTR;
;     const u16* cB = sbase + (kt & 1) * GSTAGE + 256 * LSTR + (wc * 64 + fr) * LSTR;
; #pragma unroll
;     for (int ks = 0; ks < 2; ++ks) {
;       bf16x8 bfr[4];
; #pragma unroll
;       for (int n = 0; n < 4; ++n) bfr[n] = *(const bf16x8*)(cB + n * 16 * LSTR + (ks ? fo1 : fo0));
; #pragma unroll
;       for (int mh = 0; mh < 2; ++mh) {
;         bf16x8 af[4];
; #pragma unroll
;         for (int m = 0; m < 4; ++m) af[m] = *(const bf16x8*)(cA + (mh * 4 + m) * 16 * LSTR + (ks ? fo1 : fo0));
;         __builtin_amdgcn_s_setprio(1);
; #pragma unroll
;         for (int m = 0; m < 4; ++m)
; #pragma unroll
;           for (int n = 0; n < 4; ++n)
;             acc[mh * 4 + m][n] = EpiSwap<EPI>::v ? __builtin_amdgcn_mfma_f32_16x16x32_bf16(bfr[n], af[m], acc[mh * 4 + m][n], 0, 0, 0)
;                                                  : __builtin_amdgcn_mfma_f32_16x16x32_bf16(af[m], bfr[n], acc[mh * 4 + m][n], 0, 0, 0);
;         __builtin_amdgcn_s_setprio(0);
;       }
;     }
;   }
.LBB0_1615:
	s_and_b32 s0, s43, 0x8000
	s_lshl_b32 s0, s0, 1
	s_add_i32 s0, s0, 0
	v_add3_u32 v175, s0, v169, v171
	v_add3_u32 v192, s0, v170, v171
	v_add_u32_e32 v188, v192, v172
	v_add_u32_e32 v193, v175, v172
	ds_read_b128 v[176:179], v188 offset:32768
	ds_read_b128 v[180:183], v188 offset:34816
	ds_read_b128 v[184:187], v188 offset:36864
	ds_read_b128 v[188:191], v188 offset:38912
	ds_read_b128 v[196:199], v193
	ds_read_b128 v[200:203], v193 offset:2048
	ds_read_b128 v[204:207], v193 offset:4096
	ds_read_b128 v[208:211], v193 offset:6144
	s_min_i32 s0, s44, 1
	s_lshl_b32 s2, s0, 7
	s_waitcnt vmcnt(0)
	v_lshl_add_u64 v[152:153], v[162:163], 0, s[2:3]
	v_add_co_u32_e32 v136, vcc, s15, v152
	v_lshl_add_u64 v[156:157], v[164:165], 0, s[2:3]
	s_nop 0
	v_addc_co_u32_e32 v137, vcc, 0, v153, vcc
	v_add_co_u32_e32 v140, vcc, s15, v156
	global_load_dwordx4 v[132:135], v[152:153], off offset:256
	global_load_dwordx4 v[128:131], v[156:157], off offset:256
	v_addc_co_u32_e32 v141, vcc, 0, v157, vcc
	v_add_co_u32_e32 v144, vcc, s18, v152
	global_load_dwordx4 v[136:139], v[136:137], off offset:256
	s_nop 0
	v_addc_co_u32_e32 v145, vcc, 0, v153, vcc
	v_add_co_u32_e32 v148, vcc, s18, v156
	global_load_dwordx4 v[140:143], v[140:141], off offset:256
	s_nop 0
	v_addc_co_u32_e32 v149, vcc, 0, v157, vcc
	v_add_co_u32_e32 v152, vcc, s19, v152
	global_load_dwordx4 v[144:147], v[144:145], off offset:256
	s_nop 0
	v_addc_co_u32_e32 v153, vcc, 0, v153, vcc
	v_add_co_u32_e32 v156, vcc, s19, v156
	global_load_dwordx4 v[148:151], v[148:149], off offset:256
	s_nop 0
	v_addc_co_u32_e32 v157, vcc, 0, v157, vcc
	global_load_dwordx4 v[152:155], v[152:153], off offset:256
	s_nop 0
	global_load_dwordx4 v[156:159], v[156:157], off offset:256
	s_add_i32 s44, s44, 1
	s_setprio 1
	s_waitcnt lgkmcnt(3)
	v_mfma_f32_16x16x32_bf16 v[124:127], v[196:199], v[176:179], v[124:127]
	v_mfma_f32_16x16x32_bf16 v[120:123], v[196:199], v[180:183], v[120:123]
	v_mfma_f32_16x16x32_bf16 v[116:119], v[196:199], v[184:187], v[116:119]
	v_mfma_f32_16x16x32_bf16 v[112:115], v[196:199], v[188:191], v[112:115]
	s_waitcnt lgkmcnt(2)
	v_mfma_f32_16x16x32_bf16 v[108:111], v[200:203], v[176:179], v[108:111]
	v_mfma_f32_16x16x32_bf16 v[104:107], v[200:203], v[180:183], v[104:107]
	v_mfma_f32_16x16x32_bf16 v[100:103], v[200:203], v[184:187], v[100:103]
	v_mfma_f32_16x16x32_bf16 v[96:99], v[200:203], v[188:191], v[96:99]
	s_waitcnt lgkmcnt(1)
	v_mfma_f32_16x16x32_bf16 v[92:95], v[204:207], v[176:179], v[92:95]
	v_mfma_f32_16x16x32_bf16 v[88:91], v[204:207], v[180:183], v[88:91]
	v_mfma_f32_16x16x32_bf16 v[84:87], v[204:207], v[184:187], v[84:87]
	v_mfma_f32_16x16x32_bf16 v[80:83], v[204:207], v[188:191], v[80:83]
	s_waitcnt lgkmcnt(0)
	v_mfma_f32_16x16x32_bf16 v[76:79], v[208:211], v[176:179], v[76:79]
	v_mfma_f32_16x16x32_bf16 v[72:75], v[208:211], v[180:183], v[72:75]
	v_mfma_f32_16x16x32_bf16 v[68:71], v[208:211], v[184:187], v[68:71]
	v_mfma_f32_16x16x32_bf16 v[64:67], v[208:211], v[188:191], v[64:67]
	s_setprio 0
	ds_read_b128 v[196:199], v193 offset:8192
	ds_read_b128 v[200:203], v193 offset:10240
	ds_read_b128 v[204:207], v193 offset:12288
	ds_read_b128 v[208:211], v193 offset:14336
	s_setprio 1
	s_waitcnt lgkmcnt(3)
	v_mfma_f32_16x16x32_bf16 v[60:63], v[196:199], v[176:179], v[60:63]
	v_mfma_f32_16x16x32_bf16 v[56:59], v[196:199], v[180:183], v[56:59]
	v_mfma_f32_16x16x32_bf16 v[52:55], v[196:199], v[184:187], v[52:55]
	v_mfma_f32_16x16x32_bf16 v[48:51], v[196:199], v[188:191], v[48:51]
	s_waitcnt lgkmcnt(2)
	v_mfma_f32_16x16x32_bf16 v[44:47], v[200:203], v[176:179], v[44:47]
	v_mfma_f32_16x16x32_bf16 v[40:43], v[200:203], v[180:183], v[40:43]
	v_mfma_f32_16x16x32_bf16 v[36:39], v[200:203], v[184:187], v[36:39]
	v_mfma_f32_16x16x32_bf16 v[32:35], v[200:203], v[188:191], v[32:35]
	s_waitcnt lgkmcnt(1)
; template <int EPI>
; DI void gemm_tile(const Params& p, const u16* __restrict__ A, int lda, const u16* __restrict__ Bt, int ldb, int K, int m0, int n0,
;                   char* smem, u16* Cb, int ldc) {
;     ...
; #pragma unroll
;     for (int ks = 0; ks < 2; ++ks) {
;       bf16x8 bfr[4];
; #pragma unroll
;       for (int n = 0; n < 4; ++n) bfr[n] = *(const bf16x8*)(cB + n * 16 * LSTR + (ks ? fo1 : fo0));
; #pragma unroll
;       for (int mh = 0; mh < 2; ++mh) {
;         bf16x8 af[4];
; #pragma unroll
;         for (int m = 0; m < 4; ++m) af[m] = *(const bf16x8*)(cA + (mh * 4 + m) * 16 * LSTR + (ks ? fo1 : fo0));
;         __builtin_amdgcn_s_setprio(1);
; #pragma unroll
;         for (int m = 0; m < 4; ++m)
; #pragma unroll
;           for (int n = 0; n < 4; ++n)
;             acc[mh * 4 + m][n] = EpiSwap<EPI>::v ? __builtin_amdgcn_mfma_f32_16x16x32_bf16(bfr[n], af[m], acc[mh * 4 + m][n], 0, 0, 0)
;                                                  : __builtin_amdgcn_mfma_f32_16x16x32_bf16(af[m], bfr[n], acc[mh * 4 + m][n], 0, 0, 0);
;         __builtin_amdgcn_s_setprio(0);
;       }
;     }
	v_mfma_f32_16x16x32_bf16 v[28:31], v[204:207], v[176:179], v[28:31]
	v_mfma_f32_16x16x32_bf16 v[24:27], v[204:207], v[180:183], v[24:27]
	v_mfma_f32_16x16x32_bf16 v[20:23], v[204:207], v[184:187], v[20:23]
	v_mfma_f32_16x16x32_bf16 v[16:19], v[204:207], v[188:191], v[16:19]
	s_waitcnt lgkmcnt(0)
	v_mfma_f32_16x16x32_bf16 v[12:15], v[208:211], v[176:179], v[12:15]
	v_mfma_f32_16x16x32_bf16 v[8:11], v[208:211], v[180:183], v[8:11]
	v_mfma_f32_16x16x32_bf16 v[4:7], v[208:211], v[184:187], v[4:7]
	v_mfma_f32_16x16x32_bf16 v[0:3], v[208:211], v[188:191], v[0:3]
	s_setprio 0
	v_add_u32_e32 v188, v192, v173
	v_add_u32_e32 v175, v175, v173
	ds_read_b128 v[176:179], v188 offset:32768
	ds_read_b128 v[180:183], v188 offset:34816
	ds_read_b128 v[184:187], v188 offset:36864
	ds_read_b128 v[188:191], v188 offset:38912
	ds_read_b128 v[196:199], v175
	ds_read_b128 v[200:203], v175 offset:2048
	ds_read_b128 v[204:207], v175 offset:4096
	ds_read_b128 v[208:211], v175 offset:6144
	s_setprio 1
	s_waitcnt lgkmcnt(3)
	v_mfma_f32_16x16x32_bf16 v[124:127], v[196:199], v[176:179], v[124:127]
	v_mfma_f32_16x16x32_bf16 v[120:123], v[196:199], v[180:183], v[120:123]
	v_mfma_f32_16x16x32_bf16 v[116:119], v[196:199], v[184:187], v[116:119]
	v_mfma_f32_16x16x32_bf16 v[112:115], v[196:199], v[188:191], v[112:115]
	s_waitcnt lgkmcnt(2)
	v_mfma_f32_16x16x32_bf16 v[108:111], v[200:203], v[176:179], v[108:111]
	v_mfma_f32_16x16x32_bf16 v[104:107], v[200:203], v[180:183], v[104:107]
	v_mfma_f32_16x16x32_bf16 v[100:103], v[200:203], v[184:187], v[100:103]
	v_mfma_f32_16x16x32_bf16 v[96:99], v[200:203], v[188:191], v[96:99]
	s_waitcnt lgkmcnt(1)
	v_mfma_f32_16x16x32_bf16 v[92:95], v[204:207], v[176:179], v[92:95]
	v_mfma_f32_16x16x32_bf16 v[88:91], v[204:207], v[180:183], v[88:91]
	v_mfma_f32_16x16x32_bf16 v[84:87], v[204:207], v[184:187], v[84:87]
	v_mfma_f32_16x16x32_bf16 v[80:83], v[204:207], v[188:191], v[80:83]
	s_waitcnt lgkmcnt(0)
	v_mfma_f32_16x16x32_bf16 v[76:79], v[208:211], v[176:179], v[76:79]
	v_mfma_f32_16x16x32_bf16 v[72:75], v[208:211], v[180:183], v[72:75]
	v_mfma_f32_16x16x32_bf16 v[68:71], v[208:211], v[184:187], v[68:71]
	v_mfma_f32_16x16x32_bf16 v[64:67], v[208:211], v[188:191], v[64:67]
	s_setprio 0
	ds_read_b128 v[196:199], v175 offset:8192
	ds_read_b128 v[200:203], v175 offset:10240
	ds_read_b128 v[204:207], v175 offset:12288
	ds_read_b128 v[208:211], v175 offset:14336
	s_setprio 1
	s_waitcnt lgkmcnt(3)
	v_mfma_f32_16x16x32_bf16 v[60:63], v[196:199], v[176:179], v[60:63]
	v_mfma_f32_16x16x32_bf16 v[56:59], v[196:199], v[180:183], v[56:59]
	v_mfma_f32_16x16x32_bf16 v[52:55], v[196:199], v[184:187], v[52:55]
	v_mfma_f32_16x16x32_bf16 v[48:51], v[196:199], v[188:191], v[48:51]
	s_waitcnt lgkmcnt(2)
	v_mfma_f32_16x16x32_bf16 v[44:47], v[200:203], v[176:179], v[44:47]
	v_mfma_f32_16x16x32_bf16 v[40:43], v[200:203], v[180:183], v[40:43]
	v_mfma_f32_16x16x32_bf16 v[36:39], v[200:203], v[184:187], v[36:39]
	v_mfma_f32_16x16x32_bf16 v[32:35], v[200:203], v[188:191], v[32:35]
	s_waitcnt lgkmcnt(1)
	v_mfma_f32_16x16x32_bf16 v[28:31], v[204:207], v[176:179], v[28:31]
	v_mfma_f32_16x16x32_bf16 v[24:27], v[204:207], v[180:183], v[24:27]
	v_mfma_f32_16x16x32_bf16 v[20:23], v[204:207], v[184:187], v[20:23]
	v_mfma_f32_16x16x32_bf16 v[16:19], v[204:207], v[188:191], v[16:19]
	s_waitcnt lgkmcnt(0)
	v_mfma_f32_16x16x32_bf16 v[12:15], v[208:211], v[176:179], v[12:15]
	v_mfma_f32_16x16x32_bf16 v[8:11], v[208:211], v[180:183], v[8:11]
	v_mfma_f32_16x16x32_bf16 v[4:7], v[208:211], v[184:187], v[4:7]
	v_mfma_f32_16x16x32_bf16 v[0:3], v[208:211], v[188:191], v[0:3]
	s_setprio 0
	s_cmp_eq_u32 s44, 4
	s_mov_b32 s43, s45
	s_cbranch_scc1 .LBB0_1620

; #define G_LOAD(T) { const int k_ = (T) << 6; _Pragma("unroll") for (int i = 0; i < 4; ++i) { \
;     ra[i] = *(const u32x4*)(Ag + (size_t)(i * 64) * lda + k_); rb[i] = *(const u32x4*)(Bg + (size_t)(i * 64) * ldb + k_); } }
; #define L_STORE(ST) { u16* dA_ = sbase + (ST) * GSTAGE + lr * LSTR + lkw; u16* dB_ = dA_ + 256 * LSTR; _Pragma("unroll") for (int i = 0; i < 4; ++i) { \
;     *(u32x4*)(dA_ + i * 64 * LSTR) = ra[i]; *(u32x4*)(dB_ + i * 64 * LSTR) = rb[i]; } }
; template <int EPI>
; DI void gemm_tile(const Params& p, const u16* __restrict__ A, int lda, const u16* __restrict__ Bt, int ldb, int K, int m0, int n0,
;                   char* smem, u16* Cb, int ldc) {
;     ...
;   for (int kt = 0; kt < nk; ++kt) {
;     __syncthreads();
;     if (kt + 1 < nk) L_STORE((kt + 1) & 1)
;     G_LOAD(min(kt + 2, nk - 1))
;     const u16* cA = sbase + (kt & 1) * GSTAGE + (wr * 128 + fr) * LSTR;
;     const u16* cB = sbase + (kt & 1) * GSTAGE + 256 * LSTR + (wc * 64 + fr) * LSTR;
; #pragma unroll
;     for (int ks = 0; ks < 2; ++ks) {
;       bf16x8 bfr[4];
; #pragma unroll
;       for (int n = 0; n < 4; ++n) bfr[n] = *(const bf16x8*)(cB + n * 16 * LSTR + (ks ? fo1 : fo0));
; #pragma unroll
;       for (int mh = 0; mh < 2; ++mh) {
;         bf16x8 af[4];
; #pragma unroll
;         for (int m = 0; m < 4; ++m) af[m] = *(const bf16x8*)(cA + (mh * 4 + m) * 16 * LSTR + (ks ? fo1 : fo0));
;         __builtin_amdgcn_s_setprio(1);
; #pragma unroll
;         for (int m = 0; m < 4; ++m)
; #pragma unroll
;           for (int n = 0; n < 4; ++n)
;             acc[mh * 4 + m][n] = EpiSwap<EPI>::v ? __builtin_amdgcn_mfma_f32_16x16x32_bf16(bfr[n], af[m], acc[mh * 4 + m][n], 0, 0, 0)
;                                                  : __builtin_amdgcn_mfma_f32_16x16x32_bf16(af[m], bfr[n], acc[mh * 4 + m][n], 0, 0, 0);
;         __builtin_amdgcn_s_setprio(0);
;       }
;     }
;   }
.LBB0_1751:
	s_and_b32 s0, s43, 0x8000
	s_lshl_b32 s0, s0, 1
	s_add_i32 s0, s0, 0
	v_add3_u32 v175, s0, v169, v171
	v_add3_u32 v192, s0, v170, v171
	v_add_u32_e32 v188, v192, v172
	v_add_u32_e32 v193, v175, v172
	ds_read_b128 v[176:179], v188 offset:32768
	ds_read_b128 v[180:183], v188 offset:34816
	ds_read_b128 v[184:187], v188 offset:36864
	ds_read_b128 v[188:191], v188 offset:38912
	ds_read_b128 v[196:199], v193
	ds_read_b128 v[200:203], v193 offset:2048
	ds_read_b128 v[204:207], v193 offset:4096
	ds_read_b128 v[208:211], v193 offset:6144
	s_min_i32 s0, s44, 1
	s_lshl_b32 s2, s0, 7
	s_waitcnt vmcnt(0)
	v_lshl_add_u64 v[148:149], v[162:163], 0, s[2:3]
	v_add_co_u32_e32 v132, vcc, s15, v148
	v_lshl_add_u64 v[152:153], v[164:165], 0, s[2:3]
	s_nop 0
	v_addc_co_u32_e32 v133, vcc, 0, v149, vcc
	v_add_co_u32_e32 v136, vcc, s15, v152
	global_load_dwordx4 v[128:131], v[148:149], off offset:256
	global_load_dwordx4 v[120:123], v[152:153], off offset:256
	v_addc_co_u32_e32 v137, vcc, 0, v153, vcc
	v_add_co_u32_e32 v140, vcc, s18, v148
	global_load_dwordx4 v[132:135], v[132:133], off offset:256
	s_nop 0
	v_addc_co_u32_e32 v141, vcc, 0, v149, vcc
	v_add_co_u32_e32 v144, vcc, s18, v152
	global_load_dwordx4 v[136:139], v[136:137], off offset:256
	s_nop 0
	v_addc_co_u32_e32 v145, vcc, 0, v153, vcc
	v_add_co_u32_e32 v148, vcc, s19, v148
	global_load_dwordx4 v[140:143], v[140:141], off offset:256
	s_nop 0
	v_addc_co_u32_e32 v149, vcc, 0, v149, vcc
	v_add_co_u32_e32 v152, vcc, s19, v152
	global_load_dwordx4 v[144:147], v[144:145], off offset:256
	s_nop 0
	v_addc_co_u32_e32 v153, vcc, 0, v153, vcc
	global_load_dwordx4 v[148:151], v[148:149], off offset:256
	s_nop 0
	global_load_dwordx4 v[152:155], v[152:153], off offset:256
	s_add_i32 s44, s44, 1
	s_setprio 1
	s_waitcnt lgkmcnt(3)
	v_mfma_f32_16x16x32_bf16 v[156:159], v[176:179], v[196:199], v[156:159]
	v_mfma_f32_16x16x32_bf16 v[108:111], v[180:183], v[196:199], v[108:111]
	v_mfma_f32_16x16x32_bf16 v[92:95], v[184:187], v[196:199], v[92:95]
	v_mfma_f32_16x16x32_bf16 v[64:67], v[188:191], v[196:199], v[64:67]
	s_waitcnt lgkmcnt(2)
	v_mfma_f32_16x16x32_bf16 v[124:127], v[176:179], v[200:203], v[124:127]
	v_mfma_f32_16x16x32_bf16 v[100:103], v[180:183], v[200:203], v[100:103]
	v_mfma_f32_16x16x32_bf16 v[80:83], v[184:187], v[200:203], v[80:83]
	v_mfma_f32_16x16x32_bf16 v[48:51], v[188:191], v[200:203], v[48:51]
	s_waitcnt lgkmcnt(1)
	v_mfma_f32_16x16x32_bf16 v[116:119], v[176:179], v[204:207], v[116:119]
	v_mfma_f32_16x16x32_bf16 v[96:99], v[180:183], v[204:207], v[96:99]
	v_mfma_f32_16x16x32_bf16 v[68:71], v[184:187], v[204:207], v[68:71]
	v_mfma_f32_16x16x32_bf16 v[36:39], v[188:191], v[204:207], v[36:39]
	s_waitcnt lgkmcnt(0)
	v_mfma_f32_16x16x32_bf16 v[112:115], v[176:179], v[208:211], v[112:115]
	v_mfma_f32_16x16x32_bf16 v[84:87], v[180:183], v[208:211], v[84:87]
	v_mfma_f32_16x16x32_bf16 v[52:55], v[184:187], v[208:211], v[52:55]
	v_mfma_f32_16x16x32_bf16 v[24:27], v[188:191], v[208:211], v[24:27]
	s_setprio 0
	ds_read_b128 v[196:199], v193 offset:8192
	ds_read_b128 v[200:203], v193 offset:10240
	ds_read_b128 v[204:207], v193 offset:12288
	ds_read_b128 v[208:211], v193 offset:14336
	s_setprio 1
	s_waitcnt lgkmcnt(3)
	v_mfma_f32_16x16x32_bf16 v[104:107], v[176:179], v[196:199], v[104:107]
	v_mfma_f32_16x16x32_bf16 v[72:75], v[180:183], v[196:199], v[72:75]
	v_mfma_f32_16x16x32_bf16 v[40:43], v[184:187], v[196:199], v[40:43]
	v_mfma_f32_16x16x32_bf16 v[16:19], v[188:191], v[196:199], v[16:19]
	s_waitcnt lgkmcnt(2)
	v_mfma_f32_16x16x32_bf16 v[88:91], v[176:179], v[200:203], v[88:91]
	v_mfma_f32_16x16x32_bf16 v[56:59], v[180:183], v[200:203], v[56:59]
	v_mfma_f32_16x16x32_bf16 v[28:31], v[184:187], v[200:203], v[28:31]
	v_mfma_f32_16x16x32_bf16 v[8:11], v[188:191], v[200:203], v[8:11]
	s_waitcnt lgkmcnt(1)
; template <int EPI>
; DI void gemm_tile(const Params& p, const u16* __restrict__ A, int lda, const u16* __restrict__ Bt, int ldb, int K, int m0, int n0,
;                   char* smem, u16* Cb, int ldc) {
;     ...
; #pragma unroll
;     for (int ks = 0; ks < 2; ++ks) {
;       bf16x8 bfr[4];
; #pragma unroll
;       for (int n = 0; n < 4; ++n) bfr[n] = *(const bf16x8*)(cB + n * 16 * LSTR + (ks ? fo1 : fo0));
; #pragma unroll
;       for (int mh = 0; mh < 2; ++mh) {
;         bf16x8 af[4];
; #pragma unroll
;         for (int m = 0; m < 4; ++m) af[m] = *(const bf16x8*)(cA + (mh * 4 + m) * 16 * LSTR + (ks ? fo1 : fo0));
;         __builtin_amdgcn_s_setprio(1);
; #pragma unroll
;         for (int m = 0; m < 4; ++m)
; #pragma unroll
;           for (int n = 0; n < 4; ++n)
;             acc[mh * 4 + m][n] = EpiSwap<EPI>::v ? __builtin_amdgcn_mfma_f32_16x16x32_bf16(bfr[n], af[m], acc[mh * 4 + m][n], 0, 0, 0)
;                                                  : __builtin_amdgcn_mfma_f32_16x16x32_bf16(af[m], bfr[n], acc[mh * 4 + m][n], 0, 0, 0);
;         __builtin_amdgcn_s_setprio(0);
;       }
;     }
	v_mfma_f32_16x16x32_bf16 v[76:79], v[176:179], v[204:207], v[76:79]
	v_mfma_f32_16x16x32_bf16 v[44:47], v[180:183], v[204:207], v[44:47]
	v_mfma_f32_16x16x32_bf16 v[20:23], v[184:187], v[204:207], v[20:23]
	v_mfma_f32_16x16x32_bf16 v[4:7], v[188:191], v[204:207], v[4:7]
	s_waitcnt lgkmcnt(0)
	v_mfma_f32_16x16x32_bf16 v[60:63], v[176:179], v[208:211], v[60:63]
	v_mfma_f32_16x16x32_bf16 v[32:35], v[180:183], v[208:211], v[32:35]
	v_mfma_f32_16x16x32_bf16 v[12:15], v[184:187], v[208:211], v[12:15]
	v_mfma_f32_16x16x32_bf16 v[0:3], v[188:191], v[208:211], v[0:3]
	s_setprio 0
	v_add_u32_e32 v188, v192, v173
	v_add_u32_e32 v175, v175, v173
	ds_read_b128 v[176:179], v188 offset:32768
	ds_read_b128 v[180:183], v188 offset:34816
	ds_read_b128 v[184:187], v188 offset:36864
	ds_read_b128 v[188:191], v188 offset:38912
	ds_read_b128 v[196:199], v175
	ds_read_b128 v[200:203], v175 offset:2048
	ds_read_b128 v[204:207], v175 offset:4096
	ds_read_b128 v[208:211], v175 offset:6144
	s_setprio 1
	s_waitcnt lgkmcnt(3)
	v_mfma_f32_16x16x32_bf16 v[156:159], v[176:179], v[196:199], v[156:159]
	v_mfma_f32_16x16x32_bf16 v[108:111], v[180:183], v[196:199], v[108:111]
	v_mfma_f32_16x16x32_bf16 v[92:95], v[184:187], v[196:199], v[92:95]
	v_mfma_f32_16x16x32_bf16 v[64:67], v[188:191], v[196:199], v[64:67]
	s_waitcnt lgkmcnt(2)
	v_mfma_f32_16x16x32_bf16 v[124:127], v[176:179], v[200:203], v[124:127]
	v_mfma_f32_16x16x32_bf16 v[100:103], v[180:183], v[200:203], v[100:103]
	v_mfma_f32_16x16x32_bf16 v[80:83], v[184:187], v[200:203], v[80:83]
	v_mfma_f32_16x16x32_bf16 v[48:51], v[188:191], v[200:203], v[48:51]
	s_waitcnt lgkmcnt(1)
	v_mfma_f32_16x16x32_bf16 v[116:119], v[176:179], v[204:207], v[116:119]
	v_mfma_f32_16x16x32_bf16 v[96:99], v[180:183], v[204:207], v[96:99]
	v_mfma_f32_16x16x32_bf16 v[68:71], v[184:187], v[204:207], v[68:71]
	v_mfma_f32_16x16x32_bf16 v[36:39], v[188:191], v[204:207], v[36:39]
	s_waitcnt lgkmcnt(0)
	v_mfma_f32_16x16x32_bf16 v[112:115], v[176:179], v[208:211], v[112:115]
	v_mfma_f32_16x16x32_bf16 v[84:87], v[180:183], v[208:211], v[84:87]
	v_mfma_f32_16x16x32_bf16 v[52:55], v[184:187], v[208:211], v[52:55]
	v_mfma_f32_16x16x32_bf16 v[24:27], v[188:191], v[208:211], v[24:27]
	s_setprio 0
	ds_read_b128 v[196:199], v175 offset:8192
	ds_read_b128 v[200:203], v175 offset:10240
	ds_read_b128 v[204:207], v175 offset:12288
	ds_read_b128 v[208:211], v175 offset:14336
	s_setprio 1
	s_waitcnt lgkmcnt(3)
	v_mfma_f32_16x16x32_bf16 v[104:107], v[176:179], v[196:199], v[104:107]
	v_mfma_f32_16x16x32_bf16 v[72:75], v[180:183], v[196:199], v[72:75]
	v_mfma_f32_16x16x32_bf16 v[40:43], v[184:187], v[196:199], v[40:43]
	v_mfma_f32_16x16x32_bf16 v[16:19], v[188:191], v[196:199], v[16:19]
	s_waitcnt lgkmcnt(2)
	v_mfma_f32_16x16x32_bf16 v[88:91], v[176:179], v[200:203], v[88:91]
	v_mfma_f32_16x16x32_bf16 v[56:59], v[180:183], v[200:203], v[56:59]
	v_mfma_f32_16x16x32_bf16 v[28:31], v[184:187], v[200:203], v[28:31]
	v_mfma_f32_16x16x32_bf16 v[8:11], v[188:191], v[200:203], v[8:11]
	s_waitcnt lgkmcnt(1)
	v_mfma_f32_16x16x32_bf16 v[76:79], v[176:179], v[204:207], v[76:79]
	v_mfma_f32_16x16x32_bf16 v[44:47], v[180:183], v[204:207], v[44:47]
	v_mfma_f32_16x16x32_bf16 v[20:23], v[184:187], v[204:207], v[20:23]
	v_mfma_f32_16x16x32_bf16 v[4:7], v[188:191], v[204:207], v[4:7]
	s_waitcnt lgkmcnt(0)
	v_mfma_f32_16x16x32_bf16 v[60:63], v[176:179], v[208:211], v[60:63]
	v_mfma_f32_16x16x32_bf16 v[32:35], v[180:183], v[208:211], v[32:35]
	v_mfma_f32_16x16x32_bf16 v[12:15], v[184:187], v[208:211], v[12:15]
	v_mfma_f32_16x16x32_bf16 v[0:3], v[188:191], v[208:211], v[0:3]
	s_setprio 0
	s_cmp_lg_u32 s44, 4
	s_mov_b32 s43, s45
	s_cbranch_scc0 .LBB0_1756

; #define G_LOAD(T) { const int k_ = (T) << 6; _Pragma("unroll") for (int i = 0; i < 4; ++i) { \
;     ra[i] = *(const u32x4*)(Ag + (size_t)(i * 64) * lda + k_); rb[i] = *(const u32x4*)(Bg + (size_t)(i * 64) * ldb + k_); } }
; #define L_STORE(ST) { u16* dA_ = sbase + (ST) * GSTAGE + lr * LSTR + lkw; u16* dB_ = dA_ + 256 * LSTR; _Pragma("unroll") for (int i = 0; i < 4; ++i) { \
;     *(u32x4*)(dA_ + i * 64 * LSTR) = ra[i]; *(u32x4*)(dB_ + i * 64 * LSTR) = rb[i]; } }
; template <int EPI>
; DI void gemm_tile(const Params& p, const u16* __restrict__ A, int lda, const u16* __restrict__ Bt, int ldb, int K, int m0, int n0,
;                   char* smem, u16* Cb, int ldc) {
;     ...
;   for (int kt = 0; kt < nk; ++kt) {
;     __syncthreads();
;     if (kt + 1 < nk) L_STORE((kt + 1) & 1)
;     G_LOAD(min(kt + 2, nk - 1))
;     const u16* cA = sbase + (kt & 1) * GSTAGE + (wr * 128 + fr) * LSTR;
;     const u16* cB = sbase + (kt & 1) * GSTAGE + 256 * LSTR + (wc * 64 + fr) * LSTR;
; #pragma unroll
;     for (int ks = 0; ks < 2; ++ks) {
;       bf16x8 bfr[4];
; #pragma unroll
;       for (int n = 0; n < 4; ++n) bfr[n] = *(const bf16x8*)(cB + n * 16 * LSTR + (ks ? fo1 : fo0));
; #pragma unroll
;       for (int mh = 0; mh < 2; ++mh) {
;         bf16x8 af[4];
; #pragma unroll
;         for (int m = 0; m < 4; ++m) af[m] = *(const bf16x8*)(cA + (mh * 4 + m) * 16 * LSTR + (ks ? fo1 : fo0));
;         __builtin_amdgcn_s_setprio(1);
; #pragma unroll
;         for (int m = 0; m < 4; ++m)
; #pragma unroll
;           for (int n = 0; n < 4; ++n)
;             acc[mh * 4 + m][n] = EpiSwap<EPI>::v ? __builtin_amdgcn_mfma_f32_16x16x32_bf16(bfr[n], af[m], acc[mh * 4 + m][n], 0, 0, 0)
;                                                  : __builtin_amdgcn_mfma_f32_16x16x32_bf16(af[m], bfr[n], acc[mh * 4 + m][n], 0, 0, 0);
;         __builtin_amdgcn_s_setprio(0);
;       }
;     }
;   }
.LBB0_1761:
	s_and_b32 s0, s44, 0x8000
	s_lshl_b32 s0, s0, 1
	s_add_i32 s0, s0, 0
	v_add3_u32 v175, s0, v169, v171
	v_add3_u32 v192, s0, v170, v171
	v_add_u32_e32 v188, v192, v173
	v_add_u32_e32 v193, v175, v173
	ds_read_b128 v[176:179], v188 offset:32768
	ds_read_b128 v[180:183], v188 offset:34816
	ds_read_b128 v[184:187], v188 offset:36864
	ds_read_b128 v[188:191], v188 offset:38912
	ds_read_b128 v[196:199], v193
	ds_read_b128 v[200:203], v193 offset:2048
	ds_read_b128 v[204:207], v193 offset:4096
	ds_read_b128 v[208:211], v193 offset:6144
	s_min_i32 s0, s45, 5
	s_lshl_b32 s2, s0, 7
	s_waitcnt vmcnt(0)
	v_lshl_add_u64 v[152:153], v[162:163], 0, s[2:3]
	v_add_co_u32_e32 v136, vcc, s18, v152
	v_lshl_add_u64 v[156:157], v[164:165], 0, s[2:3]
	s_nop 0
	v_addc_co_u32_e32 v137, vcc, 0, v153, vcc
	v_add_co_u32_e32 v140, vcc, s18, v156
	global_load_dwordx4 v[132:135], v[152:153], off offset:256
	global_load_dwordx4 v[128:131], v[156:157], off offset:256
	v_addc_co_u32_e32 v141, vcc, 0, v157, vcc
	v_add_co_u32_e32 v144, vcc, s33, v152
	global_load_dwordx4 v[136:139], v[136:137], off offset:256
	s_nop 0
	v_addc_co_u32_e32 v145, vcc, 0, v153, vcc
	v_add_co_u32_e32 v148, vcc, s33, v156
	global_load_dwordx4 v[140:143], v[140:141], off offset:256
	s_nop 0
	v_addc_co_u32_e32 v149, vcc, 0, v157, vcc
	v_add_co_u32_e32 v152, vcc, s34, v152
	global_load_dwordx4 v[144:147], v[144:145], off offset:256
	s_nop 0
	v_addc_co_u32_e32 v153, vcc, 0, v153, vcc
	v_add_co_u32_e32 v156, vcc, s34, v156
	global_load_dwordx4 v[148:151], v[148:149], off offset:256
	s_nop 0
	v_addc_co_u32_e32 v157, vcc, 0, v157, vcc
	global_load_dwordx4 v[152:155], v[152:153], off offset:256
	s_nop 0
	global_load_dwordx4 v[156:159], v[156:157], off offset:256
	s_add_i32 s45, s45, 1
	s_setprio 1
	s_waitcnt lgkmcnt(3)
	v_mfma_f32_16x16x32_bf16 v[124:127], v[176:179], v[196:199], v[124:127]
	v_mfma_f32_16x16x32_bf16 v[116:119], v[180:183], v[196:199], v[116:119]
	v_mfma_f32_16x16x32_bf16 v[120:123], v[184:187], v[196:199], v[120:123]
	v_mfma_f32_16x16x32_bf16 v[112:115], v[188:191], v[196:199], v[112:115]
	s_waitcnt lgkmcnt(2)
	v_mfma_f32_16x16x32_bf16 v[108:111], v[176:179], v[200:203], v[108:111]
	v_mfma_f32_16x16x32_bf16 v[100:103], v[180:183], v[200:203], v[100:103]
	v_mfma_f32_16x16x32_bf16 v[104:107], v[184:187], v[200:203], v[104:107]
	v_mfma_f32_16x16x32_bf16 v[96:99], v[188:191], v[200:203], v[96:99]
	s_waitcnt lgkmcnt(1)
	v_mfma_f32_16x16x32_bf16 v[92:95], v[176:179], v[204:207], v[92:95]
	v_mfma_f32_16x16x32_bf16 v[84:87], v[180:183], v[204:207], v[84:87]
	v_mfma_f32_16x16x32_bf16 v[88:91], v[184:187], v[204:207], v[88:91]
	v_mfma_f32_16x16x32_bf16 v[80:83], v[188:191], v[204:207], v[80:83]
	s_waitcnt lgkmcnt(0)
	v_mfma_f32_16x16x32_bf16 v[76:79], v[176:179], v[208:211], v[76:79]
	v_mfma_f32_16x16x32_bf16 v[68:71], v[180:183], v[208:211], v[68:71]
	v_mfma_f32_16x16x32_bf16 v[72:75], v[184:187], v[208:211], v[72:75]
	v_mfma_f32_16x16x32_bf16 v[64:67], v[188:191], v[208:211], v[64:67]
	s_setprio 0
	ds_read_b128 v[196:199], v193 offset:8192
	ds_read_b128 v[200:203], v193 offset:10240
	ds_read_b128 v[204:207], v193 offset:12288
	ds_read_b128 v[208:211], v193 offset:14336
	s_setprio 1
	s_waitcnt lgkmcnt(3)
	v_mfma_f32_16x16x32_bf16 v[60:63], v[176:179], v[196:199], v[60:63]
	v_mfma_f32_16x16x32_bf16 v[52:55], v[180:183], v[196:199], v[52:55]
	v_mfma_f32_16x16x32_bf16 v[56:59], v[184:187], v[196:199], v[56:59]
	v_mfma_f32_16x16x32_bf16 v[48:51], v[188:191], v[196:199], v[48:51]
	s_waitcnt lgkmcnt(2)
	v_mfma_f32_16x16x32_bf16 v[44:47], v[176:179], v[200:203], v[44:47]
	v_mfma_f32_16x16x32_bf16 v[36:39], v[180:183], v[200:203], v[36:39]
	v_mfma_f32_16x16x32_bf16 v[40:43], v[184:187], v[200:203], v[40:43]
	v_mfma_f32_16x16x32_bf16 v[32:35], v[188:191], v[200:203], v[32:35]
	s_waitcnt lgkmcnt(1)
; template <int EPI>
; DI void gemm_tile(const Params& p, const u16* __restrict__ A, int lda, const u16* __restrict__ Bt, int ldb, int K, int m0, int n0,
;                   char* smem, u16* Cb, int ldc) {
;     ...
; #pragma unroll
;     for (int ks = 0; ks < 2; ++ks) {
;       bf16x8 bfr[4];
; #pragma unroll
;       for (int n = 0; n < 4; ++n) bfr[n] = *(const bf16x8*)(cB + n * 16 * LSTR + (ks ? fo1 : fo0));
; #pragma unroll
;       for (int mh = 0; mh < 2; ++mh) {
;         bf16x8 af[4];
; #pragma unroll
;         for (int m = 0; m < 4; ++m) af[m] = *(const bf16x8*)(cA + (mh * 4 + m) * 16 * LSTR + (ks ? fo1 : fo0));
;         __builtin_amdgcn_s_setprio(1);
; #pragma unroll
;         for (int m = 0; m < 4; ++m)
; #pragma unroll
;           for (int n = 0; n < 4; ++n)
;             acc[mh * 4 + m][n] = EpiSwap<EPI>::v ? __builtin_amdgcn_mfma_f32_16x16x32_bf16(bfr[n], af[m], acc[mh * 4 + m][n], 0, 0, 0)
;                                                  : __builtin_amdgcn_mfma_f32_16x16x32_bf16(af[m], bfr[n], acc[mh * 4 + m][n], 0, 0, 0);
;         __builtin_amdgcn_s_setprio(0);
;       }
;     }
	v_mfma_f32_16x16x32_bf16 v[28:31], v[176:179], v[204:207], v[28:31]
	v_mfma_f32_16x16x32_bf16 v[20:23], v[180:183], v[204:207], v[20:23]
	v_mfma_f32_16x16x32_bf16 v[24:27], v[184:187], v[204:207], v[24:27]
	v_mfma_f32_16x16x32_bf16 v[16:19], v[188:191], v[204:207], v[16:19]
	s_waitcnt lgkmcnt(0)
	v_mfma_f32_16x16x32_bf16 v[12:15], v[176:179], v[208:211], v[12:15]
	v_mfma_f32_16x16x32_bf16 v[4:7], v[180:183], v[208:211], v[4:7]
	v_mfma_f32_16x16x32_bf16 v[8:11], v[184:187], v[208:211], v[8:11]
	v_mfma_f32_16x16x32_bf16 v[0:3], v[188:191], v[208:211], v[0:3]
	s_setprio 0
	v_add_u32_e32 v188, v192, v174
	v_add_u32_e32 v175, v175, v174
	ds_read_b128 v[176:179], v188 offset:32768
	ds_read_b128 v[180:183], v188 offset:34816
	ds_read_b128 v[184:187], v188 offset:36864
	ds_read_b128 v[188:191], v188 offset:38912
	ds_read_b128 v[196:199], v175
	ds_read_b128 v[200:203], v175 offset:2048
	ds_read_b128 v[204:207], v175 offset:4096
	ds_read_b128 v[208:211], v175 offset:6144
	s_setprio 1
	s_waitcnt lgkmcnt(3)
	v_mfma_f32_16x16x32_bf16 v[124:127], v[176:179], v[196:199], v[124:127]
	v_mfma_f32_16x16x32_bf16 v[116:119], v[180:183], v[196:199], v[116:119]
	v_mfma_f32_16x16x32_bf16 v[120:123], v[184:187], v[196:199], v[120:123]
	v_mfma_f32_16x16x32_bf16 v[112:115], v[188:191], v[196:199], v[112:115]
	s_waitcnt lgkmcnt(2)
	v_mfma_f32_16x16x32_bf16 v[108:111], v[176:179], v[200:203], v[108:111]
	v_mfma_f32_16x16x32_bf16 v[100:103], v[180:183], v[200:203], v[100:103]
	v_mfma_f32_16x16x32_bf16 v[104:107], v[184:187], v[200:203], v[104:107]
	v_mfma_f32_16x16x32_bf16 v[96:99], v[188:191], v[200:203], v[96:99]
	s_waitcnt lgkmcnt(1)
	v_mfma_f32_16x16x32_bf16 v[92:95], v[176:179], v[204:207], v[92:95]
	v_mfma_f32_16x16x32_bf16 v[84:87], v[180:183], v[204:207], v[84:87]
	v_mfma_f32_16x16x32_bf16 v[88:91], v[184:187], v[204:207], v[88:91]
	v_mfma_f32_16x16x32_bf16 v[80:83], v[188:191], v[204:207], v[80:83]
	s_waitcnt lgkmcnt(0)
	v_mfma_f32_16x16x32_bf16 v[76:79], v[176:179], v[208:211], v[76:79]
	v_mfma_f32_16x16x32_bf16 v[68:71], v[180:183], v[208:211], v[68:71]
	v_mfma_f32_16x16x32_bf16 v[72:75], v[184:187], v[208:211], v[72:75]
	v_mfma_f32_16x16x32_bf16 v[64:67], v[188:191], v[208:211], v[64:67]
	s_setprio 0
	ds_read_b128 v[196:199], v175 offset:8192
	ds_read_b128 v[200:203], v175 offset:10240
	ds_read_b128 v[204:207], v175 offset:12288
	ds_read_b128 v[208:211], v175 offset:14336
	s_setprio 1
	s_waitcnt lgkmcnt(3)
	v_mfma_f32_16x16x32_bf16 v[60:63], v[176:179], v[196:199], v[60:63]
	v_mfma_f32_16x16x32_bf16 v[52:55], v[180:183], v[196:199], v[52:55]
	v_mfma_f32_16x16x32_bf16 v[56:59], v[184:187], v[196:199], v[56:59]
	v_mfma_f32_16x16x32_bf16 v[48:51], v[188:191], v[196:199], v[48:51]
	s_waitcnt lgkmcnt(2)
	v_mfma_f32_16x16x32_bf16 v[44:47], v[176:179], v[200:203], v[44:47]
	v_mfma_f32_16x16x32_bf16 v[36:39], v[180:183], v[200:203], v[36:39]
	v_mfma_f32_16x16x32_bf16 v[40:43], v[184:187], v[200:203], v[40:43]
	v_mfma_f32_16x16x32_bf16 v[32:35], v[188:191], v[200:203], v[32:35]
	s_waitcnt lgkmcnt(1)
	v_mfma_f32_16x16x32_bf16 v[28:31], v[176:179], v[204:207], v[28:31]
	v_mfma_f32_16x16x32_bf16 v[20:23], v[180:183], v[204:207], v[20:23]
	v_mfma_f32_16x16x32_bf16 v[24:27], v[184:187], v[204:207], v[24:27]
	v_mfma_f32_16x16x32_bf16 v[16:19], v[188:191], v[204:207], v[16:19]
	s_waitcnt lgkmcnt(0)
	v_mfma_f32_16x16x32_bf16 v[12:15], v[176:179], v[208:211], v[12:15]
	v_mfma_f32_16x16x32_bf16 v[4:7], v[180:183], v[208:211], v[4:7]
	v_mfma_f32_16x16x32_bf16 v[8:11], v[184:187], v[208:211], v[8:11]
	v_mfma_f32_16x16x32_bf16 v[0:3], v[188:191], v[208:211], v[0:3]
	s_setprio 0
	s_cmp_eq_u32 s45, 8
	s_mov_b32 s44, s46
	s_cbranch_scc1 .LBB0_1766

; template <int MODE>
; DI void attn_item(const Params& p, int item, char* smem, u16* gdst) {
;     ...
;     if (active && jt < myt) {
;       f32x4 s[2][4];
; #pragma unroll
;       for (int qt = 0; qt < 2; ++qt) {
;         const float nb_ = (jt == 0) ? 0.f : -mrow[qt];
; #pragma unroll
;         for (int kt = 0; kt < 4; ++kt) s[qt][kt] = (f32x4){nb_, nb_, nb_, nb_};
;       }
; #pragma unroll
;       for (int kt = 0; kt < 4; ++kt) {
; #pragma unroll
;         for (int ks = 0; ks < NKS; ++ks) {
;           bf16x8 kf = *(const bf16x8*)(sK + (kt * 16 + fr) * KSTR + (ks >> 1) * 64 + ((ks & 1) ? ko1 : ko0));
;           s[0][kt] = __builtin_amdgcn_mfma_f32_16x16x32_bf16(kf, qf[0][ks], s[0][kt], 0, 0, 0);
;           s[1][kt] = __builtin_amdgcn_mfma_f32_16x16x32_bf16(kf, qf[1][ks], s[1][kt], 0, 0, 0);
;         }
;       }
;       unsigned mlo[2] = {0u, 0u}, mhi[2] = {0u, 0u};
;       if (MODE == 0) {
;         if (key0 + 64 > nkeys) {
.LBB0_1800:
	s_bitcmp1_b32 s0, 0
	s_cselect_b32 s36, 0xa800, 0
	v_add_u32_e32 v0, s36, v200
	v_add_u32_e32 v209, v0, v199
	v_add_u32_e32 v0, v0, v191
	ds_read_b128 v[232:235], v209
	ds_read_b128 v[236:239], v0
	ds_read_b128 v[240:243], v209 offset:128
	ds_read_b128 v[244:247], v0 offset:128
	ds_read_b128 v[248:251], v209 offset:256
	s_add_i32 s1, s0, 2
	s_min_i32 s1, s1, s13
	s_lshl_b32 s4, s1, 6
	s_add_i32 s6, s4, s12
	s_ashr_i32 s7, s6, 31
	s_waitcnt vmcnt(4)
	v_lshl_add_u64 v[52:53], s[6:7], 0, v[168:169]
	v_lshlrev_b64 v[52:53], 12, v[52:53]
	v_lshl_add_u64 v[52:53], v[2:3], 0, v[52:53]
	s_waitcnt vmcnt(2)
	v_lshl_add_u64 v[60:61], s[6:7], 0, v[170:171]
	s_ashr_i32 s5, s4, 31
	v_add_co_u32_e32 v56, vcc, 0x20000, v52
	v_lshlrev_b64 v[60:61], 7, v[60:61]
	s_waitcnt vmcnt(1)
	v_lshl_add_u64 v[64:65], s[4:5], 1, v[174:175]
	v_addc_co_u32_e32 v57, vcc, 0, v53, vcc
	v_lshl_add_u64 v[60:61], v[176:177], 0, v[60:61]
	s_waitcnt vmcnt(0)
	v_lshl_add_u64 v[68:69], v[64:65], 0, s[10:11]
	global_load_dwordx4 v[52:55], v[52:53], off
	s_nop 0
	global_load_dwordx4 v[56:59], v[56:57], off
	v_cmp_lt_i32_e32 vcc, s0, v185
	global_load_dwordx4 v[60:63], v[60:61], off
	s_nop 0
	global_load_dwordx4 v[64:67], v[64:65], off
	s_nop 0
	global_load_dwordx4 v[68:71], v[68:69], off
	s_and_b64 s[4:5], s[2:3], vcc
	s_and_saveexec_b64 s[14:15], s[4:5]
	s_cbranch_execz .LBB0_1814
	v_xor_b32_e32 v148, 0x80000000, v201
	v_xor_b32_e32 v164, 0x80000000, v203
	v_mov_b32_e32 v149, v148
	v_mov_b32_e32 v150, v148
	v_mov_b32_e32 v151, v148
	v_mov_b32_e32 v165, v164
	v_mov_b32_e32 v166, v164
	v_mov_b32_e32 v167, v164
	s_waitcnt lgkmcnt(4)
	v_mfma_f32_16x16x32_bf16 v[152:155], v[232:235], v[4:7], v[148:151]
	v_mfma_f32_16x16x32_bf16 v[136:139], v[232:235], v[28:31], v[164:167]
	ds_read_b128 v[232:235], v0 offset:256
	s_waitcnt lgkmcnt(4)
	v_mfma_f32_16x16x32_bf16 v[152:155], v[236:239], v[8:11], v[152:155]
	v_mfma_f32_16x16x32_bf16 v[136:139], v[236:239], v[32:35], v[136:139]
	v_add_u32_e32 v0, s36, v205
	v_add_u32_e32 v209, v0, v199
	v_add_u32_e32 v0, v0, v191
	ds_read_b128 v[236:239], v209
	s_waitcnt lgkmcnt(4)
	v_mfma_f32_16x16x32_bf16 v[152:155], v[240:243], v[12:15], v[152:155]
	v_mfma_f32_16x16x32_bf16 v[136:139], v[240:243], v[36:39], v[136:139]
	ds_read_b128 v[240:243], v0
	s_waitcnt lgkmcnt(4)
	v_mfma_f32_16x16x32_bf16 v[152:155], v[244:247], v[16:19], v[152:155]
	v_mfma_f32_16x16x32_bf16 v[136:139], v[244:247], v[40:43], v[136:139]
	ds_read_b128 v[244:247], v209 offset:128
	s_waitcnt lgkmcnt(4)
	v_mfma_f32_16x16x32_bf16 v[152:155], v[248:251], v[20:23], v[152:155]
	v_mfma_f32_16x16x32_bf16 v[136:139], v[248:251], v[44:47], v[136:139]
	ds_read_b128 v[248:251], v0 offset:128
	s_waitcnt lgkmcnt(4)
	v_mfma_f32_16x16x32_bf16 v[152:155], v[232:235], v[24:27], v[152:155]
	v_mfma_f32_16x16x32_bf16 v[136:139], v[232:235], v[48:51], v[136:139]
	ds_read_b128 v[232:235], v209 offset:256
	s_waitcnt lgkmcnt(4)
	v_mfma_f32_16x16x32_bf16 v[156:159], v[236:239], v[4:7], v[148:151]
	v_mfma_f32_16x16x32_bf16 v[140:143], v[236:239], v[28:31], v[164:167]
	ds_read_b128 v[236:239], v0 offset:256
	s_waitcnt lgkmcnt(4)
	v_mfma_f32_16x16x32_bf16 v[156:159], v[240:243], v[8:11], v[156:159]
	v_mfma_f32_16x16x32_bf16 v[140:143], v[240:243], v[32:35], v[140:143]
	v_add_u32_e32 v0, s36, v206
	v_add_u32_e32 v209, v0, v199
	v_add_u32_e32 v0, v0, v191
	ds_read_b128 v[240:243], v209
	s_waitcnt lgkmcnt(4)
	v_mfma_f32_16x16x32_bf16 v[156:159], v[244:247], v[12:15], v[156:159]
	v_mfma_f32_16x16x32_bf16 v[140:143], v[244:247], v[36:39], v[140:143]
	ds_read_b128 v[244:247], v0
	s_waitcnt lgkmcnt(4)
	v_mfma_f32_16x16x32_bf16 v[156:159], v[248:251], v[16:19], v[156:159]
	v_mfma_f32_16x16x32_bf16 v[140:143], v[248:251], v[40:43], v[140:143]
	ds_read_b128 v[248:251], v209 offset:128
	s_waitcnt lgkmcnt(4)
	v_mfma_f32_16x16x32_bf16 v[156:159], v[232:235], v[20:23], v[156:159]
	v_mfma_f32_16x16x32_bf16 v[140:143], v[232:235], v[44:47], v[140:143]
	ds_read_b128 v[232:235], v0 offset:128
	s_waitcnt lgkmcnt(4)
	v_mfma_f32_16x16x32_bf16 v[156:159], v[236:239], v[24:27], v[156:159]
	v_mfma_f32_16x16x32_bf16 v[140:143], v[236:239], v[48:51], v[140:143]
	ds_read_b128 v[236:239], v209 offset:256
	s_waitcnt lgkmcnt(4)
	v_mfma_f32_16x16x32_bf16 v[160:163], v[240:243], v[4:7], v[148:151]
	v_mfma_f32_16x16x32_bf16 v[144:147], v[240:243], v[28:31], v[164:167]
	ds_read_b128 v[240:243], v0 offset:256
	s_waitcnt lgkmcnt(4)
	v_mfma_f32_16x16x32_bf16 v[160:163], v[244:247], v[8:11], v[160:163]
	v_mfma_f32_16x16x32_bf16 v[144:147], v[244:247], v[32:35], v[144:147]
	v_add_u32_e32 v0, s36, v207
	v_add_u32_e32 v209, v0, v199
	v_add_u32_e32 v0, v0, v191
	ds_read_b128 v[244:247], v209
	s_waitcnt lgkmcnt(4)
	v_mfma_f32_16x16x32_bf16 v[160:163], v[248:251], v[12:15], v[160:163]
	v_mfma_f32_16x16x32_bf16 v[144:147], v[248:251], v[36:39], v[144:147]
	ds_read_b128 v[248:251], v0
	s_waitcnt lgkmcnt(4)
	v_mfma_f32_16x16x32_bf16 v[160:163], v[232:235], v[16:19], v[160:163]
	v_mfma_f32_16x16x32_bf16 v[144:147], v[232:235], v[40:43], v[144:147]
	ds_read_b128 v[232:235], v209 offset:128
	s_waitcnt lgkmcnt(4)
	v_mfma_f32_16x16x32_bf16 v[160:163], v[236:239], v[20:23], v[160:163]
	v_mfma_f32_16x16x32_bf16 v[144:147], v[236:239], v[44:47], v[144:147]
	ds_read_b128 v[236:239], v0 offset:128
	s_waitcnt lgkmcnt(4)
	v_mfma_f32_16x16x32_bf16 v[160:163], v[240:243], v[24:27], v[160:163]
	v_mfma_f32_16x16x32_bf16 v[144:147], v[240:243], v[48:51], v[144:147]
	ds_read_b128 v[240:243], v209 offset:256
	s_waitcnt lgkmcnt(4)
	v_mfma_f32_16x16x32_bf16 v[252:255], v[244:247], v[4:7], v[148:151]
	v_mfma_f32_16x16x32_bf16 v[148:151], v[244:247], v[28:31], v[164:167]
	ds_read_b128 v[244:247], v0 offset:256
	s_waitcnt lgkmcnt(4)
	v_mfma_f32_16x16x32_bf16 v[252:255], v[248:251], v[8:11], v[252:255]
	v_mfma_f32_16x16x32_bf16 v[148:151], v[248:251], v[32:35], v[148:151]
	s_waitcnt lgkmcnt(3)
	v_mfma_f32_16x16x32_bf16 v[252:255], v[232:235], v[12:15], v[252:255]
	v_mfma_f32_16x16x32_bf16 v[148:151], v[232:235], v[36:39], v[148:151]
	s_waitcnt lgkmcnt(2)
	v_mfma_f32_16x16x32_bf16 v[252:255], v[236:239], v[16:19], v[252:255]
	v_mfma_f32_16x16x32_bf16 v[148:151], v[236:239], v[40:43], v[148:151]
	s_waitcnt lgkmcnt(1)
	v_mfma_f32_16x16x32_bf16 v[252:255], v[240:243], v[20:23], v[252:255]
	v_mfma_f32_16x16x32_bf16 v[148:151], v[240:243], v[44:47], v[148:151]
	s_waitcnt lgkmcnt(0)
	v_mfma_f32_16x16x32_bf16 v[164:167], v[244:247], v[24:27], v[252:255]
	v_mfma_f32_16x16x32_bf16 v[148:151], v[244:247], v[48:51], v[148:151]
	s_cmp_le_i32 s16, s33
	s_cbranch_scc1 .LBB0_1803
; template <int MODE>
; DI void attn_item(const Params& p, int item, char* smem, u16* gdst) {
;     ...
;       if (MODE == 0) {
;         if (key0 + 64 > nkeys) {
; #pragma unroll
;           for (int kt = 0; kt < 4; ++kt)
; #pragma unroll
;             for (int j = 0; j < 4; ++j)
;               if (key0 + kt * 16 + fq * 4 + j >= nkeys) { s[0][kt][j] = -1e30f; s[1][kt][j] = -1e30f; }
;         }
	v_add_u32_e32 v0, s16, v208
	v_subrev_u32_e32 v209, 64, v0
	v_cmp_gt_i32_e32 vcc, s33, v209
	v_subrev_u32_e32 v209, 63, v0
	v_cmp_gt_i32_e64 s[4:5], s33, v209
	v_subrev_u32_e32 v209, 62, v0
	v_cmp_gt_i32_e64 s[6:7], s33, v209
	v_subrev_u32_e32 v209, 61, v0
	v_cmp_gt_i32_e64 s[8:9], s33, v209
	s_or_b64 s[6:7], s[8:9], s[6:7]
	s_or_b64 s[4:5], s[6:7], s[4:5]
	s_or_b64 vcc, s[4:5], vcc
	v_subrev_u32_e32 v209, 48, v0
	v_cndmask_b32_e32 v136, v183, v136, vcc
	v_cndmask_b32_e32 v152, v183, v152, vcc
	v_cmp_gt_i32_e32 vcc, s33, v209
	v_subrev_u32_e32 v209, 47, v0
	v_cndmask_b32_e64 v137, v183, v137, s[4:5]
	v_cndmask_b32_e64 v153, v183, v153, s[4:5]
	v_cmp_gt_i32_e64 s[4:5], s33, v209
	v_subrev_u32_e32 v209, 46, v0
	v_cndmask_b32_e64 v138, v183, v138, s[6:7]
	v_cndmask_b32_e64 v154, v183, v154, s[6:7]
	v_cmp_gt_i32_e64 s[6:7], s33, v209
	v_subrev_u32_e32 v209, 45, v0
	v_cndmask_b32_e64 v139, v183, v139, s[8:9]
	v_cndmask_b32_e64 v155, v183, v155, s[8:9]
	v_cmp_gt_i32_e64 s[8:9], s33, v209
	s_or_b64 s[6:7], s[8:9], s[6:7]
	s_or_b64 s[4:5], s[6:7], s[4:5]
	s_or_b64 vcc, s[4:5], vcc
	v_subrev_u32_e32 v209, 32, v0
	v_cndmask_b32_e32 v140, v183, v140, vcc
	v_cndmask_b32_e32 v156, v183, v156, vcc
	v_cmp_gt_i32_e32 vcc, s33, v209
	v_subrev_u32_e32 v209, 31, v0
	v_cndmask_b32_e64 v141, v183, v141, s[4:5]
	v_cndmask_b32_e64 v157, v183, v157, s[4:5]
	v_cmp_gt_i32_e64 s[4:5], s33, v209
	v_subrev_u32_e32 v209, 30, v0
	v_cndmask_b32_e64 v142, v183, v142, s[6:7]
	v_cndmask_b32_e64 v158, v183, v158, s[6:7]
	v_cmp_gt_i32_e64 s[6:7], s33, v209
	v_subrev_u32_e32 v209, 29, v0
	v_cndmask_b32_e64 v143, v183, v143, s[8:9]
	v_cndmask_b32_e64 v159, v183, v159, s[8:9]
	v_cmp_gt_i32_e64 s[8:9], s33, v209
	s_or_b64 s[6:7], s[8:9], s[6:7]
	s_or_b64 s[4:5], s[6:7], s[4:5]
	s_or_b64 vcc, s[4:5], vcc
	v_add_u32_e32 v209, -16, v0
	v_cndmask_b32_e32 v144, v183, v144, vcc
	v_cndmask_b32_e32 v160, v183, v160, vcc
	v_cmp_gt_i32_e32 vcc, s33, v209
	v_add_u32_e32 v209, -15, v0
	v_cndmask_b32_e64 v145, v183, v145, s[4:5]
	v_cndmask_b32_e64 v161, v183, v161, s[4:5]
	v_cmp_gt_i32_e64 s[4:5], s33, v209
	v_add_u32_e32 v209, -14, v0
	v_add_u32_e32 v0, -13, v0
	v_cndmask_b32_e64 v147, v183, v147, s[8:9]
	v_cndmask_b32_e64 v146, v183, v146, s[6:7]
	v_cndmask_b32_e64 v162, v183, v162, s[6:7]
	v_cndmask_b32_e64 v163, v183, v163, s[8:9]
	v_cmp_gt_i32_e64 s[6:7], s33, v209
	v_cmp_gt_i32_e64 s[8:9], s33, v0
	s_or_b64 s[6:7], s[8:9], s[6:7]
	s_or_b64 s[4:5], s[6:7], s[4:5]
	s_or_b64 vcc, s[4:5], vcc
	v_cndmask_b32_e64 v151, v183, v151, s[8:9]
	v_cndmask_b32_e64 v150, v183, v150, s[6:7]
	v_cndmask_b32_e64 v149, v183, v149, s[4:5]
	v_cndmask_b32_e32 v148, v183, v148, vcc
	v_cndmask_b32_e64 v166, v183, v166, s[6:7]
	v_cndmask_b32_e64 v165, v183, v165, s[4:5]
	v_cndmask_b32_e32 v164, v183, v164, vcc
	v_cndmask_b32_e64 v167, v183, v167, s[8:9]

; #define G_LOAD(T) { const int k_ = (T) << 6; _Pragma("unroll") for (int i = 0; i < 4; ++i) { \
;     ra[i] = *(const u32x4*)(Ag + (size_t)(i * 64) * lda + k_); rb[i] = *(const u32x4*)(Bg + (size_t)(i * 64) * ldb + k_); } }
; #define L_STORE(ST) { u16* dA_ = sbase + (ST) * GSTAGE + lr * LSTR + lkw; u16* dB_ = dA_ + 256 * LSTR; _Pragma("unroll") for (int i = 0; i < 4; ++i) { \
;     *(u32x4*)(dA_ + i * 64 * LSTR) = ra[i]; *(u32x4*)(dB_ + i * 64 * LSTR) = rb[i]; } }
; template <int EPI>
; DI void gemm_tile(const Params& p, const u16* __restrict__ A, int lda, const u16* __restrict__ Bt, int ldb, int K, int m0, int n0,
;                   char* smem, u16* Cb, int ldc) {
;     ...
;   for (int kt = 0; kt < nk; ++kt) {
;     __syncthreads();
;     if (kt + 1 < nk) L_STORE((kt + 1) & 1)
;     G_LOAD(min(kt + 2, nk - 1))
;     const u16* cA = sbase + (kt & 1) * GSTAGE + (wr * 128 + fr) * LSTR;
;     const u16* cB = sbase + (kt & 1) * GSTAGE + 256 * LSTR + (wc * 64 + fr) * LSTR;
; #pragma unroll
;     for (int ks = 0; ks < 2; ++ks) {
;       bf16x8 bfr[4];
; #pragma unroll
;       for (int n = 0; n < 4; ++n) bfr[n] = *(const bf16x8*)(cB + n * 16 * LSTR + (ks ? fo1 : fo0));
; #pragma unroll
;       for (int mh = 0; mh < 2; ++mh) {
;         bf16x8 af[4];
; #pragma unroll
;         for (int m = 0; m < 4; ++m) af[m] = *(const bf16x8*)(cA + (mh * 4 + m) * 16 * LSTR + (ks ? fo1 : fo0));
;         __builtin_amdgcn_s_setprio(1);
; #pragma unroll
;         for (int m = 0; m < 4; ++m)
; #pragma unroll
;           for (int n = 0; n < 4; ++n)
;             acc[mh * 4 + m][n] = EpiSwap<EPI>::v ? __builtin_amdgcn_mfma_f32_16x16x32_bf16(bfr[n], af[m], acc[mh * 4 + m][n], 0, 0, 0)
;                                                  : __builtin_amdgcn_mfma_f32_16x16x32_bf16(af[m], bfr[n], acc[mh * 4 + m][n], 0, 0, 0);
;         __builtin_amdgcn_s_setprio(0);
;       }
;     }
;   }
.LBB0_1836:
	s_and_b32 s0, s5, 0x8000
	s_lshl_b32 s0, s0, 1
	s_add_i32 s0, s0, 0
	v_add3_u32 v175, s0, v169, v171
	v_add3_u32 v192, s0, v170, v171
	v_add_u32_e32 v188, v192, v172
	v_add_u32_e32 v193, v175, v172
	ds_read_b128 v[176:179], v188 offset:32768
	ds_read_b128 v[180:183], v188 offset:34816
	ds_read_b128 v[184:187], v188 offset:36864
	ds_read_b128 v[188:191], v188 offset:38912
	ds_read_b128 v[196:199], v193
	ds_read_b128 v[200:203], v193 offset:2048
	ds_read_b128 v[204:207], v193 offset:4096
	ds_read_b128 v[208:211], v193 offset:6144
	s_min_i32 s0, s7, 29
	s_lshl_b32 s20, s0, 7
	s_waitcnt vmcnt(0)
	v_lshl_add_u64 v[152:153], v[162:163], 0, s[20:21]
	v_add_co_u32_e32 v136, vcc, s22, v152
	v_lshl_add_u64 v[156:157], v[164:165], 0, s[20:21]
	s_nop 0
	v_addc_co_u32_e32 v137, vcc, 0, v153, vcc
	v_add_co_u32_e32 v140, vcc, s22, v156
	global_load_dwordx4 v[132:135], v[152:153], off offset:256
	global_load_dwordx4 v[128:131], v[156:157], off offset:256
	v_addc_co_u32_e32 v141, vcc, 0, v157, vcc
	v_add_co_u32_e32 v144, vcc, s23, v152
	global_load_dwordx4 v[136:139], v[136:137], off offset:256
	s_nop 0
	v_addc_co_u32_e32 v145, vcc, 0, v153, vcc
	v_add_co_u32_e32 v148, vcc, s23, v156
	global_load_dwordx4 v[140:143], v[140:141], off offset:256
	s_nop 0
	v_addc_co_u32_e32 v149, vcc, 0, v157, vcc
	v_add_co_u32_e32 v152, vcc, s24, v152
	global_load_dwordx4 v[144:147], v[144:145], off offset:256
	s_nop 0
	v_addc_co_u32_e32 v153, vcc, 0, v153, vcc
	v_add_co_u32_e32 v156, vcc, s24, v156
	global_load_dwordx4 v[148:151], v[148:149], off offset:256
	s_nop 0
	v_addc_co_u32_e32 v157, vcc, 0, v157, vcc
	global_load_dwordx4 v[152:155], v[152:153], off offset:256
	s_nop 0
	global_load_dwordx4 v[156:159], v[156:157], off offset:256
	s_add_i32 s7, s7, 1
	s_setprio 1
	s_waitcnt lgkmcnt(3)
	v_mfma_f32_16x16x32_bf16 v[124:127], v[176:179], v[196:199], v[124:127]
	v_mfma_f32_16x16x32_bf16 v[96:99], v[180:183], v[196:199], v[96:99]
	v_mfma_f32_16x16x32_bf16 v[72:75], v[184:187], v[196:199], v[72:75]
	v_mfma_f32_16x16x32_bf16 v[44:47], v[188:191], v[196:199], v[44:47]
	s_waitcnt lgkmcnt(2)
	v_mfma_f32_16x16x32_bf16 v[120:123], v[176:179], v[200:203], v[120:123]
	v_mfma_f32_16x16x32_bf16 v[92:95], v[180:183], v[200:203], v[92:95]
	v_mfma_f32_16x16x32_bf16 v[68:71], v[184:187], v[200:203], v[68:71]
	v_mfma_f32_16x16x32_bf16 v[36:39], v[188:191], v[200:203], v[36:39]
	s_waitcnt lgkmcnt(1)
	v_mfma_f32_16x16x32_bf16 v[116:119], v[176:179], v[204:207], v[116:119]
	v_mfma_f32_16x16x32_bf16 v[84:87], v[180:183], v[204:207], v[84:87]
	v_mfma_f32_16x16x32_bf16 v[60:63], v[184:187], v[204:207], v[60:63]
	v_mfma_f32_16x16x32_bf16 v[28:31], v[188:191], v[204:207], v[28:31]
	s_waitcnt lgkmcnt(0)
	v_mfma_f32_16x16x32_bf16 v[112:115], v[176:179], v[208:211], v[112:115]
	v_mfma_f32_16x16x32_bf16 v[80:83], v[180:183], v[208:211], v[80:83]
	v_mfma_f32_16x16x32_bf16 v[52:55], v[184:187], v[208:211], v[52:55]
	v_mfma_f32_16x16x32_bf16 v[20:23], v[188:191], v[208:211], v[20:23]
	s_setprio 0
	ds_read_b128 v[196:199], v193 offset:8192
	ds_read_b128 v[200:203], v193 offset:10240
	ds_read_b128 v[204:207], v193 offset:12288
	ds_read_b128 v[208:211], v193 offset:14336
	s_setprio 1
	s_waitcnt lgkmcnt(3)
	v_mfma_f32_16x16x32_bf16 v[108:111], v[176:179], v[196:199], v[108:111]
	v_mfma_f32_16x16x32_bf16 v[76:79], v[180:183], v[196:199], v[76:79]
	v_mfma_f32_16x16x32_bf16 v[40:43], v[184:187], v[196:199], v[40:43]
	v_mfma_f32_16x16x32_bf16 v[12:15], v[188:191], v[196:199], v[12:15]
	s_waitcnt lgkmcnt(2)
	v_mfma_f32_16x16x32_bf16 v[104:107], v[176:179], v[200:203], v[104:107]
	v_mfma_f32_16x16x32_bf16 v[64:67], v[180:183], v[200:203], v[64:67]
	v_mfma_f32_16x16x32_bf16 v[32:35], v[184:187], v[200:203], v[32:35]
	v_mfma_f32_16x16x32_bf16 v[8:11], v[188:191], v[200:203], v[8:11]
	s_waitcnt lgkmcnt(1)
; template <int EPI>
; DI void gemm_tile(const Params& p, const u16* __restrict__ A, int lda, const u16* __restrict__ Bt, int ldb, int K, int m0, int n0,
;                   char* smem, u16* Cb, int ldc) {
;     ...
; #pragma unroll
;     for (int ks = 0; ks < 2; ++ks) {
;       bf16x8 bfr[4];
; #pragma unroll
;       for (int n = 0; n < 4; ++n) bfr[n] = *(const bf16x8*)(cB + n * 16 * LSTR + (ks ? fo1 : fo0));
; #pragma unroll
;       for (int mh = 0; mh < 2; ++mh) {
;         bf16x8 af[4];
; #pragma unroll
;         for (int m = 0; m < 4; ++m) af[m] = *(const bf16x8*)(cA + (mh * 4 + m) * 16 * LSTR + (ks ? fo1 : fo0));
;         __builtin_amdgcn_s_setprio(1);
; #pragma unroll
;         for (int m = 0; m < 4; ++m)
; #pragma unroll
;           for (int n = 0; n < 4; ++n)
;             acc[mh * 4 + m][n] = EpiSwap<EPI>::v ? __builtin_amdgcn_mfma_f32_16x16x32_bf16(bfr[n], af[m], acc[mh * 4 + m][n], 0, 0, 0)
;                                                  : __builtin_amdgcn_mfma_f32_16x16x32_bf16(af[m], bfr[n], acc[mh * 4 + m][n], 0, 0, 0);
;         __builtin_amdgcn_s_setprio(0);
;       }
;     }
	v_mfma_f32_16x16x32_bf16 v[100:103], v[176:179], v[204:207], v[100:103]
	v_mfma_f32_16x16x32_bf16 v[56:59], v[180:183], v[204:207], v[56:59]
	v_mfma_f32_16x16x32_bf16 v[24:27], v[184:187], v[204:207], v[24:27]
	v_mfma_f32_16x16x32_bf16 v[4:7], v[188:191], v[204:207], v[4:7]
	s_waitcnt lgkmcnt(0)
	v_mfma_f32_16x16x32_bf16 v[88:91], v[176:179], v[208:211], v[88:91]
	v_mfma_f32_16x16x32_bf16 v[48:51], v[180:183], v[208:211], v[48:51]
	v_mfma_f32_16x16x32_bf16 v[16:19], v[184:187], v[208:211], v[16:19]
	v_mfma_f32_16x16x32_bf16 v[0:3], v[188:191], v[208:211], v[0:3]
	s_setprio 0
	v_add_u32_e32 v188, v192, v174
	v_add_u32_e32 v175, v175, v174
	ds_read_b128 v[176:179], v188 offset:32768
	ds_read_b128 v[180:183], v188 offset:34816
	ds_read_b128 v[184:187], v188 offset:36864
	ds_read_b128 v[188:191], v188 offset:38912
	ds_read_b128 v[196:199], v175
	ds_read_b128 v[200:203], v175 offset:2048
	ds_read_b128 v[204:207], v175 offset:4096
	ds_read_b128 v[208:211], v175 offset:6144
	s_setprio 1
	s_waitcnt lgkmcnt(3)
	v_mfma_f32_16x16x32_bf16 v[124:127], v[176:179], v[196:199], v[124:127]
	v_mfma_f32_16x16x32_bf16 v[96:99], v[180:183], v[196:199], v[96:99]
	v_mfma_f32_16x16x32_bf16 v[72:75], v[184:187], v[196:199], v[72:75]
	v_mfma_f32_16x16x32_bf16 v[44:47], v[188:191], v[196:199], v[44:47]
	s_waitcnt lgkmcnt(2)
	v_mfma_f32_16x16x32_bf16 v[120:123], v[176:179], v[200:203], v[120:123]
	v_mfma_f32_16x16x32_bf16 v[92:95], v[180:183], v[200:203], v[92:95]
	v_mfma_f32_16x16x32_bf16 v[68:71], v[184:187], v[200:203], v[68:71]
	v_mfma_f32_16x16x32_bf16 v[36:39], v[188:191], v[200:203], v[36:39]
	s_waitcnt lgkmcnt(1)
	v_mfma_f32_16x16x32_bf16 v[116:119], v[176:179], v[204:207], v[116:119]
	v_mfma_f32_16x16x32_bf16 v[84:87], v[180:183], v[204:207], v[84:87]
	v_mfma_f32_16x16x32_bf16 v[60:63], v[184:187], v[204:207], v[60:63]
	v_mfma_f32_16x16x32_bf16 v[28:31], v[188:191], v[204:207], v[28:31]
	s_waitcnt lgkmcnt(0)
	v_mfma_f32_16x16x32_bf16 v[112:115], v[176:179], v[208:211], v[112:115]
	v_mfma_f32_16x16x32_bf16 v[80:83], v[180:183], v[208:211], v[80:83]
	v_mfma_f32_16x16x32_bf16 v[52:55], v[184:187], v[208:211], v[52:55]
	v_mfma_f32_16x16x32_bf16 v[20:23], v[188:191], v[208:211], v[20:23]
	s_setprio 0
	ds_read_b128 v[196:199], v175 offset:8192
	ds_read_b128 v[200:203], v175 offset:10240
	ds_read_b128 v[204:207], v175 offset:12288
	ds_read_b128 v[208:211], v175 offset:14336
	s_setprio 1
	s_waitcnt lgkmcnt(3)
	v_mfma_f32_16x16x32_bf16 v[108:111], v[176:179], v[196:199], v[108:111]
	v_mfma_f32_16x16x32_bf16 v[76:79], v[180:183], v[196:199], v[76:79]
	v_mfma_f32_16x16x32_bf16 v[40:43], v[184:187], v[196:199], v[40:43]
	v_mfma_f32_16x16x32_bf16 v[12:15], v[188:191], v[196:199], v[12:15]
	s_waitcnt lgkmcnt(2)
	v_mfma_f32_16x16x32_bf16 v[104:107], v[176:179], v[200:203], v[104:107]
	v_mfma_f32_16x16x32_bf16 v[64:67], v[180:183], v[200:203], v[64:67]
	v_mfma_f32_16x16x32_bf16 v[32:35], v[184:187], v[200:203], v[32:35]
	v_mfma_f32_16x16x32_bf16 v[8:11], v[188:191], v[200:203], v[8:11]
	s_waitcnt lgkmcnt(1)
	v_mfma_f32_16x16x32_bf16 v[100:103], v[176:179], v[204:207], v[100:103]
	v_mfma_f32_16x16x32_bf16 v[56:59], v[180:183], v[204:207], v[56:59]
	v_mfma_f32_16x16x32_bf16 v[24:27], v[184:187], v[204:207], v[24:27]
	v_mfma_f32_16x16x32_bf16 v[4:7], v[188:191], v[204:207], v[4:7]
	s_waitcnt lgkmcnt(0)
	v_mfma_f32_16x16x32_bf16 v[88:91], v[176:179], v[208:211], v[88:91]
	v_mfma_f32_16x16x32_bf16 v[48:51], v[180:183], v[208:211], v[48:51]
	v_mfma_f32_16x16x32_bf16 v[16:19], v[184:187], v[208:211], v[16:19]
	v_mfma_f32_16x16x32_bf16 v[0:3], v[188:191], v[208:211], v[0:3]
	s_setprio 0
	s_cmp_eq_u32 s7, 32
	s_mov_b32 s5, s8
	s_cbranch_scc1 .LBB0_1841

; #define G_LOAD(T) { const int k_ = (T) << 6; _Pragma("unroll") for (int i = 0; i < 4; ++i) { \
;     ra[i] = *(const u32x4*)(Ag + (size_t)(i * 64) * lda + k_); rb[i] = *(const u32x4*)(Bg + (size_t)(i * 64) * ldb + k_); } }
; #define L_STORE(ST) { u16* dA_ = sbase + (ST) * GSTAGE + lr * LSTR + lkw; u16* dB_ = dA_ + 256 * LSTR; _Pragma("unroll") for (int i = 0; i < 4; ++i) { \
;     *(u32x4*)(dA_ + i * 64 * LSTR) = ra[i]; *(u32x4*)(dB_ + i * 64 * LSTR) = rb[i]; } }
; template <int EPI>
; DI void gemm_tile(const Params& p, const u16* __restrict__ A, int lda, const u16* __restrict__ Bt, int ldb, int K, int m0, int n0,
;                   char* smem, u16* Cb, int ldc) {
;     ...
;   for (int kt = 0; kt < nk; ++kt) {
;     __syncthreads();
;     if (kt + 1 < nk) L_STORE((kt + 1) & 1)
;     G_LOAD(min(kt + 2, nk - 1))
;     const u16* cA = sbase + (kt & 1) * GSTAGE + (wr * 128 + fr) * LSTR;
;     const u16* cB = sbase + (kt & 1) * GSTAGE + 256 * LSTR + (wc * 64 + fr) * LSTR;
; #pragma unroll
;     for (int ks = 0; ks < 2; ++ks) {
;       bf16x8 bfr[4];
; #pragma unroll
;       for (int n = 0; n < 4; ++n) bfr[n] = *(const bf16x8*)(cB + n * 16 * LSTR + (ks ? fo1 : fo0));
; #pragma unroll
;       for (int mh = 0; mh < 2; ++mh) {
;         bf16x8 af[4];
; #pragma unroll
;         for (int m = 0; m < 4; ++m) af[m] = *(const bf16x8*)(cA + (mh * 4 + m) * 16 * LSTR + (ks ? fo1 : fo0));
;         __builtin_amdgcn_s_setprio(1);
; #pragma unroll
;         for (int m = 0; m < 4; ++m)
; #pragma unroll
;           for (int n = 0; n < 4; ++n)
;             acc[mh * 4 + m][n] = EpiSwap<EPI>::v ? __builtin_amdgcn_mfma_f32_16x16x32_bf16(bfr[n], af[m], acc[mh * 4 + m][n], 0, 0, 0)
;                                                  : __builtin_amdgcn_mfma_f32_16x16x32_bf16(af[m], bfr[n], acc[mh * 4 + m][n], 0, 0, 0);
;         __builtin_amdgcn_s_setprio(0);
;       }
;     }
;   }
.LBB0_1879:
	s_and_b32 s0, s7, 0x8000
	s_lshl_b32 s0, s0, 1
	s_add_i32 s0, s0, 0
	v_add3_u32 v175, s0, v169, v171
	v_add3_u32 v192, s0, v170, v171
	v_add_u32_e32 v188, v192, v172
	v_add_u32_e32 v193, v175, v172
	ds_read_b128 v[176:179], v188 offset:32768
	ds_read_b128 v[180:183], v188 offset:34816
	ds_read_b128 v[184:187], v188 offset:36864
	ds_read_b128 v[188:191], v188 offset:38912
	ds_read_b128 v[196:199], v193
	ds_read_b128 v[200:203], v193 offset:2048
	ds_read_b128 v[204:207], v193 offset:4096
	ds_read_b128 v[208:211], v193 offset:6144
	s_min_i32 s0, s8, 29
	s_lshl_b32 s22, s0, 7
	s_waitcnt vmcnt(1)
	v_lshl_add_u64 v[152:153], v[162:163], 0, s[22:23]
	v_add_co_u32_e32 v136, vcc, s26, v152
	s_waitcnt vmcnt(0)
	v_lshl_add_u64 v[156:157], v[164:165], 0, s[22:23]
	v_addc_co_u32_e32 v137, vcc, 0, v153, vcc
	v_add_co_u32_e32 v140, vcc, s26, v156
	global_load_dwordx4 v[128:131], v[152:153], off offset:256
	global_load_dwordx4 v[132:135], v[156:157], off offset:256
	v_addc_co_u32_e32 v141, vcc, 0, v157, vcc
	v_add_co_u32_e32 v144, vcc, s27, v152
	global_load_dwordx4 v[136:139], v[136:137], off offset:256
	s_nop 0
	v_addc_co_u32_e32 v145, vcc, 0, v153, vcc
	v_add_co_u32_e32 v148, vcc, s27, v156
	global_load_dwordx4 v[140:143], v[140:141], off offset:256
	s_nop 0
	v_addc_co_u32_e32 v149, vcc, 0, v157, vcc
	v_add_co_u32_e32 v152, vcc, s28, v152
	global_load_dwordx4 v[144:147], v[144:145], off offset:256
	s_nop 0
	v_addc_co_u32_e32 v153, vcc, 0, v153, vcc
	v_add_co_u32_e32 v156, vcc, s28, v156
	global_load_dwordx4 v[148:151], v[148:149], off offset:256
	s_nop 0
	v_addc_co_u32_e32 v157, vcc, 0, v157, vcc
	global_load_dwordx4 v[152:155], v[152:153], off offset:256
	s_nop 0
	global_load_dwordx4 v[156:159], v[156:157], off offset:256
	s_add_i32 s8, s8, 1
	s_setprio 1
	s_waitcnt lgkmcnt(3)
	v_mfma_f32_16x16x32_bf16 v[124:127], v[176:179], v[196:199], v[124:127]
	v_mfma_f32_16x16x32_bf16 v[96:99], v[180:183], v[196:199], v[96:99]
	v_mfma_f32_16x16x32_bf16 v[72:75], v[184:187], v[196:199], v[72:75]
	v_mfma_f32_16x16x32_bf16 v[44:47], v[188:191], v[196:199], v[44:47]
	s_waitcnt lgkmcnt(2)
	v_mfma_f32_16x16x32_bf16 v[120:123], v[176:179], v[200:203], v[120:123]
	v_mfma_f32_16x16x32_bf16 v[92:95], v[180:183], v[200:203], v[92:95]
	v_mfma_f32_16x16x32_bf16 v[68:71], v[184:187], v[200:203], v[68:71]
	v_mfma_f32_16x16x32_bf16 v[36:39], v[188:191], v[200:203], v[36:39]
	s_waitcnt lgkmcnt(1)
	v_mfma_f32_16x16x32_bf16 v[116:119], v[176:179], v[204:207], v[116:119]
	v_mfma_f32_16x16x32_bf16 v[84:87], v[180:183], v[204:207], v[84:87]
	v_mfma_f32_16x16x32_bf16 v[60:63], v[184:187], v[204:207], v[60:63]
	v_mfma_f32_16x16x32_bf16 v[28:31], v[188:191], v[204:207], v[28:31]
	s_waitcnt lgkmcnt(0)
	v_mfma_f32_16x16x32_bf16 v[112:115], v[176:179], v[208:211], v[112:115]
	v_mfma_f32_16x16x32_bf16 v[80:83], v[180:183], v[208:211], v[80:83]
	v_mfma_f32_16x16x32_bf16 v[52:55], v[184:187], v[208:211], v[52:55]
	v_mfma_f32_16x16x32_bf16 v[20:23], v[188:191], v[208:211], v[20:23]
	s_setprio 0
	ds_read_b128 v[196:199], v193 offset:8192
	ds_read_b128 v[200:203], v193 offset:10240
	ds_read_b128 v[204:207], v193 offset:12288
	ds_read_b128 v[208:211], v193 offset:14336
	s_setprio 1
	s_waitcnt lgkmcnt(3)
	v_mfma_f32_16x16x32_bf16 v[108:111], v[176:179], v[196:199], v[108:111]
	v_mfma_f32_16x16x32_bf16 v[76:79], v[180:183], v[196:199], v[76:79]
	v_mfma_f32_16x16x32_bf16 v[40:43], v[184:187], v[196:199], v[40:43]
	v_mfma_f32_16x16x32_bf16 v[12:15], v[188:191], v[196:199], v[12:15]
	s_waitcnt lgkmcnt(2)
	v_mfma_f32_16x16x32_bf16 v[104:107], v[176:179], v[200:203], v[104:107]
	v_mfma_f32_16x16x32_bf16 v[64:67], v[180:183], v[200:203], v[64:67]
	v_mfma_f32_16x16x32_bf16 v[32:35], v[184:187], v[200:203], v[32:35]
	v_mfma_f32_16x16x32_bf16 v[8:11], v[188:191], v[200:203], v[8:11]
	s_waitcnt lgkmcnt(1)
; template <int EPI>
; DI void gemm_tile(const Params& p, const u16* __restrict__ A, int lda, const u16* __restrict__ Bt, int ldb, int K, int m0, int n0,
;                   char* smem, u16* Cb, int ldc) {
;     ...
; #pragma unroll
;     for (int ks = 0; ks < 2; ++ks) {
;       bf16x8 bfr[4];
; #pragma unroll
;       for (int n = 0; n < 4; ++n) bfr[n] = *(const bf16x8*)(cB + n * 16 * LSTR + (ks ? fo1 : fo0));
; #pragma unroll
;       for (int mh = 0; mh < 2; ++mh) {
;         bf16x8 af[4];
; #pragma unroll
;         for (int m = 0; m < 4; ++m) af[m] = *(const bf16x8*)(cA + (mh * 4 + m) * 16 * LSTR + (ks ? fo1 : fo0));
;         __builtin_amdgcn_s_setprio(1);
; #pragma unroll
;         for (int m = 0; m < 4; ++m)
; #pragma unroll
;           for (int n = 0; n < 4; ++n)
;             acc[mh * 4 + m][n] = EpiSwap<EPI>::v ? __builtin_amdgcn_mfma_f32_16x16x32_bf16(bfr[n], af[m], acc[mh * 4 + m][n], 0, 0, 0)
;                                                  : __builtin_amdgcn_mfma_f32_16x16x32_bf16(af[m], bfr[n], acc[mh * 4 + m][n], 0, 0, 0);
;         __builtin_amdgcn_s_setprio(0);
;       }
;     }
	v_mfma_f32_16x16x32_bf16 v[100:103], v[176:179], v[204:207], v[100:103]
	v_mfma_f32_16x16x32_bf16 v[56:59], v[180:183], v[204:207], v[56:59]
	v_mfma_f32_16x16x32_bf16 v[24:27], v[184:187], v[204:207], v[24:27]
	v_mfma_f32_16x16x32_bf16 v[4:7], v[188:191], v[204:207], v[4:7]
	s_waitcnt lgkmcnt(0)
	v_mfma_f32_16x16x32_bf16 v[88:91], v[176:179], v[208:211], v[88:91]
	v_mfma_f32_16x16x32_bf16 v[48:51], v[180:183], v[208:211], v[48:51]
	v_mfma_f32_16x16x32_bf16 v[16:19], v[184:187], v[208:211], v[16:19]
	v_mfma_f32_16x16x32_bf16 v[0:3], v[188:191], v[208:211], v[0:3]
	s_setprio 0
	v_add_u32_e32 v188, v192, v173
	v_add_u32_e32 v175, v175, v173
	ds_read_b128 v[176:179], v188 offset:32768
	ds_read_b128 v[180:183], v188 offset:34816
	ds_read_b128 v[184:187], v188 offset:36864
	ds_read_b128 v[188:191], v188 offset:38912
	ds_read_b128 v[196:199], v175
	ds_read_b128 v[200:203], v175 offset:2048
	ds_read_b128 v[204:207], v175 offset:4096
	ds_read_b128 v[208:211], v175 offset:6144
	s_setprio 1
	s_waitcnt lgkmcnt(3)
	v_mfma_f32_16x16x32_bf16 v[124:127], v[176:179], v[196:199], v[124:127]
	v_mfma_f32_16x16x32_bf16 v[96:99], v[180:183], v[196:199], v[96:99]
	v_mfma_f32_16x16x32_bf16 v[72:75], v[184:187], v[196:199], v[72:75]
	v_mfma_f32_16x16x32_bf16 v[44:47], v[188:191], v[196:199], v[44:47]
	s_waitcnt lgkmcnt(2)
	v_mfma_f32_16x16x32_bf16 v[120:123], v[176:179], v[200:203], v[120:123]
	v_mfma_f32_16x16x32_bf16 v[92:95], v[180:183], v[200:203], v[92:95]
	v_mfma_f32_16x16x32_bf16 v[68:71], v[184:187], v[200:203], v[68:71]
	v_mfma_f32_16x16x32_bf16 v[36:39], v[188:191], v[200:203], v[36:39]
	s_waitcnt lgkmcnt(1)
	v_mfma_f32_16x16x32_bf16 v[116:119], v[176:179], v[204:207], v[116:119]
	v_mfma_f32_16x16x32_bf16 v[84:87], v[180:183], v[204:207], v[84:87]
	v_mfma_f32_16x16x32_bf16 v[60:63], v[184:187], v[204:207], v[60:63]
	v_mfma_f32_16x16x32_bf16 v[28:31], v[188:191], v[204:207], v[28:31]
	s_waitcnt lgkmcnt(0)
	v_mfma_f32_16x16x32_bf16 v[112:115], v[176:179], v[208:211], v[112:115]
	v_mfma_f32_16x16x32_bf16 v[80:83], v[180:183], v[208:211], v[80:83]
	v_mfma_f32_16x16x32_bf16 v[52:55], v[184:187], v[208:211], v[52:55]
	v_mfma_f32_16x16x32_bf16 v[20:23], v[188:191], v[208:211], v[20:23]
	s_setprio 0
	ds_read_b128 v[196:199], v175 offset:8192
	ds_read_b128 v[200:203], v175 offset:10240
	ds_read_b128 v[204:207], v175 offset:12288
	ds_read_b128 v[208:211], v175 offset:14336
	s_setprio 1
	s_waitcnt lgkmcnt(3)
	v_mfma_f32_16x16x32_bf16 v[108:111], v[176:179], v[196:199], v[108:111]
	v_mfma_f32_16x16x32_bf16 v[76:79], v[180:183], v[196:199], v[76:79]
	v_mfma_f32_16x16x32_bf16 v[40:43], v[184:187], v[196:199], v[40:43]
	v_mfma_f32_16x16x32_bf16 v[12:15], v[188:191], v[196:199], v[12:15]
	s_waitcnt lgkmcnt(2)
	v_mfma_f32_16x16x32_bf16 v[104:107], v[176:179], v[200:203], v[104:107]
	v_mfma_f32_16x16x32_bf16 v[64:67], v[180:183], v[200:203], v[64:67]
	v_mfma_f32_16x16x32_bf16 v[32:35], v[184:187], v[200:203], v[32:35]
	v_mfma_f32_16x16x32_bf16 v[8:11], v[188:191], v[200:203], v[8:11]
	s_waitcnt lgkmcnt(1)
	v_mfma_f32_16x16x32_bf16 v[100:103], v[176:179], v[204:207], v[100:103]
	v_mfma_f32_16x16x32_bf16 v[56:59], v[180:183], v[204:207], v[56:59]
	v_mfma_f32_16x16x32_bf16 v[24:27], v[184:187], v[204:207], v[24:27]
	v_mfma_f32_16x16x32_bf16 v[4:7], v[188:191], v[204:207], v[4:7]
	s_waitcnt lgkmcnt(0)
	v_mfma_f32_16x16x32_bf16 v[88:91], v[176:179], v[208:211], v[88:91]
	v_mfma_f32_16x16x32_bf16 v[48:51], v[180:183], v[208:211], v[48:51]
	v_mfma_f32_16x16x32_bf16 v[16:19], v[184:187], v[208:211], v[16:19]
	v_mfma_f32_16x16x32_bf16 v[0:3], v[188:191], v[208:211], v[0:3]
	s_setprio 0
	s_cmp_eq_u32 s8, 32
	s_mov_b32 s7, s9
	s_cbranch_scc1 .LBB0_1884

; #define G_LOAD(T) { const int k_ = (T) << 6; _Pragma("unroll") for (int i = 0; i < 4; ++i) { \
;     ra[i] = *(const u32x4*)(Ag + (size_t)(i * 64) * lda + k_); rb[i] = *(const u32x4*)(Bg + (size_t)(i * 64) * ldb + k_); } }
; #define L_STORE(ST) { u16* dA_ = sbase + (ST) * GSTAGE + lr * LSTR + lkw; u16* dB_ = dA_ + 256 * LSTR; _Pragma("unroll") for (int i = 0; i < 4; ++i) { \
;     *(u32x4*)(dA_ + i * 64 * LSTR) = ra[i]; *(u32x4*)(dB_ + i * 64 * LSTR) = rb[i]; } }
; template <int EPI>
; DI void gemm_tile(const Params& p, const u16* __restrict__ A, int lda, const u16* __restrict__ Bt, int ldb, int K, int m0, int n0,
;                   char* smem, u16* Cb, int ldc) {
;     ...
;   for (int kt = 0; kt < nk; ++kt) {
;     __syncthreads();
;     if (kt + 1 < nk) L_STORE((kt + 1) & 1)
;     G_LOAD(min(kt + 2, nk - 1))
;     const u16* cA = sbase + (kt & 1) * GSTAGE + (wr * 128 + fr) * LSTR;
;     const u16* cB = sbase + (kt & 1) * GSTAGE + 256 * LSTR + (wc * 64 + fr) * LSTR;
; #pragma unroll
;     for (int ks = 0; ks < 2; ++ks) {
;       bf16x8 bfr[4];
; #pragma unroll
;       for (int n = 0; n < 4; ++n) bfr[n] = *(const bf16x8*)(cB + n * 16 * LSTR + (ks ? fo1 : fo0));
; #pragma unroll
;       for (int mh = 0; mh < 2; ++mh) {
;         bf16x8 af[4];
; #pragma unroll
;         for (int m = 0; m < 4; ++m) af[m] = *(const bf16x8*)(cA + (mh * 4 + m) * 16 * LSTR + (ks ? fo1 : fo0));
;         __builtin_amdgcn_s_setprio(1);
; #pragma unroll
;         for (int m = 0; m < 4; ++m)
; #pragma unroll
;           for (int n = 0; n < 4; ++n)
;             acc[mh * 4 + m][n] = EpiSwap<EPI>::v ? __builtin_amdgcn_mfma_f32_16x16x32_bf16(bfr[n], af[m], acc[mh * 4 + m][n], 0, 0, 0)
;                                                  : __builtin_amdgcn_mfma_f32_16x16x32_bf16(af[m], bfr[n], acc[mh * 4 + m][n], 0, 0, 0);
;         __builtin_amdgcn_s_setprio(0);
;       }
;     }
;   }
.LBB0_1953:
	s_and_b32 s0, s12, 0x8000
	s_lshl_b32 s0, s0, 1
	s_add_i32 s0, s0, 0
	v_add3_u32 v175, s0, v169, v171
	v_add3_u32 v192, s0, v170, v171
	v_add_u32_e32 v188, v192, v172
	v_add_u32_e32 v193, v175, v172
	ds_read_b128 v[176:179], v188 offset:32768
	ds_read_b128 v[180:183], v188 offset:34816
	ds_read_b128 v[184:187], v188 offset:36864
	ds_read_b128 v[188:191], v188 offset:38912
	ds_read_b128 v[196:199], v193
	ds_read_b128 v[200:203], v193 offset:2048
	ds_read_b128 v[204:207], v193 offset:4096
	ds_read_b128 v[208:211], v193 offset:6144
	s_min_i32 s0, s13, 29
	s_lshl_b32 s4, s0, 7
	s_waitcnt vmcnt(0)
	v_lshl_add_u64 v[148:149], v[162:163], 0, s[4:5]
	v_add_co_u32_e32 v132, vcc, s6, v148
	v_lshl_add_u64 v[152:153], v[164:165], 0, s[4:5]
	s_nop 0
	v_addc_co_u32_e32 v133, vcc, 0, v149, vcc
	v_add_co_u32_e32 v136, vcc, s6, v152
	global_load_dwordx4 v[128:131], v[148:149], off offset:256
	global_load_dwordx4 v[124:127], v[152:153], off offset:256
	v_addc_co_u32_e32 v137, vcc, 0, v153, vcc
	v_add_co_u32_e32 v140, vcc, s7, v148
	global_load_dwordx4 v[132:135], v[132:133], off offset:256
	s_nop 0
	v_addc_co_u32_e32 v141, vcc, 0, v149, vcc
	v_add_co_u32_e32 v144, vcc, s7, v152
	global_load_dwordx4 v[136:139], v[136:137], off offset:256
	s_nop 0
	v_addc_co_u32_e32 v145, vcc, 0, v153, vcc
	v_add_co_u32_e32 v148, vcc, s8, v148
	global_load_dwordx4 v[140:143], v[140:141], off offset:256
	s_nop 0
	v_addc_co_u32_e32 v149, vcc, 0, v149, vcc
	v_add_co_u32_e32 v152, vcc, s8, v152
	global_load_dwordx4 v[144:147], v[144:145], off offset:256
	s_nop 0
	v_addc_co_u32_e32 v153, vcc, 0, v153, vcc
	global_load_dwordx4 v[148:151], v[148:149], off offset:256
	s_nop 0
	global_load_dwordx4 v[152:155], v[152:153], off offset:256
	s_add_i32 s13, s13, 1
	s_setprio 1
	s_waitcnt lgkmcnt(3)
	v_mfma_f32_16x16x32_bf16 v[156:159], v[176:179], v[196:199], v[156:159]
	v_mfma_f32_16x16x32_bf16 v[104:107], v[180:183], v[196:199], v[104:107]
	v_mfma_f32_16x16x32_bf16 v[76:79], v[184:187], v[196:199], v[76:79]
	v_mfma_f32_16x16x32_bf16 v[44:47], v[188:191], v[196:199], v[44:47]
	s_waitcnt lgkmcnt(2)
	v_mfma_f32_16x16x32_bf16 v[120:123], v[176:179], v[200:203], v[120:123]
	v_mfma_f32_16x16x32_bf16 v[96:99], v[180:183], v[200:203], v[96:99]
	v_mfma_f32_16x16x32_bf16 v[68:71], v[184:187], v[200:203], v[68:71]
	v_mfma_f32_16x16x32_bf16 v[36:39], v[188:191], v[200:203], v[36:39]
	s_waitcnt lgkmcnt(1)
	v_mfma_f32_16x16x32_bf16 v[116:119], v[176:179], v[204:207], v[116:119]
	v_mfma_f32_16x16x32_bf16 v[88:91], v[180:183], v[204:207], v[88:91]
	v_mfma_f32_16x16x32_bf16 v[60:63], v[184:187], v[204:207], v[60:63]
	v_mfma_f32_16x16x32_bf16 v[28:31], v[188:191], v[204:207], v[28:31]
	s_waitcnt lgkmcnt(0)
	v_mfma_f32_16x16x32_bf16 v[112:115], v[176:179], v[208:211], v[112:115]
	v_mfma_f32_16x16x32_bf16 v[80:83], v[180:183], v[208:211], v[80:83]
	v_mfma_f32_16x16x32_bf16 v[52:55], v[184:187], v[208:211], v[52:55]
	v_mfma_f32_16x16x32_bf16 v[20:23], v[188:191], v[208:211], v[20:23]
	s_setprio 0
	ds_read_b128 v[196:199], v193 offset:8192
	ds_read_b128 v[200:203], v193 offset:10240
	ds_read_b128 v[204:207], v193 offset:12288
	ds_read_b128 v[208:211], v193 offset:14336
	s_setprio 1
	s_waitcnt lgkmcnt(3)
	v_mfma_f32_16x16x32_bf16 v[108:111], v[176:179], v[196:199], v[108:111]
	v_mfma_f32_16x16x32_bf16 v[72:75], v[180:183], v[196:199], v[72:75]
	v_mfma_f32_16x16x32_bf16 v[40:43], v[184:187], v[196:199], v[40:43]
	v_mfma_f32_16x16x32_bf16 v[12:15], v[188:191], v[196:199], v[12:15]
	s_waitcnt lgkmcnt(2)
	v_mfma_f32_16x16x32_bf16 v[100:103], v[176:179], v[200:203], v[100:103]
	v_mfma_f32_16x16x32_bf16 v[64:67], v[180:183], v[200:203], v[64:67]
	v_mfma_f32_16x16x32_bf16 v[32:35], v[184:187], v[200:203], v[32:35]
	v_mfma_f32_16x16x32_bf16 v[8:11], v[188:191], v[200:203], v[8:11]
	s_waitcnt lgkmcnt(1)
; template <int EPI>
; DI void gemm_tile(const Params& p, const u16* __restrict__ A, int lda, const u16* __restrict__ Bt, int ldb, int K, int m0, int n0,
;                   char* smem, u16* Cb, int ldc) {
;     ...
; #pragma unroll
;     for (int ks = 0; ks < 2; ++ks) {
;       bf16x8 bfr[4];
; #pragma unroll
;       for (int n = 0; n < 4; ++n) bfr[n] = *(const bf16x8*)(cB + n * 16 * LSTR + (ks ? fo1 : fo0));
; #pragma unroll
;       for (int mh = 0; mh < 2; ++mh) {
;         bf16x8 af[4];
; #pragma unroll
;         for (int m = 0; m < 4; ++m) af[m] = *(const bf16x8*)(cA + (mh * 4 + m) * 16 * LSTR + (ks ? fo1 : fo0));
;         __builtin_amdgcn_s_setprio(1);
; #pragma unroll
;         for (int m = 0; m < 4; ++m)
; #pragma unroll
;           for (int n = 0; n < 4; ++n)
;             acc[mh * 4 + m][n] = EpiSwap<EPI>::v ? __builtin_amdgcn_mfma_f32_16x16x32_bf16(bfr[n], af[m], acc[mh * 4 + m][n], 0, 0, 0)
;                                                  : __builtin_amdgcn_mfma_f32_16x16x32_bf16(af[m], bfr[n], acc[mh * 4 + m][n], 0, 0, 0);
;         __builtin_amdgcn_s_setprio(0);
;       }
;     }
	v_mfma_f32_16x16x32_bf16 v[92:95], v[176:179], v[204:207], v[92:95]
	v_mfma_f32_16x16x32_bf16 v[56:59], v[180:183], v[204:207], v[56:59]
	v_mfma_f32_16x16x32_bf16 v[24:27], v[184:187], v[204:207], v[24:27]
	v_mfma_f32_16x16x32_bf16 v[4:7], v[188:191], v[204:207], v[4:7]
	s_waitcnt lgkmcnt(0)
	v_mfma_f32_16x16x32_bf16 v[84:87], v[176:179], v[208:211], v[84:87]
	v_mfma_f32_16x16x32_bf16 v[48:51], v[180:183], v[208:211], v[48:51]
	v_mfma_f32_16x16x32_bf16 v[16:19], v[184:187], v[208:211], v[16:19]
	v_mfma_f32_16x16x32_bf16 v[0:3], v[188:191], v[208:211], v[0:3]
	s_setprio 0
	v_add_u32_e32 v188, v192, v173
	v_add_u32_e32 v175, v175, v173
	ds_read_b128 v[176:179], v188 offset:32768
	ds_read_b128 v[180:183], v188 offset:34816
	ds_read_b128 v[184:187], v188 offset:36864
	ds_read_b128 v[188:191], v188 offset:38912
	ds_read_b128 v[196:199], v175
	ds_read_b128 v[200:203], v175 offset:2048
	ds_read_b128 v[204:207], v175 offset:4096
	ds_read_b128 v[208:211], v175 offset:6144
	s_setprio 1
	s_waitcnt lgkmcnt(3)
	v_mfma_f32_16x16x32_bf16 v[156:159], v[176:179], v[196:199], v[156:159]
	v_mfma_f32_16x16x32_bf16 v[104:107], v[180:183], v[196:199], v[104:107]
	v_mfma_f32_16x16x32_bf16 v[76:79], v[184:187], v[196:199], v[76:79]
	v_mfma_f32_16x16x32_bf16 v[44:47], v[188:191], v[196:199], v[44:47]
	s_waitcnt lgkmcnt(2)
	v_mfma_f32_16x16x32_bf16 v[120:123], v[176:179], v[200:203], v[120:123]
	v_mfma_f32_16x16x32_bf16 v[96:99], v[180:183], v[200:203], v[96:99]
	v_mfma_f32_16x16x32_bf16 v[68:71], v[184:187], v[200:203], v[68:71]
	v_mfma_f32_16x16x32_bf16 v[36:39], v[188:191], v[200:203], v[36:39]
	s_waitcnt lgkmcnt(1)
	v_mfma_f32_16x16x32_bf16 v[116:119], v[176:179], v[204:207], v[116:119]
	v_mfma_f32_16x16x32_bf16 v[88:91], v[180:183], v[204:207], v[88:91]
	v_mfma_f32_16x16x32_bf16 v[60:63], v[184:187], v[204:207], v[60:63]
	v_mfma_f32_16x16x32_bf16 v[28:31], v[188:191], v[204:207], v[28:31]
	s_waitcnt lgkmcnt(0)
	v_mfma_f32_16x16x32_bf16 v[112:115], v[176:179], v[208:211], v[112:115]
	v_mfma_f32_16x16x32_bf16 v[80:83], v[180:183], v[208:211], v[80:83]
	v_mfma_f32_16x16x32_bf16 v[52:55], v[184:187], v[208:211], v[52:55]
	v_mfma_f32_16x16x32_bf16 v[20:23], v[188:191], v[208:211], v[20:23]
	s_setprio 0
	ds_read_b128 v[196:199], v175 offset:8192
	ds_read_b128 v[200:203], v175 offset:10240
	ds_read_b128 v[204:207], v175 offset:12288
	ds_read_b128 v[208:211], v175 offset:14336
	s_setprio 1
	s_waitcnt lgkmcnt(3)
	v_mfma_f32_16x16x32_bf16 v[108:111], v[176:179], v[196:199], v[108:111]
	v_mfma_f32_16x16x32_bf16 v[72:75], v[180:183], v[196:199], v[72:75]
	v_mfma_f32_16x16x32_bf16 v[40:43], v[184:187], v[196:199], v[40:43]
	v_mfma_f32_16x16x32_bf16 v[12:15], v[188:191], v[196:199], v[12:15]
	s_waitcnt lgkmcnt(2)
	v_mfma_f32_16x16x32_bf16 v[100:103], v[176:179], v[200:203], v[100:103]
	v_mfma_f32_16x16x32_bf16 v[64:67], v[180:183], v[200:203], v[64:67]
	v_mfma_f32_16x16x32_bf16 v[32:35], v[184:187], v[200:203], v[32:35]
	v_mfma_f32_16x16x32_bf16 v[8:11], v[188:191], v[200:203], v[8:11]
	s_waitcnt lgkmcnt(1)
	v_mfma_f32_16x16x32_bf16 v[92:95], v[176:179], v[204:207], v[92:95]
	v_mfma_f32_16x16x32_bf16 v[56:59], v[180:183], v[204:207], v[56:59]
	v_mfma_f32_16x16x32_bf16 v[24:27], v[184:187], v[204:207], v[24:27]
	v_mfma_f32_16x16x32_bf16 v[4:7], v[188:191], v[204:207], v[4:7]
	s_waitcnt lgkmcnt(0)
	v_mfma_f32_16x16x32_bf16 v[84:87], v[176:179], v[208:211], v[84:87]
	v_mfma_f32_16x16x32_bf16 v[48:51], v[180:183], v[208:211], v[48:51]
	v_mfma_f32_16x16x32_bf16 v[16:19], v[184:187], v[208:211], v[16:19]
	v_mfma_f32_16x16x32_bf16 v[0:3], v[188:191], v[208:211], v[0:3]
	s_setprio 0
	s_cmp_lg_u32 s13, 32
	s_mov_b32 s12, s14
	s_cbranch_scc0 .LBB0_1951

; #define G_LOAD(T) { const int k_ = (T) << 6; _Pragma("unroll") for (int i = 0; i < 4; ++i) { \
;     ra[i] = *(const u32x4*)(Ag + (size_t)(i * 64) * lda + k_); rb[i] = *(const u32x4*)(Bg + (size_t)(i * 64) * ldb + k_); } }
; #define L_STORE(ST) { u16* dA_ = sbase + (ST) * GSTAGE + lr * LSTR + lkw; u16* dB_ = dA_ + 256 * LSTR; _Pragma("unroll") for (int i = 0; i < 4; ++i) { \
;     *(u32x4*)(dA_ + i * 64 * LSTR) = ra[i]; *(u32x4*)(dB_ + i * 64 * LSTR) = rb[i]; } }
; template <int EPI>
; DI void gemm_tile(const Params& p, const u16* __restrict__ A, int lda, const u16* __restrict__ Bt, int ldb, int K, int m0, int n0,
;                   char* smem, u16* Cb, int ldc) {
;     ...
;   for (int kt = 0; kt < nk; ++kt) {
;     __syncthreads();
;     if (kt + 1 < nk) L_STORE((kt + 1) & 1)
;     G_LOAD(min(kt + 2, nk - 1))
;     const u16* cA = sbase + (kt & 1) * GSTAGE + (wr * 128 + fr) * LSTR;
;     const u16* cB = sbase + (kt & 1) * GSTAGE + 256 * LSTR + (wc * 64 + fr) * LSTR;
; #pragma unroll
;     for (int ks = 0; ks < 2; ++ks) {
;       bf16x8 bfr[4];
; #pragma unroll
;       for (int n = 0; n < 4; ++n) bfr[n] = *(const bf16x8*)(cB + n * 16 * LSTR + (ks ? fo1 : fo0));
; #pragma unroll
;       for (int mh = 0; mh < 2; ++mh) {
;         bf16x8 af[4];
; #pragma unroll
;         for (int m = 0; m < 4; ++m) af[m] = *(const bf16x8*)(cA + (mh * 4 + m) * 16 * LSTR + (ks ? fo1 : fo0));
;         __builtin_amdgcn_s_setprio(1);
; #pragma unroll
;         for (int m = 0; m < 4; ++m)
; #pragma unroll
;           for (int n = 0; n < 4; ++n)
;             acc[mh * 4 + m][n] = EpiSwap<EPI>::v ? __builtin_amdgcn_mfma_f32_16x16x32_bf16(bfr[n], af[m], acc[mh * 4 + m][n], 0, 0, 0)
;                                                  : __builtin_amdgcn_mfma_f32_16x16x32_bf16(af[m], bfr[n], acc[mh * 4 + m][n], 0, 0, 0);
;         __builtin_amdgcn_s_setprio(0);
;       }
;     }
;   }
.LBB0_1965:
	s_and_b32 s0, s12, 0x8000
	s_lshl_b32 s0, s0, 1
	s_add_i32 s0, s0, 0
	v_add3_u32 v175, s0, v169, v171
	v_add3_u32 v192, s0, v170, v171
	v_add_u32_e32 v188, v192, v172
	v_add_u32_e32 v193, v175, v172
	ds_read_b128 v[176:179], v188 offset:32768
	ds_read_b128 v[180:183], v188 offset:34816
	ds_read_b128 v[184:187], v188 offset:36864
	ds_read_b128 v[188:191], v188 offset:38912
	ds_read_b128 v[196:199], v193
	ds_read_b128 v[200:203], v193 offset:2048
	ds_read_b128 v[204:207], v193 offset:4096
	ds_read_b128 v[208:211], v193 offset:6144
	s_min_i32 s0, s13, 29
	s_lshl_b32 s4, s0, 7
	s_waitcnt vmcnt(1)
	v_lshl_add_u64 v[152:153], v[162:163], 0, s[4:5]
	v_add_co_u32_e32 v132, vcc, s6, v152
	s_waitcnt vmcnt(0)
	v_lshl_add_u64 v[156:157], v[164:165], 0, s[4:5]
	v_addc_co_u32_e32 v133, vcc, 0, v153, vcc
	v_add_co_u32_e32 v136, vcc, s6, v156
	global_load_dwordx4 v[124:127], v[152:153], off offset:256
	global_load_dwordx4 v[128:131], v[156:157], off offset:256
	v_addc_co_u32_e32 v137, vcc, 0, v157, vcc
	v_add_co_u32_e32 v140, vcc, s7, v152
	global_load_dwordx4 v[132:135], v[132:133], off offset:256
	s_nop 0
	v_addc_co_u32_e32 v141, vcc, 0, v153, vcc
	v_add_co_u32_e32 v148, vcc, s7, v156
	global_load_dwordx4 v[136:139], v[136:137], off offset:256
	s_nop 0
	v_addc_co_u32_e32 v149, vcc, 0, v157, vcc
	v_add_co_u32_e32 v152, vcc, s8, v152
	global_load_dwordx4 v[140:143], v[140:141], off offset:256
	s_nop 0
	v_addc_co_u32_e32 v153, vcc, 0, v153, vcc
	v_add_co_u32_e32 v156, vcc, s8, v156
	global_load_dwordx4 v[148:151], v[148:149], off offset:256
	s_nop 0
	v_addc_co_u32_e32 v157, vcc, 0, v157, vcc
	global_load_dwordx4 v[152:155], v[152:153], off offset:256
	s_nop 0
	global_load_dwordx4 v[156:159], v[156:157], off offset:256
	s_add_i32 s13, s13, 1
	s_setprio 1
	s_waitcnt lgkmcnt(3)
	v_mfma_f32_16x16x32_bf16 v[144:147], v[176:179], v[196:199], v[144:147]
	v_mfma_f32_16x16x32_bf16 v[104:107], v[180:183], v[196:199], v[104:107]
	v_mfma_f32_16x16x32_bf16 v[76:79], v[184:187], v[196:199], v[76:79]
	v_mfma_f32_16x16x32_bf16 v[44:47], v[188:191], v[196:199], v[44:47]
	s_waitcnt lgkmcnt(2)
	v_mfma_f32_16x16x32_bf16 v[120:123], v[176:179], v[200:203], v[120:123]
	v_mfma_f32_16x16x32_bf16 v[96:99], v[180:183], v[200:203], v[96:99]
	v_mfma_f32_16x16x32_bf16 v[68:71], v[184:187], v[200:203], v[68:71]
	v_mfma_f32_16x16x32_bf16 v[36:39], v[188:191], v[200:203], v[36:39]
	s_waitcnt lgkmcnt(1)
	v_mfma_f32_16x16x32_bf16 v[116:119], v[176:179], v[204:207], v[116:119]
	v_mfma_f32_16x16x32_bf16 v[88:91], v[180:183], v[204:207], v[88:91]
	v_mfma_f32_16x16x32_bf16 v[60:63], v[184:187], v[204:207], v[60:63]
	v_mfma_f32_16x16x32_bf16 v[28:31], v[188:191], v[204:207], v[28:31]
	s_waitcnt lgkmcnt(0)
	v_mfma_f32_16x16x32_bf16 v[112:115], v[176:179], v[208:211], v[112:115]
	v_mfma_f32_16x16x32_bf16 v[80:83], v[180:183], v[208:211], v[80:83]
	v_mfma_f32_16x16x32_bf16 v[52:55], v[184:187], v[208:211], v[52:55]
	v_mfma_f32_16x16x32_bf16 v[20:23], v[188:191], v[208:211], v[20:23]
	s_setprio 0
	ds_read_b128 v[196:199], v193 offset:8192
	ds_read_b128 v[200:203], v193 offset:10240
	ds_read_b128 v[204:207], v193 offset:12288
	ds_read_b128 v[208:211], v193 offset:14336
	s_setprio 1
	s_waitcnt lgkmcnt(3)
	v_mfma_f32_16x16x32_bf16 v[108:111], v[176:179], v[196:199], v[108:111]
	v_mfma_f32_16x16x32_bf16 v[72:75], v[180:183], v[196:199], v[72:75]
	v_mfma_f32_16x16x32_bf16 v[40:43], v[184:187], v[196:199], v[40:43]
	v_mfma_f32_16x16x32_bf16 v[12:15], v[188:191], v[196:199], v[12:15]
	s_waitcnt lgkmcnt(2)
	v_mfma_f32_16x16x32_bf16 v[100:103], v[176:179], v[200:203], v[100:103]
	v_mfma_f32_16x16x32_bf16 v[64:67], v[180:183], v[200:203], v[64:67]
	v_mfma_f32_16x16x32_bf16 v[32:35], v[184:187], v[200:203], v[32:35]
	v_mfma_f32_16x16x32_bf16 v[8:11], v[188:191], v[200:203], v[8:11]
	s_waitcnt lgkmcnt(1)
; template <int EPI>
; DI void gemm_tile(const Params& p, const u16* __restrict__ A, int lda, const u16* __restrict__ Bt, int ldb, int K, int m0, int n0,
;                   char* smem, u16* Cb, int ldc) {
;     ...
; #pragma unroll
;     for (int ks = 0; ks < 2; ++ks) {
;       bf16x8 bfr[4];
; #pragma unroll
;       for (int n = 0; n < 4; ++n) bfr[n] = *(const bf16x8*)(cB + n * 16 * LSTR + (ks ? fo1 : fo0));
; #pragma unroll
;       for (int mh = 0; mh < 2; ++mh) {
;         bf16x8 af[4];
; #pragma unroll
;         for (int m = 0; m < 4; ++m) af[m] = *(const bf16x8*)(cA + (mh * 4 + m) * 16 * LSTR + (ks ? fo1 : fo0));
;         __builtin_amdgcn_s_setprio(1);
; #pragma unroll
;         for (int m = 0; m < 4; ++m)
; #pragma unroll
;           for (int n = 0; n < 4; ++n)
;             acc[mh * 4 + m][n] = EpiSwap<EPI>::v ? __builtin_amdgcn_mfma_f32_16x16x32_bf16(bfr[n], af[m], acc[mh * 4 + m][n], 0, 0, 0)
;                                                  : __builtin_amdgcn_mfma_f32_16x16x32_bf16(af[m], bfr[n], acc[mh * 4 + m][n], 0, 0, 0);
;         __builtin_amdgcn_s_setprio(0);
;       }
;     }
	v_mfma_f32_16x16x32_bf16 v[92:95], v[176:179], v[204:207], v[92:95]
	v_mfma_f32_16x16x32_bf16 v[56:59], v[180:183], v[204:207], v[56:59]
	v_mfma_f32_16x16x32_bf16 v[24:27], v[184:187], v[204:207], v[24:27]
	v_mfma_f32_16x16x32_bf16 v[4:7], v[188:191], v[204:207], v[4:7]
	s_waitcnt lgkmcnt(0)
	v_mfma_f32_16x16x32_bf16 v[84:87], v[176:179], v[208:211], v[84:87]
	v_mfma_f32_16x16x32_bf16 v[48:51], v[180:183], v[208:211], v[48:51]
	v_mfma_f32_16x16x32_bf16 v[16:19], v[184:187], v[208:211], v[16:19]
	v_mfma_f32_16x16x32_bf16 v[0:3], v[188:191], v[208:211], v[0:3]
	s_setprio 0
	v_add_u32_e32 v188, v192, v173
	v_add_u32_e32 v175, v175, v173
	ds_read_b128 v[176:179], v188 offset:32768
	ds_read_b128 v[180:183], v188 offset:34816
	ds_read_b128 v[184:187], v188 offset:36864
	ds_read_b128 v[188:191], v188 offset:38912
	ds_read_b128 v[196:199], v175
	ds_read_b128 v[200:203], v175 offset:2048
	ds_read_b128 v[204:207], v175 offset:4096
	ds_read_b128 v[208:211], v175 offset:6144
	s_setprio 1
	s_waitcnt lgkmcnt(3)
	v_mfma_f32_16x16x32_bf16 v[144:147], v[176:179], v[196:199], v[144:147]
	v_mfma_f32_16x16x32_bf16 v[104:107], v[180:183], v[196:199], v[104:107]
	v_mfma_f32_16x16x32_bf16 v[76:79], v[184:187], v[196:199], v[76:79]
	v_mfma_f32_16x16x32_bf16 v[44:47], v[188:191], v[196:199], v[44:47]
	s_waitcnt lgkmcnt(2)
	v_mfma_f32_16x16x32_bf16 v[120:123], v[176:179], v[200:203], v[120:123]
	v_mfma_f32_16x16x32_bf16 v[96:99], v[180:183], v[200:203], v[96:99]
	v_mfma_f32_16x16x32_bf16 v[68:71], v[184:187], v[200:203], v[68:71]
	v_mfma_f32_16x16x32_bf16 v[36:39], v[188:191], v[200:203], v[36:39]
	s_waitcnt lgkmcnt(1)
	v_mfma_f32_16x16x32_bf16 v[116:119], v[176:179], v[204:207], v[116:119]
	v_mfma_f32_16x16x32_bf16 v[88:91], v[180:183], v[204:207], v[88:91]
	v_mfma_f32_16x16x32_bf16 v[60:63], v[184:187], v[204:207], v[60:63]
	v_mfma_f32_16x16x32_bf16 v[28:31], v[188:191], v[204:207], v[28:31]
	s_waitcnt lgkmcnt(0)
	v_mfma_f32_16x16x32_bf16 v[112:115], v[176:179], v[208:211], v[112:115]
	v_mfma_f32_16x16x32_bf16 v[80:83], v[180:183], v[208:211], v[80:83]
	v_mfma_f32_16x16x32_bf16 v[52:55], v[184:187], v[208:211], v[52:55]
	v_mfma_f32_16x16x32_bf16 v[20:23], v[188:191], v[208:211], v[20:23]
	s_setprio 0
	ds_read_b128 v[196:199], v175 offset:8192
	ds_read_b128 v[200:203], v175 offset:10240
	ds_read_b128 v[204:207], v175 offset:12288
	ds_read_b128 v[208:211], v175 offset:14336
	s_setprio 1
	s_waitcnt lgkmcnt(3)
	v_mfma_f32_16x16x32_bf16 v[108:111], v[176:179], v[196:199], v[108:111]
	v_mfma_f32_16x16x32_bf16 v[72:75], v[180:183], v[196:199], v[72:75]
	v_mfma_f32_16x16x32_bf16 v[40:43], v[184:187], v[196:199], v[40:43]
	v_mfma_f32_16x16x32_bf16 v[12:15], v[188:191], v[196:199], v[12:15]
	s_waitcnt lgkmcnt(2)
	v_mfma_f32_16x16x32_bf16 v[100:103], v[176:179], v[200:203], v[100:103]
	v_mfma_f32_16x16x32_bf16 v[64:67], v[180:183], v[200:203], v[64:67]
	v_mfma_f32_16x16x32_bf16 v[32:35], v[184:187], v[200:203], v[32:35]
	v_mfma_f32_16x16x32_bf16 v[8:11], v[188:191], v[200:203], v[8:11]
	s_waitcnt lgkmcnt(1)
	v_mfma_f32_16x16x32_bf16 v[92:95], v[176:179], v[204:207], v[92:95]
	v_mfma_f32_16x16x32_bf16 v[56:59], v[180:183], v[204:207], v[56:59]
	v_mfma_f32_16x16x32_bf16 v[24:27], v[184:187], v[204:207], v[24:27]
	v_mfma_f32_16x16x32_bf16 v[4:7], v[188:191], v[204:207], v[4:7]
	s_waitcnt lgkmcnt(0)
	v_mfma_f32_16x16x32_bf16 v[84:87], v[176:179], v[208:211], v[84:87]
	v_mfma_f32_16x16x32_bf16 v[48:51], v[180:183], v[208:211], v[48:51]
	v_mfma_f32_16x16x32_bf16 v[16:19], v[184:187], v[208:211], v[16:19]
	v_mfma_f32_16x16x32_bf16 v[0:3], v[188:191], v[208:211], v[0:3]
	s_setprio 0
	s_cmp_lg_u32 s13, 32
	s_mov_b32 s12, s14
	s_cbranch_scc0 .LBB0_1961

; #define G_LOAD(T) { const int k_ = (T) << 6; _Pragma("unroll") for (int i = 0; i < 4; ++i) { \
;     ra[i] = *(const u32x4*)(Ag + (size_t)(i * 64) * lda + k_); rb[i] = *(const u32x4*)(Bg + (size_t)(i * 64) * ldb + k_); } }
; #define L_STORE(ST) { u16* dA_ = sbase + (ST) * GSTAGE + lr * LSTR + lkw; u16* dB_ = dA_ + 256 * LSTR; _Pragma("unroll") for (int i = 0; i < 4; ++i) { \
;     *(u32x4*)(dA_ + i * 64 * LSTR) = ra[i]; *(u32x4*)(dB_ + i * 64 * LSTR) = rb[i]; } }
; template <int EPI>
; DI void gemm_tile(const Params& p, const u16* __restrict__ A, int lda, const u16* __restrict__ Bt, int ldb, int K, int m0, int n0,
;                   char* smem, u16* Cb, int ldc) {
;     ...
;   for (int kt = 0; kt < nk; ++kt) {
;     __syncthreads();
;     if (kt + 1 < nk) L_STORE((kt + 1) & 1)
;     G_LOAD(min(kt + 2, nk - 1))
;     const u16* cA = sbase + (kt & 1) * GSTAGE + (wr * 128 + fr) * LSTR;
;     const u16* cB = sbase + (kt & 1) * GSTAGE + 256 * LSTR + (wc * 64 + fr) * LSTR;
; #pragma unroll
;     for (int ks = 0; ks < 2; ++ks) {
;       bf16x8 bfr[4];
; #pragma unroll
;       for (int n = 0; n < 4; ++n) bfr[n] = *(const bf16x8*)(cB + n * 16 * LSTR + (ks ? fo1 : fo0));
; #pragma unroll
;       for (int mh = 0; mh < 2; ++mh) {
;         bf16x8 af[4];
; #pragma unroll
;         for (int m = 0; m < 4; ++m) af[m] = *(const bf16x8*)(cA + (mh * 4 + m) * 16 * LSTR + (ks ? fo1 : fo0));
;         __builtin_amdgcn_s_setprio(1);
; #pragma unroll
;         for (int m = 0; m < 4; ++m)
; #pragma unroll
;           for (int n = 0; n < 4; ++n)
;             acc[mh * 4 + m][n] = EpiSwap<EPI>::v ? __builtin_amdgcn_mfma_f32_16x16x32_bf16(bfr[n], af[m], acc[mh * 4 + m][n], 0, 0, 0)
;                                                  : __builtin_amdgcn_mfma_f32_16x16x32_bf16(af[m], bfr[n], acc[mh * 4 + m][n], 0, 0, 0);
;         __builtin_amdgcn_s_setprio(0);
;       }
;     }
;   }
.LBB0_1985:
	s_and_b32 s0, s10, 0x8000
	s_lshl_b32 s0, s0, 1
	s_add_i32 s0, s0, 0
	v_add3_u32 v175, s0, v169, v171
	v_add3_u32 v192, s0, v170, v171
	v_add_u32_e32 v188, v192, v172
	v_add_u32_e32 v193, v175, v172
	ds_read_b128 v[176:179], v188 offset:32768
	ds_read_b128 v[180:183], v188 offset:34816
	ds_read_b128 v[184:187], v188 offset:36864
	ds_read_b128 v[188:191], v188 offset:38912
	ds_read_b128 v[196:199], v193
	ds_read_b128 v[200:203], v193 offset:2048
	ds_read_b128 v[204:207], v193 offset:4096
	ds_read_b128 v[208:211], v193 offset:6144
	s_min_i32 s0, s11, 0x7d
	s_lshl_b32 s2, s0, 7
	s_waitcnt vmcnt(0)
	v_lshl_add_u64 v[152:153], v[162:163], 0, s[2:3]
	v_add_co_u32_e32 v136, vcc, s4, v152
	v_lshl_add_u64 v[156:157], v[164:165], 0, s[2:3]
	s_nop 0
	v_addc_co_u32_e32 v137, vcc, 0, v153, vcc
	v_add_co_u32_e32 v140, vcc, s4, v156
	global_load_dwordx4 v[132:135], v[152:153], off offset:256
	global_load_dwordx4 v[128:131], v[156:157], off offset:256
	v_addc_co_u32_e32 v141, vcc, 0, v157, vcc
	v_add_co_u32_e32 v144, vcc, s5, v152
	global_load_dwordx4 v[136:139], v[136:137], off offset:256
	s_nop 0
	v_addc_co_u32_e32 v145, vcc, 0, v153, vcc
	v_add_co_u32_e32 v148, vcc, s5, v156
	global_load_dwordx4 v[140:143], v[140:141], off offset:256
	s_nop 0
	v_addc_co_u32_e32 v149, vcc, 0, v157, vcc
	v_add_co_u32_e32 v152, vcc, s6, v152
	global_load_dwordx4 v[144:147], v[144:145], off offset:256
	s_nop 0
	v_addc_co_u32_e32 v153, vcc, 0, v153, vcc
	v_add_co_u32_e32 v156, vcc, s6, v156
	global_load_dwordx4 v[148:151], v[148:149], off offset:256
	s_nop 0
	v_addc_co_u32_e32 v157, vcc, 0, v157, vcc
	global_load_dwordx4 v[152:155], v[152:153], off offset:256
	s_nop 0
	global_load_dwordx4 v[156:159], v[156:157], off offset:256
	s_add_i32 s11, s11, 1
	s_setprio 1
	s_waitcnt lgkmcnt(3)
	v_mfma_f32_16x16x32_bf16 v[124:127], v[176:179], v[196:199], v[124:127]
	v_mfma_f32_16x16x32_bf16 v[108:111], v[180:183], v[196:199], v[108:111]
	v_mfma_f32_16x16x32_bf16 v[76:79], v[184:187], v[196:199], v[76:79]
	v_mfma_f32_16x16x32_bf16 v[44:47], v[188:191], v[196:199], v[44:47]
	s_waitcnt lgkmcnt(2)
	v_mfma_f32_16x16x32_bf16 v[120:123], v[176:179], v[200:203], v[120:123]
	v_mfma_f32_16x16x32_bf16 v[100:103], v[180:183], v[200:203], v[100:103]
	v_mfma_f32_16x16x32_bf16 v[68:71], v[184:187], v[200:203], v[68:71]
	v_mfma_f32_16x16x32_bf16 v[36:39], v[188:191], v[200:203], v[36:39]
	s_waitcnt lgkmcnt(1)
	v_mfma_f32_16x16x32_bf16 v[116:119], v[176:179], v[204:207], v[116:119]
	v_mfma_f32_16x16x32_bf16 v[92:95], v[180:183], v[204:207], v[92:95]
	v_mfma_f32_16x16x32_bf16 v[60:63], v[184:187], v[204:207], v[60:63]
	v_mfma_f32_16x16x32_bf16 v[28:31], v[188:191], v[204:207], v[28:31]
	s_waitcnt lgkmcnt(0)
	v_mfma_f32_16x16x32_bf16 v[112:115], v[176:179], v[208:211], v[112:115]
	v_mfma_f32_16x16x32_bf16 v[84:87], v[180:183], v[208:211], v[84:87]
	v_mfma_f32_16x16x32_bf16 v[52:55], v[184:187], v[208:211], v[52:55]
	v_mfma_f32_16x16x32_bf16 v[20:23], v[188:191], v[208:211], v[20:23]
	s_setprio 0
	ds_read_b128 v[196:199], v193 offset:8192
	ds_read_b128 v[200:203], v193 offset:10240
	ds_read_b128 v[204:207], v193 offset:12288
	ds_read_b128 v[208:211], v193 offset:14336
	s_setprio 1
	s_waitcnt lgkmcnt(3)
	v_mfma_f32_16x16x32_bf16 v[104:107], v[176:179], v[196:199], v[104:107]
	v_mfma_f32_16x16x32_bf16 v[72:75], v[180:183], v[196:199], v[72:75]
	v_mfma_f32_16x16x32_bf16 v[40:43], v[184:187], v[196:199], v[40:43]
	v_mfma_f32_16x16x32_bf16 v[12:15], v[188:191], v[196:199], v[12:15]
	s_waitcnt lgkmcnt(2)
	v_mfma_f32_16x16x32_bf16 v[96:99], v[176:179], v[200:203], v[96:99]
	v_mfma_f32_16x16x32_bf16 v[64:67], v[180:183], v[200:203], v[64:67]
	v_mfma_f32_16x16x32_bf16 v[32:35], v[184:187], v[200:203], v[32:35]
	v_mfma_f32_16x16x32_bf16 v[8:11], v[188:191], v[200:203], v[8:11]
	s_waitcnt lgkmcnt(1)
; template <int EPI>
; DI void gemm_tile(const Params& p, const u16* __restrict__ A, int lda, const u16* __restrict__ Bt, int ldb, int K, int m0, int n0,
;                   char* smem, u16* Cb, int ldc) {
;     ...
; #pragma unroll
;     for (int ks = 0; ks < 2; ++ks) {
;       bf16x8 bfr[4];
; #pragma unroll
;       for (int n = 0; n < 4; ++n) bfr[n] = *(const bf16x8*)(cB + n * 16 * LSTR + (ks ? fo1 : fo0));
; #pragma unroll
;       for (int mh = 0; mh < 2; ++mh) {
;         bf16x8 af[4];
; #pragma unroll
;         for (int m = 0; m < 4; ++m) af[m] = *(const bf16x8*)(cA + (mh * 4 + m) * 16 * LSTR + (ks ? fo1 : fo0));
;         __builtin_amdgcn_s_setprio(1);
; #pragma unroll
;         for (int m = 0; m < 4; ++m)
; #pragma unroll
;           for (int n = 0; n < 4; ++n)
;             acc[mh * 4 + m][n] = EpiSwap<EPI>::v ? __builtin_amdgcn_mfma_f32_16x16x32_bf16(bfr[n], af[m], acc[mh * 4 + m][n], 0, 0, 0)
;                                                  : __builtin_amdgcn_mfma_f32_16x16x32_bf16(af[m], bfr[n], acc[mh * 4 + m][n], 0, 0, 0);
;         __builtin_amdgcn_s_setprio(0);
;       }
;     }
	v_mfma_f32_16x16x32_bf16 v[88:91], v[176:179], v[204:207], v[88:91]
	v_mfma_f32_16x16x32_bf16 v[56:59], v[180:183], v[204:207], v[56:59]
	v_mfma_f32_16x16x32_bf16 v[24:27], v[184:187], v[204:207], v[24:27]
	v_mfma_f32_16x16x32_bf16 v[4:7], v[188:191], v[204:207], v[4:7]
	s_waitcnt lgkmcnt(0)
	v_mfma_f32_16x16x32_bf16 v[80:83], v[176:179], v[208:211], v[80:83]
	v_mfma_f32_16x16x32_bf16 v[48:51], v[180:183], v[208:211], v[48:51]
	v_mfma_f32_16x16x32_bf16 v[16:19], v[184:187], v[208:211], v[16:19]
	v_mfma_f32_16x16x32_bf16 v[0:3], v[188:191], v[208:211], v[0:3]
	s_setprio 0
	v_add_u32_e32 v188, v192, v174
	v_add_u32_e32 v175, v175, v174
	ds_read_b128 v[176:179], v188 offset:32768
	ds_read_b128 v[180:183], v188 offset:34816
	ds_read_b128 v[184:187], v188 offset:36864
	ds_read_b128 v[188:191], v188 offset:38912
	ds_read_b128 v[196:199], v175
	ds_read_b128 v[200:203], v175 offset:2048
	ds_read_b128 v[204:207], v175 offset:4096
	ds_read_b128 v[208:211], v175 offset:6144
	s_setprio 1
	s_waitcnt lgkmcnt(3)
	v_mfma_f32_16x16x32_bf16 v[124:127], v[176:179], v[196:199], v[124:127]
	v_mfma_f32_16x16x32_bf16 v[108:111], v[180:183], v[196:199], v[108:111]
	v_mfma_f32_16x16x32_bf16 v[76:79], v[184:187], v[196:199], v[76:79]
	v_mfma_f32_16x16x32_bf16 v[44:47], v[188:191], v[196:199], v[44:47]
	s_waitcnt lgkmcnt(2)
	v_mfma_f32_16x16x32_bf16 v[120:123], v[176:179], v[200:203], v[120:123]
	v_mfma_f32_16x16x32_bf16 v[100:103], v[180:183], v[200:203], v[100:103]
	v_mfma_f32_16x16x32_bf16 v[68:71], v[184:187], v[200:203], v[68:71]
	v_mfma_f32_16x16x32_bf16 v[36:39], v[188:191], v[200:203], v[36:39]
	s_waitcnt lgkmcnt(1)
	v_mfma_f32_16x16x32_bf16 v[116:119], v[176:179], v[204:207], v[116:119]
	v_mfma_f32_16x16x32_bf16 v[92:95], v[180:183], v[204:207], v[92:95]
	v_mfma_f32_16x16x32_bf16 v[60:63], v[184:187], v[204:207], v[60:63]
	v_mfma_f32_16x16x32_bf16 v[28:31], v[188:191], v[204:207], v[28:31]
	s_waitcnt lgkmcnt(0)
	v_mfma_f32_16x16x32_bf16 v[112:115], v[176:179], v[208:211], v[112:115]
	v_mfma_f32_16x16x32_bf16 v[84:87], v[180:183], v[208:211], v[84:87]
	v_mfma_f32_16x16x32_bf16 v[52:55], v[184:187], v[208:211], v[52:55]
	v_mfma_f32_16x16x32_bf16 v[20:23], v[188:191], v[208:211], v[20:23]
	s_setprio 0
	ds_read_b128 v[196:199], v175 offset:8192
	ds_read_b128 v[200:203], v175 offset:10240
	ds_read_b128 v[204:207], v175 offset:12288
	ds_read_b128 v[208:211], v175 offset:14336
	s_setprio 1
	s_waitcnt lgkmcnt(3)
	v_mfma_f32_16x16x32_bf16 v[104:107], v[176:179], v[196:199], v[104:107]
	v_mfma_f32_16x16x32_bf16 v[72:75], v[180:183], v[196:199], v[72:75]
	v_mfma_f32_16x16x32_bf16 v[40:43], v[184:187], v[196:199], v[40:43]
	v_mfma_f32_16x16x32_bf16 v[12:15], v[188:191], v[196:199], v[12:15]
	s_waitcnt lgkmcnt(2)
	v_mfma_f32_16x16x32_bf16 v[96:99], v[176:179], v[200:203], v[96:99]
	v_mfma_f32_16x16x32_bf16 v[64:67], v[180:183], v[200:203], v[64:67]
	v_mfma_f32_16x16x32_bf16 v[32:35], v[184:187], v[200:203], v[32:35]
	v_mfma_f32_16x16x32_bf16 v[8:11], v[188:191], v[200:203], v[8:11]
	s_waitcnt lgkmcnt(1)
	v_mfma_f32_16x16x32_bf16 v[88:91], v[176:179], v[204:207], v[88:91]
	v_mfma_f32_16x16x32_bf16 v[56:59], v[180:183], v[204:207], v[56:59]
	v_mfma_f32_16x16x32_bf16 v[24:27], v[184:187], v[204:207], v[24:27]
	v_mfma_f32_16x16x32_bf16 v[4:7], v[188:191], v[204:207], v[4:7]
	s_waitcnt lgkmcnt(0)
	v_mfma_f32_16x16x32_bf16 v[80:83], v[176:179], v[208:211], v[80:83]
	v_mfma_f32_16x16x32_bf16 v[48:51], v[180:183], v[208:211], v[48:51]
	v_mfma_f32_16x16x32_bf16 v[16:19], v[184:187], v[208:211], v[16:19]
	v_mfma_f32_16x16x32_bf16 v[0:3], v[188:191], v[208:211], v[0:3]
	s_setprio 0
	s_cmpk_lg_i32 s11, 0x80
	s_mov_b32 s10, s12
	s_cbranch_scc0 .LBB0_1983

; #define G_LOAD(T) { const int k_ = (T) << 6; _Pragma("unroll") for (int i = 0; i < 4; ++i) { \
;     ra[i] = *(const u32x4*)(Ag + (size_t)(i * 64) * lda + k_); rb[i] = *(const u32x4*)(Bg + (size_t)(i * 64) * ldb + k_); } }
; #define L_STORE(ST) { u16* dA_ = sbase + (ST) * GSTAGE + lr * LSTR + lkw; u16* dB_ = dA_ + 256 * LSTR; _Pragma("unroll") for (int i = 0; i < 4; ++i) { \
;     *(u32x4*)(dA_ + i * 64 * LSTR) = ra[i]; *(u32x4*)(dB_ + i * 64 * LSTR) = rb[i]; } }
; template <int EPI>
; DI void gemm_tile(const Params& p, const u16* __restrict__ A, int lda, const u16* __restrict__ Bt, int ldb, int K, int m0, int n0,
;                   char* smem, u16* Cb, int ldc) {
;     ...
;   for (int kt = 0; kt < nk; ++kt) {
;     __syncthreads();
;     if (kt + 1 < nk) L_STORE((kt + 1) & 1)
;     G_LOAD(min(kt + 2, nk - 1))
;     const u16* cA = sbase + (kt & 1) * GSTAGE + (wr * 128 + fr) * LSTR;
;     const u16* cB = sbase + (kt & 1) * GSTAGE + 256 * LSTR + (wc * 64 + fr) * LSTR;
; #pragma unroll
;     for (int ks = 0; ks < 2; ++ks) {
;       bf16x8 bfr[4];
; #pragma unroll
;       for (int n = 0; n < 4; ++n) bfr[n] = *(const bf16x8*)(cB + n * 16 * LSTR + (ks ? fo1 : fo0));
; #pragma unroll
;       for (int mh = 0; mh < 2; ++mh) {
;         bf16x8 af[4];
; #pragma unroll
;         for (int m = 0; m < 4; ++m) af[m] = *(const bf16x8*)(cA + (mh * 4 + m) * 16 * LSTR + (ks ? fo1 : fo0));
;         __builtin_amdgcn_s_setprio(1);
; #pragma unroll
;         for (int m = 0; m < 4; ++m)
; #pragma unroll
;           for (int n = 0; n < 4; ++n)
;             acc[mh * 4 + m][n] = EpiSwap<EPI>::v ? __builtin_amdgcn_mfma_f32_16x16x32_bf16(bfr[n], af[m], acc[mh * 4 + m][n], 0, 0, 0)
;                                                  : __builtin_amdgcn_mfma_f32_16x16x32_bf16(af[m], bfr[n], acc[mh * 4 + m][n], 0, 0, 0);
;         __builtin_amdgcn_s_setprio(0);
;       }
;     }
;   }
.LBB0_1997:
	s_and_b32 s0, s12, 0x8000
	s_lshl_b32 s0, s0, 1
	s_add_i32 s0, s0, 0
	v_add3_u32 v175, s0, v169, v171
	v_add3_u32 v192, s0, v170, v171
	v_add_u32_e32 v188, v192, v172
	v_add_u32_e32 v193, v175, v172
	ds_read_b128 v[176:179], v188 offset:32768
	ds_read_b128 v[180:183], v188 offset:34816
	ds_read_b128 v[184:187], v188 offset:36864
	ds_read_b128 v[188:191], v188 offset:38912
	ds_read_b128 v[196:199], v193
	ds_read_b128 v[200:203], v193 offset:2048
	ds_read_b128 v[204:207], v193 offset:4096
	ds_read_b128 v[208:211], v193 offset:6144
	s_min_i32 s0, s13, 0x7d
	s_lshl_b32 s4, s0, 7
	s_waitcnt vmcnt(1)
	v_lshl_add_u64 v[152:153], v[162:163], 0, s[4:5]
	v_add_co_u32_e32 v136, vcc, s8, v152
	s_waitcnt vmcnt(0)
	v_lshl_add_u64 v[156:157], v[164:165], 0, s[4:5]
	v_addc_co_u32_e32 v137, vcc, 0, v153, vcc
	v_add_co_u32_e32 v140, vcc, s8, v156
	global_load_dwordx4 v[128:131], v[152:153], off offset:256
	global_load_dwordx4 v[132:135], v[156:157], off offset:256
	v_addc_co_u32_e32 v141, vcc, 0, v157, vcc
	v_add_co_u32_e32 v144, vcc, s9, v152
	global_load_dwordx4 v[136:139], v[136:137], off offset:256
	s_nop 0
	v_addc_co_u32_e32 v145, vcc, 0, v153, vcc
	v_add_co_u32_e32 v148, vcc, s9, v156
	global_load_dwordx4 v[140:143], v[140:141], off offset:256
	s_nop 0
	v_addc_co_u32_e32 v149, vcc, 0, v157, vcc
	v_add_co_u32_e32 v152, vcc, s10, v152
	global_load_dwordx4 v[144:147], v[144:145], off offset:256
	s_nop 0
	v_addc_co_u32_e32 v153, vcc, 0, v153, vcc
	v_add_co_u32_e32 v156, vcc, s10, v156
	global_load_dwordx4 v[148:151], v[148:149], off offset:256
	s_nop 0
	v_addc_co_u32_e32 v157, vcc, 0, v157, vcc
	global_load_dwordx4 v[152:155], v[152:153], off offset:256
	s_nop 0
	global_load_dwordx4 v[156:159], v[156:157], off offset:256
	s_add_i32 s13, s13, 1
	s_setprio 1
	s_waitcnt lgkmcnt(3)
	v_mfma_f32_16x16x32_bf16 v[124:127], v[176:179], v[196:199], v[124:127]
	v_mfma_f32_16x16x32_bf16 v[108:111], v[180:183], v[196:199], v[108:111]
	v_mfma_f32_16x16x32_bf16 v[76:79], v[184:187], v[196:199], v[76:79]
	v_mfma_f32_16x16x32_bf16 v[44:47], v[188:191], v[196:199], v[44:47]
	s_waitcnt lgkmcnt(2)
	v_mfma_f32_16x16x32_bf16 v[120:123], v[176:179], v[200:203], v[120:123]
	v_mfma_f32_16x16x32_bf16 v[100:103], v[180:183], v[200:203], v[100:103]
	v_mfma_f32_16x16x32_bf16 v[68:71], v[184:187], v[200:203], v[68:71]
	v_mfma_f32_16x16x32_bf16 v[36:39], v[188:191], v[200:203], v[36:39]
	s_waitcnt lgkmcnt(1)
	v_mfma_f32_16x16x32_bf16 v[116:119], v[176:179], v[204:207], v[116:119]
	v_mfma_f32_16x16x32_bf16 v[92:95], v[180:183], v[204:207], v[92:95]
	v_mfma_f32_16x16x32_bf16 v[60:63], v[184:187], v[204:207], v[60:63]
	v_mfma_f32_16x16x32_bf16 v[28:31], v[188:191], v[204:207], v[28:31]
	s_waitcnt lgkmcnt(0)
	v_mfma_f32_16x16x32_bf16 v[112:115], v[176:179], v[208:211], v[112:115]
	v_mfma_f32_16x16x32_bf16 v[84:87], v[180:183], v[208:211], v[84:87]
	v_mfma_f32_16x16x32_bf16 v[52:55], v[184:187], v[208:211], v[52:55]
	v_mfma_f32_16x16x32_bf16 v[20:23], v[188:191], v[208:211], v[20:23]
	s_setprio 0
	ds_read_b128 v[196:199], v193 offset:8192
	ds_read_b128 v[200:203], v193 offset:10240
	ds_read_b128 v[204:207], v193 offset:12288
	ds_read_b128 v[208:211], v193 offset:14336
	s_setprio 1
	s_waitcnt lgkmcnt(3)
	v_mfma_f32_16x16x32_bf16 v[104:107], v[176:179], v[196:199], v[104:107]
	v_mfma_f32_16x16x32_bf16 v[72:75], v[180:183], v[196:199], v[72:75]
	v_mfma_f32_16x16x32_bf16 v[40:43], v[184:187], v[196:199], v[40:43]
	v_mfma_f32_16x16x32_bf16 v[12:15], v[188:191], v[196:199], v[12:15]
	s_waitcnt lgkmcnt(2)
	v_mfma_f32_16x16x32_bf16 v[96:99], v[176:179], v[200:203], v[96:99]
	v_mfma_f32_16x16x32_bf16 v[64:67], v[180:183], v[200:203], v[64:67]
	v_mfma_f32_16x16x32_bf16 v[32:35], v[184:187], v[200:203], v[32:35]
	v_mfma_f32_16x16x32_bf16 v[8:11], v[188:191], v[200:203], v[8:11]
	s_waitcnt lgkmcnt(1)
; template <int EPI>
; DI void gemm_tile(const Params& p, const u16* __restrict__ A, int lda, const u16* __restrict__ Bt, int ldb, int K, int m0, int n0,
;                   char* smem, u16* Cb, int ldc) {
;     ...
; #pragma unroll
;     for (int ks = 0; ks < 2; ++ks) {
;       bf16x8 bfr[4];
; #pragma unroll
;       for (int n = 0; n < 4; ++n) bfr[n] = *(const bf16x8*)(cB + n * 16 * LSTR + (ks ? fo1 : fo0));
; #pragma unroll
;       for (int mh = 0; mh < 2; ++mh) {
;         bf16x8 af[4];
; #pragma unroll
;         for (int m = 0; m < 4; ++m) af[m] = *(const bf16x8*)(cA + (mh * 4 + m) * 16 * LSTR + (ks ? fo1 : fo0));
;         __builtin_amdgcn_s_setprio(1);
; #pragma unroll
;         for (int m = 0; m < 4; ++m)
; #pragma unroll
;           for (int n = 0; n < 4; ++n)
;             acc[mh * 4 + m][n] = EpiSwap<EPI>::v ? __builtin_amdgcn_mfma_f32_16x16x32_bf16(bfr[n], af[m], acc[mh * 4 + m][n], 0, 0, 0)
;                                                  : __builtin_amdgcn_mfma_f32_16x16x32_bf16(af[m], bfr[n], acc[mh * 4 + m][n], 0, 0, 0);
;         __builtin_amdgcn_s_setprio(0);
;       }
;     }
	v_mfma_f32_16x16x32_bf16 v[88:91], v[176:179], v[204:207], v[88:91]
	v_mfma_f32_16x16x32_bf16 v[56:59], v[180:183], v[204:207], v[56:59]
	v_mfma_f32_16x16x32_bf16 v[24:27], v[184:187], v[204:207], v[24:27]
	v_mfma_f32_16x16x32_bf16 v[4:7], v[188:191], v[204:207], v[4:7]
	s_waitcnt lgkmcnt(0)
	v_mfma_f32_16x16x32_bf16 v[80:83], v[176:179], v[208:211], v[80:83]
	v_mfma_f32_16x16x32_bf16 v[48:51], v[180:183], v[208:211], v[48:51]
	v_mfma_f32_16x16x32_bf16 v[16:19], v[184:187], v[208:211], v[16:19]
	v_mfma_f32_16x16x32_bf16 v[0:3], v[188:191], v[208:211], v[0:3]
	s_setprio 0
	v_add_u32_e32 v188, v192, v173
	v_add_u32_e32 v175, v175, v173
	ds_read_b128 v[176:179], v188 offset:32768
	ds_read_b128 v[180:183], v188 offset:34816
	ds_read_b128 v[184:187], v188 offset:36864
	ds_read_b128 v[188:191], v188 offset:38912
	ds_read_b128 v[196:199], v175
	ds_read_b128 v[200:203], v175 offset:2048
	ds_read_b128 v[204:207], v175 offset:4096
	ds_read_b128 v[208:211], v175 offset:6144
	s_setprio 1
	s_waitcnt lgkmcnt(3)
	v_mfma_f32_16x16x32_bf16 v[124:127], v[176:179], v[196:199], v[124:127]
	v_mfma_f32_16x16x32_bf16 v[108:111], v[180:183], v[196:199], v[108:111]
	v_mfma_f32_16x16x32_bf16 v[76:79], v[184:187], v[196:199], v[76:79]
	v_mfma_f32_16x16x32_bf16 v[44:47], v[188:191], v[196:199], v[44:47]
	s_waitcnt lgkmcnt(2)
	v_mfma_f32_16x16x32_bf16 v[120:123], v[176:179], v[200:203], v[120:123]
	v_mfma_f32_16x16x32_bf16 v[100:103], v[180:183], v[200:203], v[100:103]
	v_mfma_f32_16x16x32_bf16 v[68:71], v[184:187], v[200:203], v[68:71]
	v_mfma_f32_16x16x32_bf16 v[36:39], v[188:191], v[200:203], v[36:39]
	s_waitcnt lgkmcnt(1)
	v_mfma_f32_16x16x32_bf16 v[116:119], v[176:179], v[204:207], v[116:119]
	v_mfma_f32_16x16x32_bf16 v[92:95], v[180:183], v[204:207], v[92:95]
	v_mfma_f32_16x16x32_bf16 v[60:63], v[184:187], v[204:207], v[60:63]
	v_mfma_f32_16x16x32_bf16 v[28:31], v[188:191], v[204:207], v[28:31]
	s_waitcnt lgkmcnt(0)
	v_mfma_f32_16x16x32_bf16 v[112:115], v[176:179], v[208:211], v[112:115]
	v_mfma_f32_16x16x32_bf16 v[84:87], v[180:183], v[208:211], v[84:87]
	v_mfma_f32_16x16x32_bf16 v[52:55], v[184:187], v[208:211], v[52:55]
	v_mfma_f32_16x16x32_bf16 v[20:23], v[188:191], v[208:211], v[20:23]
	s_setprio 0
	ds_read_b128 v[196:199], v175 offset:8192
	ds_read_b128 v[200:203], v175 offset:10240
	ds_read_b128 v[204:207], v175 offset:12288
	ds_read_b128 v[208:211], v175 offset:14336
	s_setprio 1
	s_waitcnt lgkmcnt(3)
	v_mfma_f32_16x16x32_bf16 v[104:107], v[176:179], v[196:199], v[104:107]
	v_mfma_f32_16x16x32_bf16 v[72:75], v[180:183], v[196:199], v[72:75]
	v_mfma_f32_16x16x32_bf16 v[40:43], v[184:187], v[196:199], v[40:43]
	v_mfma_f32_16x16x32_bf16 v[12:15], v[188:191], v[196:199], v[12:15]
	s_waitcnt lgkmcnt(2)
	v_mfma_f32_16x16x32_bf16 v[96:99], v[176:179], v[200:203], v[96:99]
	v_mfma_f32_16x16x32_bf16 v[64:67], v[180:183], v[200:203], v[64:67]
	v_mfma_f32_16x16x32_bf16 v[32:35], v[184:187], v[200:203], v[32:35]
	v_mfma_f32_16x16x32_bf16 v[8:11], v[188:191], v[200:203], v[8:11]
	s_waitcnt lgkmcnt(1)
	v_mfma_f32_16x16x32_bf16 v[88:91], v[176:179], v[204:207], v[88:91]
	v_mfma_f32_16x16x32_bf16 v[56:59], v[180:183], v[204:207], v[56:59]
	v_mfma_f32_16x16x32_bf16 v[24:27], v[184:187], v[204:207], v[24:27]
	v_mfma_f32_16x16x32_bf16 v[4:7], v[188:191], v[204:207], v[4:7]
	s_waitcnt lgkmcnt(0)
	v_mfma_f32_16x16x32_bf16 v[80:83], v[176:179], v[208:211], v[80:83]
	v_mfma_f32_16x16x32_bf16 v[48:51], v[180:183], v[208:211], v[48:51]
	v_mfma_f32_16x16x32_bf16 v[16:19], v[184:187], v[208:211], v[16:19]
	v_mfma_f32_16x16x32_bf16 v[0:3], v[188:191], v[208:211], v[0:3]
	s_setprio 0
	s_cmpk_lg_i32 s13, 0x80
	s_mov_b32 s12, s14
	s_cbranch_scc0 .LBB0_1993

; #define G_LOAD(T) { const int k_ = (T) << 6; _Pragma("unroll") for (int i = 0; i < 4; ++i) { \
;     ra[i] = *(const u32x4*)(Ag + (size_t)(i * 64) * lda + k_); rb[i] = *(const u32x4*)(Bg + (size_t)(i * 64) * ldb + k_); } }
; #define L_STORE(ST) { u16* dA_ = sbase + (ST) * GSTAGE + lr * LSTR + lkw; u16* dB_ = dA_ + 256 * LSTR; _Pragma("unroll") for (int i = 0; i < 4; ++i) { \
;     *(u32x4*)(dA_ + i * 64 * LSTR) = ra[i]; *(u32x4*)(dB_ + i * 64 * LSTR) = rb[i]; } }
; template <int EPI>
; DI void gemm_tile(const Params& p, const u16* __restrict__ A, int lda, const u16* __restrict__ Bt, int ldb, int K, int m0, int n0,
;                   char* smem, u16* Cb, int ldc) {
;     ...
;   for (int kt = 0; kt < nk; ++kt) {
;     __syncthreads();
;     if (kt + 1 < nk) L_STORE((kt + 1) & 1)
;     G_LOAD(min(kt + 2, nk - 1))
;     const u16* cA = sbase + (kt & 1) * GSTAGE + (wr * 128 + fr) * LSTR;
;     const u16* cB = sbase + (kt & 1) * GSTAGE + 256 * LSTR + (wc * 64 + fr) * LSTR;
; #pragma unroll
;     for (int ks = 0; ks < 2; ++ks) {
;       bf16x8 bfr[4];
; #pragma unroll
;       for (int n = 0; n < 4; ++n) bfr[n] = *(const bf16x8*)(cB + n * 16 * LSTR + (ks ? fo1 : fo0));
; #pragma unroll
;       for (int mh = 0; mh < 2; ++mh) {
;         bf16x8 af[4];
; #pragma unroll
;         for (int m = 0; m < 4; ++m) af[m] = *(const bf16x8*)(cA + (mh * 4 + m) * 16 * LSTR + (ks ? fo1 : fo0));
;         __builtin_amdgcn_s_setprio(1);
; #pragma unroll
;         for (int m = 0; m < 4; ++m)
; #pragma unroll
;           for (int n = 0; n < 4; ++n)
;             acc[mh * 4 + m][n] = EpiSwap<EPI>::v ? __builtin_amdgcn_mfma_f32_16x16x32_bf16(bfr[n], af[m], acc[mh * 4 + m][n], 0, 0, 0)
;                                                  : __builtin_amdgcn_mfma_f32_16x16x32_bf16(af[m], bfr[n], acc[mh * 4 + m][n], 0, 0, 0);
;         __builtin_amdgcn_s_setprio(0);
;       }
;     }
;   }
.LBB0_2006:
	s_and_b32 s0, s14, 0x8000
	s_lshl_b32 s0, s0, 1
	s_add_i32 s0, s0, 0
	v_add3_u32 v175, s0, v169, v171
	v_add3_u32 v192, s0, v170, v171
	v_add_u32_e32 v188, v192, v173
	v_add_u32_e32 v193, v175, v173
	ds_read_b128 v[176:179], v188 offset:32768
	ds_read_b128 v[180:183], v188 offset:34816
	ds_read_b128 v[184:187], v188 offset:36864
	ds_read_b128 v[188:191], v188 offset:38912
	ds_read_b128 v[196:199], v193
	ds_read_b128 v[200:203], v193 offset:2048
	ds_read_b128 v[204:207], v193 offset:4096
	ds_read_b128 v[208:211], v193 offset:6144
	s_min_i32 s0, s15, 1
	s_lshl_b32 s4, s0, 7
	s_waitcnt vmcnt(0)
	v_lshl_add_u64 v[144:145], v[164:165], 0, s[4:5]
	s_waitcnt vmcnt(5)
	v_add_co_u32_e32 v128, vcc, s8, v144
	s_waitcnt vmcnt(2)
	v_lshl_add_u64 v[152:153], v[162:163], 0, s[4:5]
	v_addc_co_u32_e32 v129, vcc, 0, v145, vcc
	v_add_co_u32_e32 v132, vcc, s8, v152
	global_load_dwordx4 v[120:123], v[144:145], off offset:256
	global_load_dwordx4 v[124:127], v[152:153], off offset:256
	v_addc_co_u32_e32 v133, vcc, 0, v153, vcc
	global_load_dwordx4 v[136:139], v[132:133], off offset:256
	v_add_co_u32_e32 v132, vcc, s10, v144
	global_load_dwordx4 v[128:131], v[128:129], off offset:256
	s_nop 0
	v_addc_co_u32_e32 v133, vcc, 0, v145, vcc
	v_add_co_u32_e32 v146, vcc, s10, v152
	global_load_dwordx4 v[132:135], v[132:133], off offset:256
	s_nop 0
	v_addc_co_u32_e32 v147, vcc, 0, v153, vcc
	v_add_co_u32_e32 v144, vcc, s12, v144
	global_load_dwordx4 v[148:151], v[146:147], off offset:256
	s_nop 0
	v_addc_co_u32_e32 v145, vcc, 0, v145, vcc
	v_add_co_u32_e32 v152, vcc, s12, v152
	s_nop 0
	s_nop 0
	v_addc_co_u32_e32 v153, vcc, 0, v153, vcc
	global_load_dwordx4 v[152:155], v[152:153], off offset:256
	s_nop 0
	global_load_dwordx4 v[144:147], v[144:145], off offset:256
	s_add_i32 s15, s15, 1
	s_setprio 1
	s_waitcnt lgkmcnt(3)
	v_mfma_f32_16x16x32_bf16 v[156:159], v[176:179], v[196:199], v[156:159]
	v_mfma_f32_16x16x32_bf16 v[108:111], v[180:183], v[196:199], v[108:111]
	v_mfma_f32_16x16x32_bf16 v[96:99], v[184:187], v[196:199], v[96:99]
	v_mfma_f32_16x16x32_bf16 v[76:79], v[188:191], v[196:199], v[76:79]
	s_waitcnt lgkmcnt(2)
	v_mfma_f32_16x16x32_bf16 v[140:143], v[176:179], v[200:203], v[140:143]
	v_mfma_f32_16x16x32_bf16 v[104:107], v[180:183], v[200:203], v[104:107]
	v_mfma_f32_16x16x32_bf16 v[84:87], v[184:187], v[200:203], v[84:87]
	v_mfma_f32_16x16x32_bf16 v[60:63], v[188:191], v[200:203], v[60:63]
	s_waitcnt lgkmcnt(1)
	v_mfma_f32_16x16x32_bf16 v[116:119], v[176:179], v[204:207], v[116:119]
	v_mfma_f32_16x16x32_bf16 v[92:95], v[180:183], v[204:207], v[92:95]
	v_mfma_f32_16x16x32_bf16 v[72:75], v[184:187], v[204:207], v[72:75]
	v_mfma_f32_16x16x32_bf16 v[44:47], v[188:191], v[204:207], v[44:47]
	s_waitcnt lgkmcnt(0)
	v_mfma_f32_16x16x32_bf16 v[112:115], v[176:179], v[208:211], v[112:115]
	v_mfma_f32_16x16x32_bf16 v[80:83], v[180:183], v[208:211], v[80:83]
	v_mfma_f32_16x16x32_bf16 v[56:59], v[184:187], v[208:211], v[56:59]
	v_mfma_f32_16x16x32_bf16 v[32:35], v[188:191], v[208:211], v[32:35]
	s_setprio 0
	ds_read_b128 v[196:199], v193 offset:8192
	ds_read_b128 v[200:203], v193 offset:10240
	ds_read_b128 v[204:207], v193 offset:12288
	ds_read_b128 v[208:211], v193 offset:14336
	s_setprio 1
	s_waitcnt lgkmcnt(3)
	v_mfma_f32_16x16x32_bf16 v[100:103], v[176:179], v[196:199], v[100:103]
	v_mfma_f32_16x16x32_bf16 v[64:67], v[180:183], v[196:199], v[64:67]
	v_mfma_f32_16x16x32_bf16 v[40:43], v[184:187], v[196:199], v[40:43]
	v_mfma_f32_16x16x32_bf16 v[20:23], v[188:191], v[196:199], v[20:23]
	s_waitcnt lgkmcnt(2)
	v_mfma_f32_16x16x32_bf16 v[88:91], v[176:179], v[200:203], v[88:91]
	v_mfma_f32_16x16x32_bf16 v[52:55], v[180:183], v[200:203], v[52:55]
	v_mfma_f32_16x16x32_bf16 v[28:31], v[184:187], v[200:203], v[28:31]
	v_mfma_f32_16x16x32_bf16 v[12:15], v[188:191], v[200:203], v[12:15]
	s_waitcnt lgkmcnt(1)
; template <int EPI>
; DI void gemm_tile(const Params& p, const u16* __restrict__ A, int lda, const u16* __restrict__ Bt, int ldb, int K, int m0, int n0,
;                   char* smem, u16* Cb, int ldc) {
;     ...
; #pragma unroll
;     for (int ks = 0; ks < 2; ++ks) {
;       bf16x8 bfr[4];
; #pragma unroll
;       for (int n = 0; n < 4; ++n) bfr[n] = *(const bf16x8*)(cB + n * 16 * LSTR + (ks ? fo1 : fo0));
; #pragma unroll
;       for (int mh = 0; mh < 2; ++mh) {
;         bf16x8 af[4];
; #pragma unroll
;         for (int m = 0; m < 4; ++m) af[m] = *(const bf16x8*)(cA + (mh * 4 + m) * 16 * LSTR + (ks ? fo1 : fo0));
;         __builtin_amdgcn_s_setprio(1);
; #pragma unroll
;         for (int m = 0; m < 4; ++m)
; #pragma unroll
;           for (int n = 0; n < 4; ++n)
;             acc[mh * 4 + m][n] = EpiSwap<EPI>::v ? __builtin_amdgcn_mfma_f32_16x16x32_bf16(bfr[n], af[m], acc[mh * 4 + m][n], 0, 0, 0)
;                                                  : __builtin_amdgcn_mfma_f32_16x16x32_bf16(af[m], bfr[n], acc[mh * 4 + m][n], 0, 0, 0);
;         __builtin_amdgcn_s_setprio(0);
;       }
;     }
	v_mfma_f32_16x16x32_bf16 v[68:71], v[176:179], v[204:207], v[68:71]
	v_mfma_f32_16x16x32_bf16 v[36:39], v[180:183], v[204:207], v[36:39]
	v_mfma_f32_16x16x32_bf16 v[16:19], v[184:187], v[204:207], v[16:19]
	v_mfma_f32_16x16x32_bf16 v[4:7], v[188:191], v[204:207], v[4:7]
	s_waitcnt lgkmcnt(0)
	v_mfma_f32_16x16x32_bf16 v[48:51], v[176:179], v[208:211], v[48:51]
	v_mfma_f32_16x16x32_bf16 v[24:27], v[180:183], v[208:211], v[24:27]
	v_mfma_f32_16x16x32_bf16 v[8:11], v[184:187], v[208:211], v[8:11]
	v_mfma_f32_16x16x32_bf16 v[0:3], v[188:191], v[208:211], v[0:3]
	s_setprio 0
	v_add_u32_e32 v188, v192, v174
	v_add_u32_e32 v175, v175, v174
	ds_read_b128 v[176:179], v188 offset:32768
	ds_read_b128 v[180:183], v188 offset:34816
	ds_read_b128 v[184:187], v188 offset:36864
	ds_read_b128 v[188:191], v188 offset:38912
	ds_read_b128 v[196:199], v175
	ds_read_b128 v[200:203], v175 offset:2048
	ds_read_b128 v[204:207], v175 offset:4096
	ds_read_b128 v[208:211], v175 offset:6144
	s_setprio 1
	s_waitcnt lgkmcnt(3)
	v_mfma_f32_16x16x32_bf16 v[156:159], v[176:179], v[196:199], v[156:159]
	v_mfma_f32_16x16x32_bf16 v[108:111], v[180:183], v[196:199], v[108:111]
	v_mfma_f32_16x16x32_bf16 v[96:99], v[184:187], v[196:199], v[96:99]
	v_mfma_f32_16x16x32_bf16 v[76:79], v[188:191], v[196:199], v[76:79]
	s_waitcnt lgkmcnt(2)
	v_mfma_f32_16x16x32_bf16 v[140:143], v[176:179], v[200:203], v[140:143]
	v_mfma_f32_16x16x32_bf16 v[104:107], v[180:183], v[200:203], v[104:107]
	v_mfma_f32_16x16x32_bf16 v[84:87], v[184:187], v[200:203], v[84:87]
	v_mfma_f32_16x16x32_bf16 v[60:63], v[188:191], v[200:203], v[60:63]
	s_waitcnt lgkmcnt(1)
	v_mfma_f32_16x16x32_bf16 v[116:119], v[176:179], v[204:207], v[116:119]
	v_mfma_f32_16x16x32_bf16 v[92:95], v[180:183], v[204:207], v[92:95]
	v_mfma_f32_16x16x32_bf16 v[72:75], v[184:187], v[204:207], v[72:75]
	v_mfma_f32_16x16x32_bf16 v[44:47], v[188:191], v[204:207], v[44:47]
	s_waitcnt lgkmcnt(0)
	v_mfma_f32_16x16x32_bf16 v[112:115], v[176:179], v[208:211], v[112:115]
	v_mfma_f32_16x16x32_bf16 v[80:83], v[180:183], v[208:211], v[80:83]
	v_mfma_f32_16x16x32_bf16 v[56:59], v[184:187], v[208:211], v[56:59]
	v_mfma_f32_16x16x32_bf16 v[32:35], v[188:191], v[208:211], v[32:35]
	s_setprio 0
	ds_read_b128 v[196:199], v175 offset:8192
	ds_read_b128 v[200:203], v175 offset:10240
	ds_read_b128 v[204:207], v175 offset:12288
	ds_read_b128 v[208:211], v175 offset:14336
	s_setprio 1
	s_waitcnt lgkmcnt(3)
	v_mfma_f32_16x16x32_bf16 v[100:103], v[176:179], v[196:199], v[100:103]
	v_mfma_f32_16x16x32_bf16 v[64:67], v[180:183], v[196:199], v[64:67]
	v_mfma_f32_16x16x32_bf16 v[40:43], v[184:187], v[196:199], v[40:43]
	v_mfma_f32_16x16x32_bf16 v[20:23], v[188:191], v[196:199], v[20:23]
	s_waitcnt lgkmcnt(2)
	v_mfma_f32_16x16x32_bf16 v[88:91], v[176:179], v[200:203], v[88:91]
	v_mfma_f32_16x16x32_bf16 v[52:55], v[180:183], v[200:203], v[52:55]
	v_mfma_f32_16x16x32_bf16 v[28:31], v[184:187], v[200:203], v[28:31]
	v_mfma_f32_16x16x32_bf16 v[12:15], v[188:191], v[200:203], v[12:15]
	s_waitcnt lgkmcnt(1)
	v_mfma_f32_16x16x32_bf16 v[68:71], v[176:179], v[204:207], v[68:71]
	v_mfma_f32_16x16x32_bf16 v[36:39], v[180:183], v[204:207], v[36:39]
	v_mfma_f32_16x16x32_bf16 v[16:19], v[184:187], v[204:207], v[16:19]
	v_mfma_f32_16x16x32_bf16 v[4:7], v[188:191], v[204:207], v[4:7]
	s_waitcnt lgkmcnt(0)
	v_mfma_f32_16x16x32_bf16 v[48:51], v[176:179], v[208:211], v[48:51]
	v_mfma_f32_16x16x32_bf16 v[24:27], v[180:183], v[208:211], v[24:27]
	v_mfma_f32_16x16x32_bf16 v[8:11], v[184:187], v[208:211], v[8:11]
	v_mfma_f32_16x16x32_bf16 v[0:3], v[188:191], v[208:211], v[0:3]
	s_setprio 0
	s_cmp_lg_u32 s15, 4
	s_mov_b32 s14, s16
	s_cbranch_scc0 .LBB0_2004
